# GEMM K-loops: per-tile 128-register accumulator zero-fill removed; phases 1-4 of the first K-iteration peeled with inline-zero C on the k=0 MFMAs
# speedup vs baseline: 1.0006x; 1.0006x over previous
; #define STAGE(P, BASE, br, kt) do { const bf16_t* _gb = (BASE) + (long)(br) * K + (long)(kt) * 64; asm volatile("" : "+s"(_gb)); \
;     __builtin_amdgcn_global_load_lds((const unsigned*)(_gb + go0), (lds_u32*)((char*)(P) + tid * 16), 16, 0, 0); \
;     __builtin_amdgcn_global_load_lds((const unsigned*)(_gb + go1), (lds_u32*)((char*)(P) + tid * 16 + 8192), 16, 0, 0); } while (0)
; #define LDA(dst, b, h) _Pragma("unroll") for (int m = 0; m < 4; ++m) _Pragma("unroll") for (int k = 0; k < 2; ++k) \
;     dst[m][k] = *(const __attribute__((address_space(3))) bf16x8*)(aB + (((b) * 2 + (h)) * 16384 + m * 2048 + k * 1024))
; #define LDB(dst, b, h) _Pragma("unroll") for (int n = 0; n < 2; ++n) _Pragma("unroll") for (int k = 0; k < 2; ++k) \
;     dst[n][k] = *(const __attribute__((address_space(3))) bf16x8*)(bB + (((b) * 2 + (h)) * 16384 + n * 2048 + k * 1024))
; #define MMA(ai, bj, At, Bq) do { __builtin_amdgcn_s_setprio(1); \
;     _Pragma("unroll") for (int m = 0; m < 4; ++m) _Pragma("unroll") for (int n = 0; n < 2; ++n) _Pragma("unroll") for (int k = 0; k < 2; ++k) \
;       acc[ai][bj][m][n] = __builtin_amdgcn_mfma_f32_16x16x32_bf16(At[m][k], Bq[n][k], acc[ai][bj][m][n], 0, 0, 0); \
;     __builtin_amdgcn_s_setprio(0); } while (0)
; #define WAIT_V(n) asm volatile("s_waitcnt vmcnt(" #n ")" ::: "memory")
; #define WAIT_L(n) asm volatile("s_waitcnt lgkmcnt(" #n ")" ::: "memory")
; #define BAR __builtin_amdgcn_s_barrier()
; template <int MODE>
; DI void gemm_tile(const Params& p, const bf16_t* __restrict__ A, const bf16_t* __restrict__ Bt, int K, int brow, int bcol, int mp, int nt, bool vt, char* smem) {
;     ...
;   f32x4 acc[2][2][4][2];
; #pragma unroll
;   for (int a = 0; a < 2; ++a)
; #pragma unroll
;     for (int b = 0; b < 2; ++b)
; #pragma unroll
;       for (int m = 0; m < 4; ++m)
; #pragma unroll
;         for (int n = 0; n < 2; ++n) acc[a][b][m][n] = (f32x4){0.f, 0.f, 0.f, 0.f};
;     ...
;   for (int t = 0; t < ntk - 2; t += 2) {
;     LDB(B0, 0, 0); SCHED; LDA(At, 0, 0); STAGE(SA(1, 1), A, brow + 128, t + 1);
;     WAIT_L(8); BAR; WAIT_L(0); MMA(0, 0, At, B0); BAR; SCHED;
;     LDB(B1, 0, 1); STAGE(SB(0, 0), Bt, bcol, t + 2);
;     BAR; WAIT_L(0); MMA(0, 1, At, B1); BAR;
;     LDA(At, 0, 1); STAGE(SA(0, 0), A, brow, t + 2);
;     BAR; WAIT_L(0); MMA(1, 0, At, B0); BAR; SCHED;
;     STAGE(SB(0, 1), Bt, bcol + 128, t + 2);
;     WAIT_V(6); BAR; MMA(1, 1, At, B1); BAR;
.LBB0_36:
	s_or_b64 exec, exec, s[16:17]
	v_and_b32_e32 v142, 15, v0
	s_add_u32 s1, s12, 0x100
	v_bfe_u32 v131, v0, 6, 2
	v_and_b32_e32 v141, 48, v0
	v_and_b32_e32 v2, 32, v130
	v_lshlrev_b32_e32 v5, 6, v142
	s_addc_u32 s3, s13, 0
	s_waitcnt lgkmcnt(0)
	v_lshlrev_b32_e32 v3, 13, v6
	v_lshl_or_b32 v4, v131, 12, v205
	v_bitop3_b32 v5, v5, v2, v141 bitop3:0x36
	s_add_u32 s5, s20, s14
	s_addc_u32 s16, s21, s15
	s_mov_b32 s17, -2
	s_mov_b64 s[14:15], 0
	v_add_u32_e32 v147, v4, v5
	v_add_u32_e32 v145, v3, v5
	s_nop 0
	ds_read_b128 v[164:167], v147
	ds_read_b128 v[168:171], v147 offset:1024
	ds_read_b128 v[172:175], v147 offset:2048
	ds_read_b128 v[176:179], v147 offset:3072
	s_add_u32 s23, s5, s14
	s_addc_u32 s25, s16, s15
	s_add_u32 s24, s23, 0x80
	v_add_u32_e32 v162, 0xc000, v140
	s_addc_u32 s25, s25, 0
	v_readfirstlane_b32 s23, v162
	v_add_u32_e32 v163, 0xe000, v140
	ds_read_b128 v[180:183], v145
	ds_read_b128 v[184:187], v145 offset:1024
	ds_read_b128 v[188:191], v145 offset:2048
	ds_read_b128 v[192:195], v145 offset:3072
	ds_read_b128 v[196:199], v145 offset:4096
	ds_read_b128 v[214:217], v145 offset:5120
	ds_read_b128 v[218:221], v145 offset:6144
	ds_read_b128 v[222:225], v145 offset:7168
	s_mov_b32 m0, s23
	v_lshl_add_u64 v[226:227], s[24:25], 0, v[136:137]
	v_readfirstlane_b32 s23, v163
	global_load_lds_dwordx4 v[226:227], off
	v_lshl_add_u64 v[226:227], s[24:25], 0, v[138:139]
	s_mov_b32 m0, s23
	s_nop 0
	global_load_lds_dwordx4 v[226:227], off
	s_waitcnt lgkmcnt(8)
	s_barrier
	s_waitcnt lgkmcnt(0)
	s_setprio 1
	s_waitcnt lgkmcnt(0)
	v_mfma_f32_16x16x32_bf16 v[126:129], v[180:183], v[164:167], 0
	v_mfma_f32_16x16x32_bf16 v[122:125], v[180:183], v[172:175], 0
	v_mfma_f32_16x16x32_bf16 v[118:121], v[188:191], v[164:167], 0
	v_mfma_f32_16x16x32_bf16 v[114:117], v[188:191], v[172:175], 0
	v_mfma_f32_16x16x32_bf16 v[110:113], v[196:199], v[164:167], 0
	v_mfma_f32_16x16x32_bf16 v[106:109], v[196:199], v[172:175], 0
	v_mfma_f32_16x16x32_bf16 v[102:105], v[218:221], v[164:167], 0
	v_mfma_f32_16x16x32_bf16 v[98:101], v[218:221], v[172:175], 0
	v_mfma_f32_16x16x32_bf16 v[126:129], v[184:187], v[168:171], v[126:129]
	v_mfma_f32_16x16x32_bf16 v[122:125], v[184:187], v[176:179], v[122:125]
	v_mfma_f32_16x16x32_bf16 v[118:121], v[192:195], v[168:171], v[118:121]
	v_mfma_f32_16x16x32_bf16 v[114:117], v[192:195], v[176:179], v[114:117]
	v_mfma_f32_16x16x32_bf16 v[110:113], v[214:217], v[168:171], v[110:113]
	v_mfma_f32_16x16x32_bf16 v[106:109], v[214:217], v[176:179], v[106:109]
	v_mfma_f32_16x16x32_bf16 v[102:105], v[222:225], v[168:171], v[102:105]
	v_mfma_f32_16x16x32_bf16 v[98:101], v[222:225], v[176:179], v[98:101]
	s_setprio 0
	s_barrier
	s_add_u32 s23, s6, s14
	s_addc_u32 s26, s7, s15
	s_add_u32 s24, s23, 0x100
	s_addc_u32 s25, s26, 0
	v_readfirstlane_b32 s27, v144
	s_nop 0
	ds_read_b128 v[226:229], v147 offset:16384
	ds_read_b128 v[230:233], v147 offset:17408
	ds_read_b128 v[234:237], v147 offset:18432
	ds_read_b128 v[238:241], v147 offset:19456
	s_mov_b32 m0, s27
	v_lshl_add_u64 v[242:243], s[24:25], 0, v[136:137]
	global_load_lds_dwordx4 v[242:243], off
	v_lshl_add_u64 v[242:243], s[24:25], 0, v[138:139]
	v_readfirstlane_b32 s24, v146
	s_mov_b32 m0, s24
	s_nop 0
	global_load_lds_dwordx4 v[242:243], off
	s_barrier
	s_waitcnt lgkmcnt(0)
	s_setprio 1
	s_waitcnt lgkmcnt(0)
	v_mfma_f32_16x16x32_bf16 v[94:97], v[180:183], v[226:229], 0
	v_mfma_f32_16x16x32_bf16 v[90:93], v[180:183], v[234:237], 0
	v_mfma_f32_16x16x32_bf16 v[86:89], v[188:191], v[226:229], 0
	v_mfma_f32_16x16x32_bf16 v[82:85], v[188:191], v[234:237], 0
	v_mfma_f32_16x16x32_bf16 v[78:81], v[196:199], v[226:229], 0
	v_mfma_f32_16x16x32_bf16 v[74:77], v[196:199], v[234:237], 0
	v_mfma_f32_16x16x32_bf16 v[70:73], v[218:221], v[226:229], 0
	v_mfma_f32_16x16x32_bf16 v[66:69], v[218:221], v[234:237], 0
	v_mfma_f32_16x16x32_bf16 v[94:97], v[184:187], v[230:233], v[94:97]
	v_mfma_f32_16x16x32_bf16 v[90:93], v[184:187], v[238:241], v[90:93]
	v_mfma_f32_16x16x32_bf16 v[86:89], v[192:195], v[230:233], v[86:89]
	v_mfma_f32_16x16x32_bf16 v[82:85], v[192:195], v[238:241], v[82:85]
	v_mfma_f32_16x16x32_bf16 v[78:81], v[214:217], v[230:233], v[78:81]
	v_mfma_f32_16x16x32_bf16 v[74:77], v[214:217], v[238:241], v[74:77]
	v_mfma_f32_16x16x32_bf16 v[70:73], v[222:225], v[230:233], v[70:73]
	v_mfma_f32_16x16x32_bf16 v[66:69], v[222:225], v[238:241], v[66:69]
	s_setprio 0
	s_add_u32 s27, s8, s14
	s_addc_u32 s28, s9, s15
	s_add_u32 s24, s27, 0x100
	s_addc_u32 s25, s28, 0
	v_readfirstlane_b32 s29, v140
	s_barrier
; #define STAGE(P, BASE, br, kt) do { const bf16_t* _gb = (BASE) + (long)(br) * K + (long)(kt) * 64; asm volatile("" : "+s"(_gb)); \
;     __builtin_amdgcn_global_load_lds((const unsigned*)(_gb + go0), (lds_u32*)((char*)(P) + tid * 16), 16, 0, 0); \
;     __builtin_amdgcn_global_load_lds((const unsigned*)(_gb + go1), (lds_u32*)((char*)(P) + tid * 16 + 8192), 16, 0, 0); } while (0)
; #define LDA(dst, b, h) _Pragma("unroll") for (int m = 0; m < 4; ++m) _Pragma("unroll") for (int k = 0; k < 2; ++k) \
;     dst[m][k] = *(const __attribute__((address_space(3))) bf16x8*)(aB + (((b) * 2 + (h)) * 16384 + m * 2048 + k * 1024))
; #define MMA(ai, bj, At, Bq) do { __builtin_amdgcn_s_setprio(1); \
;     _Pragma("unroll") for (int m = 0; m < 4; ++m) _Pragma("unroll") for (int n = 0; n < 2; ++n) _Pragma("unroll") for (int k = 0; k < 2; ++k) \
;       acc[ai][bj][m][n] = __builtin_amdgcn_mfma_f32_16x16x32_bf16(At[m][k], Bq[n][k], acc[ai][bj][m][n], 0, 0, 0); \
;     __builtin_amdgcn_s_setprio(0); } while (0)
; #define WAIT_V(n) asm volatile("s_waitcnt vmcnt(" #n ")" ::: "memory")
; #define WAIT_L(n) asm volatile("s_waitcnt lgkmcnt(" #n ")" ::: "memory")
; #define BAR __builtin_amdgcn_s_barrier()
; #define SCHED __builtin_amdgcn_sched_barrier(0)
; template <int MODE>
; DI void gemm_tile(const Params& p, const bf16_t* __restrict__ A, const bf16_t* __restrict__ Bt, int K, int brow, int bcol, int mp, int nt, bool vt, char* smem) {
;     ...
;     LDA(At, 0, 1); STAGE(SA(0, 0), A, brow, t + 2);
;     BAR; WAIT_L(0); MMA(1, 0, At, B0); BAR; SCHED;
;     STAGE(SB(0, 1), Bt, bcol + 128, t + 2);
;     WAIT_V(6); BAR; MMA(1, 1, At, B1); BAR;
	s_nop 0
	ds_read_b128 v[180:183], v145 offset:16384
	ds_read_b128 v[184:187], v145 offset:17408
	ds_read_b128 v[188:191], v145 offset:18432
	ds_read_b128 v[192:195], v145 offset:19456
	ds_read_b128 v[196:199], v145 offset:20480
	ds_read_b128 v[214:217], v145 offset:21504
	ds_read_b128 v[218:221], v145 offset:22528
	ds_read_b128 v[222:225], v145 offset:23552
	s_mov_b32 m0, s29
	v_lshl_add_u64 v[242:243], s[24:25], 0, v[136:137]
	global_load_lds_dwordx4 v[242:243], off
	v_lshl_add_u64 v[242:243], s[24:25], 0, v[138:139]
	v_readfirstlane_b32 s24, v143
	s_mov_b32 m0, s24
	s_nop 0
	global_load_lds_dwordx4 v[242:243], off
	s_barrier
	s_waitcnt lgkmcnt(0)
	s_setprio 1
	s_waitcnt lgkmcnt(0)
	v_mfma_f32_16x16x32_bf16 v[62:65], v[180:183], v[164:167], 0
	v_mfma_f32_16x16x32_bf16 v[58:61], v[180:183], v[172:175], 0
	v_mfma_f32_16x16x32_bf16 v[54:57], v[188:191], v[164:167], 0
	v_mfma_f32_16x16x32_bf16 v[50:53], v[188:191], v[172:175], 0
	v_mfma_f32_16x16x32_bf16 v[46:49], v[196:199], v[164:167], 0
	v_mfma_f32_16x16x32_bf16 v[42:45], v[196:199], v[172:175], 0
	v_mfma_f32_16x16x32_bf16 v[38:41], v[218:221], v[164:167], 0
	v_mfma_f32_16x16x32_bf16 v[34:37], v[218:221], v[172:175], 0
	v_mfma_f32_16x16x32_bf16 v[62:65], v[184:187], v[168:171], v[62:65]
	v_mfma_f32_16x16x32_bf16 v[58:61], v[184:187], v[176:179], v[58:61]
	v_mfma_f32_16x16x32_bf16 v[54:57], v[192:195], v[168:171], v[54:57]
	v_mfma_f32_16x16x32_bf16 v[50:53], v[192:195], v[176:179], v[50:53]
	v_mfma_f32_16x16x32_bf16 v[46:49], v[214:217], v[168:171], v[46:49]
	v_mfma_f32_16x16x32_bf16 v[42:45], v[214:217], v[176:179], v[42:45]
	v_mfma_f32_16x16x32_bf16 v[38:41], v[222:225], v[168:171], v[38:41]
	v_mfma_f32_16x16x32_bf16 v[34:37], v[222:225], v[176:179], v[34:37]
	s_setprio 0
	s_barrier
	s_add_u32 s29, s10, s14
	s_addc_u32 s30, s11, s15
	s_add_u32 s24, s29, 0x100
	s_addc_u32 s25, s30, 0
	v_readfirstlane_b32 s31, v148
	s_mov_b32 m0, s31
	v_lshl_add_u64 v[164:165], s[24:25], 0, v[136:137]
	global_load_lds_dwordx4 v[164:165], off
	v_lshl_add_u64 v[164:165], s[24:25], 0, v[138:139]
	v_readfirstlane_b32 s24, v149
	s_mov_b32 m0, s24
	s_nop 0
	global_load_lds_dwordx4 v[164:165], off
	s_waitcnt vmcnt(6)
	s_barrier
	s_setprio 1
	v_mfma_f32_16x16x32_bf16 v[30:33], v[180:183], v[226:229], 0
	v_mfma_f32_16x16x32_bf16 v[26:29], v[180:183], v[234:237], 0
	v_mfma_f32_16x16x32_bf16 v[22:25], v[188:191], v[226:229], 0
	v_mfma_f32_16x16x32_bf16 v[18:21], v[188:191], v[234:237], 0
	v_mfma_f32_16x16x32_bf16 v[14:17], v[196:199], v[226:229], 0
	v_mfma_f32_16x16x32_bf16 v[10:13], v[196:199], v[234:237], 0
	v_mfma_f32_16x16x32_bf16 v[6:9], v[218:221], v[226:229], 0
	v_mfma_f32_16x16x32_bf16 v[2:5], v[218:221], v[234:237], 0
	v_mfma_f32_16x16x32_bf16 v[30:33], v[184:187], v[230:233], v[30:33]
	v_mfma_f32_16x16x32_bf16 v[26:29], v[184:187], v[238:241], v[26:29]
	v_mfma_f32_16x16x32_bf16 v[22:25], v[192:195], v[230:233], v[22:25]
	v_mfma_f32_16x16x32_bf16 v[18:21], v[192:195], v[238:241], v[18:21]
	v_mfma_f32_16x16x32_bf16 v[14:17], v[214:217], v[230:233], v[14:17]
	v_mfma_f32_16x16x32_bf16 v[10:13], v[214:217], v[238:241], v[10:13]
	v_mfma_f32_16x16x32_bf16 v[6:9], v[222:225], v[230:233], v[6:9]
	v_mfma_f32_16x16x32_bf16 v[2:5], v[222:225], v[238:241], v[2:5]
	s_setprio 0
	s_barrier
	s_branch .Lgemm0_p5

; #define STAGE(P, BASE, br, kt) do { const bf16_t* _gb = (BASE) + (long)(br) * K + (long)(kt) * 64; asm volatile("" : "+s"(_gb)); \
;     __builtin_amdgcn_global_load_lds((const unsigned*)(_gb + go0), (lds_u32*)((char*)(P) + tid * 16), 16, 0, 0); \
;     __builtin_amdgcn_global_load_lds((const unsigned*)(_gb + go1), (lds_u32*)((char*)(P) + tid * 16 + 8192), 16, 0, 0); } while (0)
; #define LDA(dst, b, h) _Pragma("unroll") for (int m = 0; m < 4; ++m) _Pragma("unroll") for (int k = 0; k < 2; ++k) \
;     dst[m][k] = *(const __attribute__((address_space(3))) bf16x8*)(aB + (((b) * 2 + (h)) * 16384 + m * 2048 + k * 1024))
; #define LDB(dst, b, h) _Pragma("unroll") for (int n = 0; n < 2; ++n) _Pragma("unroll") for (int k = 0; k < 2; ++k) \
;     dst[n][k] = *(const __attribute__((address_space(3))) bf16x8*)(bB + (((b) * 2 + (h)) * 16384 + n * 2048 + k * 1024))
; #define MMA(ai, bj, At, Bq) do { __builtin_amdgcn_s_setprio(1); \
;     _Pragma("unroll") for (int m = 0; m < 4; ++m) _Pragma("unroll") for (int n = 0; n < 2; ++n) _Pragma("unroll") for (int k = 0; k < 2; ++k) \
;       acc[ai][bj][m][n] = __builtin_amdgcn_mfma_f32_16x16x32_bf16(At[m][k], Bq[n][k], acc[ai][bj][m][n], 0, 0, 0); \
;     __builtin_amdgcn_s_setprio(0); } while (0)
; #define WAIT_L(n) asm volatile("s_waitcnt lgkmcnt(" #n ")" ::: "memory")
; #define BAR __builtin_amdgcn_s_barrier()
; #define SCHED __builtin_amdgcn_sched_barrier(0)
; template <int MODE>
; DI void gemm_tile(const Params& p, const bf16_t* __restrict__ A, const bf16_t* __restrict__ Bt, int K, int brow, int bcol, int mp, int nt, bool vt, char* smem) {
;     ...
;     LDB(B0, 1, 0); SCHED; LDA(At, 1, 0); STAGE(SA(0, 1), A, brow + 128, t + 2);
;     WAIT_L(8); BAR; WAIT_L(0); MMA(0, 0, At, B0); BAR; SCHED;
;     LDB(B1, 1, 1); STAGE(SB(1, 0), Bt, bcol, t + 3);
;     BAR; WAIT_L(0); MMA(0, 1, At, B1); BAR;
;     LDA(At, 1, 1); STAGE(SA(1, 0), A, brow, t + 3);
;     BAR; WAIT_L(0); MMA(1, 0, At, B0); BAR; SCHED;
.Lgemm0_p5:
	s_nop 0
	ds_read_b128 v[164:167], v147 offset:32768
	ds_read_b128 v[168:171], v147 offset:33792
	ds_read_b128 v[172:175], v147 offset:34816
	ds_read_b128 v[176:179], v147 offset:35840
	s_add_u32 s24, s1, s14
	s_addc_u32 s25, s3, s15
	v_readfirstlane_b32 s31, v150
	ds_read_b128 v[180:183], v145 offset:32768
	ds_read_b128 v[184:187], v145 offset:33792
	ds_read_b128 v[188:191], v145 offset:34816
	ds_read_b128 v[192:195], v145 offset:35840
	ds_read_b128 v[196:199], v145 offset:36864
	ds_read_b128 v[214:217], v145 offset:37888
	ds_read_b128 v[218:221], v145 offset:38912
	ds_read_b128 v[222:225], v145 offset:39936
	s_mov_b32 m0, s31
	v_lshl_add_u64 v[226:227], s[24:25], 0, v[136:137]
	global_load_lds_dwordx4 v[226:227], off
	v_lshl_add_u64 v[226:227], s[24:25], 0, v[138:139]
	v_readfirstlane_b32 s24, v151
	s_mov_b32 m0, s24
	s_nop 0
	global_load_lds_dwordx4 v[226:227], off
	s_waitcnt lgkmcnt(8)
	s_barrier
	s_waitcnt lgkmcnt(0)
	s_setprio 1
	s_waitcnt lgkmcnt(0)
	v_mfma_f32_16x16x32_bf16 v[126:129], v[180:183], v[164:167], v[126:129]
	v_mfma_f32_16x16x32_bf16 v[122:125], v[180:183], v[172:175], v[122:125]
	v_mfma_f32_16x16x32_bf16 v[118:121], v[188:191], v[164:167], v[118:121]
	v_mfma_f32_16x16x32_bf16 v[114:117], v[188:191], v[172:175], v[114:117]
	v_mfma_f32_16x16x32_bf16 v[110:113], v[196:199], v[164:167], v[110:113]
	v_mfma_f32_16x16x32_bf16 v[106:109], v[196:199], v[172:175], v[106:109]
	v_mfma_f32_16x16x32_bf16 v[102:105], v[218:221], v[164:167], v[102:105]
	v_mfma_f32_16x16x32_bf16 v[98:101], v[218:221], v[172:175], v[98:101]
	v_mfma_f32_16x16x32_bf16 v[126:129], v[184:187], v[168:171], v[126:129]
	v_mfma_f32_16x16x32_bf16 v[122:125], v[184:187], v[176:179], v[122:125]
	v_mfma_f32_16x16x32_bf16 v[118:121], v[192:195], v[168:171], v[118:121]
	v_mfma_f32_16x16x32_bf16 v[114:117], v[192:195], v[176:179], v[114:117]
	v_mfma_f32_16x16x32_bf16 v[110:113], v[214:217], v[168:171], v[110:113]
	v_mfma_f32_16x16x32_bf16 v[106:109], v[214:217], v[176:179], v[106:109]
	v_mfma_f32_16x16x32_bf16 v[102:105], v[222:225], v[168:171], v[102:105]
	v_mfma_f32_16x16x32_bf16 v[98:101], v[222:225], v[176:179], v[98:101]
	s_setprio 0
	s_barrier
	s_add_u32 s24, s23, 0x180
	s_addc_u32 s25, s26, 0
	v_readfirstlane_b32 s23, v156
	s_nop 0
	ds_read_b128 v[226:229], v147 offset:49152
	ds_read_b128 v[230:233], v147 offset:50176
	ds_read_b128 v[234:237], v147 offset:51200
	ds_read_b128 v[238:241], v147 offset:52224
	s_mov_b32 m0, s23
	v_lshl_add_u64 v[242:243], s[24:25], 0, v[136:137]
	v_readfirstlane_b32 s23, v157
	global_load_lds_dwordx4 v[242:243], off
	v_lshl_add_u64 v[242:243], s[24:25], 0, v[138:139]
	s_mov_b32 m0, s23
	s_nop 0
	global_load_lds_dwordx4 v[242:243], off
	s_barrier
	s_waitcnt lgkmcnt(0)
	s_setprio 1
	s_waitcnt lgkmcnt(0)
	v_mfma_f32_16x16x32_bf16 v[94:97], v[180:183], v[226:229], v[94:97]
	v_mfma_f32_16x16x32_bf16 v[90:93], v[180:183], v[234:237], v[90:93]
	v_mfma_f32_16x16x32_bf16 v[86:89], v[188:191], v[226:229], v[86:89]
	v_mfma_f32_16x16x32_bf16 v[82:85], v[188:191], v[234:237], v[82:85]
	v_mfma_f32_16x16x32_bf16 v[78:81], v[196:199], v[226:229], v[78:81]
	v_mfma_f32_16x16x32_bf16 v[74:77], v[196:199], v[234:237], v[74:77]
	v_mfma_f32_16x16x32_bf16 v[70:73], v[218:221], v[226:229], v[70:73]
	v_mfma_f32_16x16x32_bf16 v[66:69], v[218:221], v[234:237], v[66:69]
	v_mfma_f32_16x16x32_bf16 v[94:97], v[184:187], v[230:233], v[94:97]
	v_mfma_f32_16x16x32_bf16 v[90:93], v[184:187], v[238:241], v[90:93]
	v_mfma_f32_16x16x32_bf16 v[86:89], v[192:195], v[230:233], v[86:89]
	v_mfma_f32_16x16x32_bf16 v[82:85], v[192:195], v[238:241], v[82:85]
	v_mfma_f32_16x16x32_bf16 v[78:81], v[214:217], v[230:233], v[78:81]
	v_mfma_f32_16x16x32_bf16 v[74:77], v[214:217], v[238:241], v[74:77]
	v_mfma_f32_16x16x32_bf16 v[70:73], v[222:225], v[230:233], v[70:73]
	v_mfma_f32_16x16x32_bf16 v[66:69], v[222:225], v[238:241], v[66:69]
	s_setprio 0
	s_add_u32 s24, s27, 0x180
	s_addc_u32 s25, s28, 0
	v_readfirstlane_b32 s23, v158
	s_barrier
	s_nop 0
	ds_read_b128 v[180:183], v145 offset:49152
	ds_read_b128 v[184:187], v145 offset:50176
	ds_read_b128 v[188:191], v145 offset:51200
	ds_read_b128 v[192:195], v145 offset:52224
	ds_read_b128 v[196:199], v145 offset:53248
	ds_read_b128 v[214:217], v145 offset:54272
	ds_read_b128 v[218:221], v145 offset:55296
	ds_read_b128 v[222:225], v145 offset:56320
	s_mov_b32 m0, s23
	v_lshl_add_u64 v[242:243], s[24:25], 0, v[136:137]
	v_readfirstlane_b32 s23, v159
	global_load_lds_dwordx4 v[242:243], off
	v_lshl_add_u64 v[242:243], s[24:25], 0, v[138:139]
	s_mov_b32 m0, s23
	s_nop 0
	global_load_lds_dwordx4 v[242:243], off
	s_barrier
	s_waitcnt lgkmcnt(0)
	s_setprio 1
	s_waitcnt lgkmcnt(0)
	v_mfma_f32_16x16x32_bf16 v[62:65], v[180:183], v[164:167], v[62:65]
	v_mfma_f32_16x16x32_bf16 v[58:61], v[180:183], v[172:175], v[58:61]
	v_mfma_f32_16x16x32_bf16 v[54:57], v[188:191], v[164:167], v[54:57]
	v_mfma_f32_16x16x32_bf16 v[50:53], v[188:191], v[172:175], v[50:53]
	v_mfma_f32_16x16x32_bf16 v[46:49], v[196:199], v[164:167], v[46:49]
	v_mfma_f32_16x16x32_bf16 v[42:45], v[196:199], v[172:175], v[42:45]
	v_mfma_f32_16x16x32_bf16 v[38:41], v[218:221], v[164:167], v[38:41]
	v_mfma_f32_16x16x32_bf16 v[34:37], v[218:221], v[172:175], v[34:37]
	v_mfma_f32_16x16x32_bf16 v[62:65], v[184:187], v[168:171], v[62:65]
	v_mfma_f32_16x16x32_bf16 v[58:61], v[184:187], v[176:179], v[58:61]
	v_mfma_f32_16x16x32_bf16 v[54:57], v[192:195], v[168:171], v[54:57]
	v_mfma_f32_16x16x32_bf16 v[50:53], v[192:195], v[176:179], v[50:53]
	v_mfma_f32_16x16x32_bf16 v[46:49], v[214:217], v[168:171], v[46:49]
	v_mfma_f32_16x16x32_bf16 v[42:45], v[214:217], v[176:179], v[42:45]
	v_mfma_f32_16x16x32_bf16 v[38:41], v[222:225], v[168:171], v[38:41]
	v_mfma_f32_16x16x32_bf16 v[34:37], v[222:225], v[176:179], v[34:37]
	s_setprio 0
	s_barrier
; #define STAGE(P, BASE, br, kt) do { const bf16_t* _gb = (BASE) + (long)(br) * K + (long)(kt) * 64; asm volatile("" : "+s"(_gb)); \
;     __builtin_amdgcn_global_load_lds((const unsigned*)(_gb + go0), (lds_u32*)((char*)(P) + tid * 16), 16, 0, 0); \
;     __builtin_amdgcn_global_load_lds((const unsigned*)(_gb + go1), (lds_u32*)((char*)(P) + tid * 16 + 8192), 16, 0, 0); } while (0)
; #define LDA(dst, b, h) _Pragma("unroll") for (int m = 0; m < 4; ++m) _Pragma("unroll") for (int k = 0; k < 2; ++k) \
;     dst[m][k] = *(const __attribute__((address_space(3))) bf16x8*)(aB + (((b) * 2 + (h)) * 16384 + m * 2048 + k * 1024))
; #define LDB(dst, b, h) _Pragma("unroll") for (int n = 0; n < 2; ++n) _Pragma("unroll") for (int k = 0; k < 2; ++k) \
;     dst[n][k] = *(const __attribute__((address_space(3))) bf16x8*)(bB + (((b) * 2 + (h)) * 16384 + n * 2048 + k * 1024))
; #define MMA(ai, bj, At, Bq) do { __builtin_amdgcn_s_setprio(1); \
;     _Pragma("unroll") for (int m = 0; m < 4; ++m) _Pragma("unroll") for (int n = 0; n < 2; ++n) _Pragma("unroll") for (int k = 0; k < 2; ++k) \
;       acc[ai][bj][m][n] = __builtin_amdgcn_mfma_f32_16x16x32_bf16(At[m][k], Bq[n][k], acc[ai][bj][m][n], 0, 0, 0); \
;     __builtin_amdgcn_s_setprio(0); } while (0)
; #define WAIT_V(n) asm volatile("s_waitcnt vmcnt(" #n ")" ::: "memory")
; #define WAIT_L(n) asm volatile("s_waitcnt lgkmcnt(" #n ")" ::: "memory")
; #define BAR __builtin_amdgcn_s_barrier()
; template <int MODE>
; DI void gemm_tile(const Params& p, const bf16_t* __restrict__ A, const bf16_t* __restrict__ Bt, int K, int brow, int bcol, int mp, int nt, bool vt, char* smem) {
;     ...
;     STAGE(SB(1, 1), Bt, bcol + 128, t + 3);
;     WAIT_V(6); BAR; MMA(1, 1, At, B1); BAR;
;   }
;   { LDB(B0, 0, 0); LDA(At, 0, 0); STAGE(SA(1, 1), A, brow + 128, ntk - 1);
;     BAR; WAIT_L(0); MMA(0, 0, At, B0); BAR;
;     LDB(B1, 0, 1); BAR; WAIT_L(0); MMA(0, 1, At, B1); BAR;
;     LDA(At, 0, 1); WAIT_V(4); BAR; WAIT_L(0); MMA(1, 0, At, B0); MMA(1, 1, At, B1); BAR; }
	s_add_u32 s24, s29, 0x180
	s_addc_u32 s25, s30, 0
	v_readfirstlane_b32 s23, v160
	s_mov_b32 m0, s23
	v_lshl_add_u64 v[164:165], s[24:25], 0, v[136:137]
	v_readfirstlane_b32 s23, v161
	global_load_lds_dwordx4 v[164:165], off
	v_lshl_add_u64 v[164:165], s[24:25], 0, v[138:139]
	s_mov_b32 m0, s23
	s_nop 0
	global_load_lds_dwordx4 v[164:165], off
	s_waitcnt vmcnt(6)
	s_barrier
	s_setprio 1
	v_mfma_f32_16x16x32_bf16 v[30:33], v[180:183], v[226:229], v[30:33]
	v_mfma_f32_16x16x32_bf16 v[26:29], v[180:183], v[234:237], v[26:29]
	v_mfma_f32_16x16x32_bf16 v[22:25], v[188:191], v[226:229], v[22:25]
	v_mfma_f32_16x16x32_bf16 v[18:21], v[188:191], v[234:237], v[18:21]
	v_mfma_f32_16x16x32_bf16 v[14:17], v[196:199], v[226:229], v[14:17]
	v_mfma_f32_16x16x32_bf16 v[10:13], v[196:199], v[234:237], v[10:13]
	v_mfma_f32_16x16x32_bf16 v[6:9], v[218:221], v[226:229], v[6:9]
	v_mfma_f32_16x16x32_bf16 v[2:5], v[218:221], v[234:237], v[2:5]
	v_mfma_f32_16x16x32_bf16 v[30:33], v[184:187], v[230:233], v[30:33]
	v_mfma_f32_16x16x32_bf16 v[26:29], v[184:187], v[238:241], v[26:29]
	v_mfma_f32_16x16x32_bf16 v[22:25], v[192:195], v[230:233], v[22:25]
	v_mfma_f32_16x16x32_bf16 v[18:21], v[192:195], v[238:241], v[18:21]
	v_mfma_f32_16x16x32_bf16 v[14:17], v[214:217], v[230:233], v[14:17]
	v_mfma_f32_16x16x32_bf16 v[10:13], v[214:217], v[238:241], v[10:13]
	v_mfma_f32_16x16x32_bf16 v[6:9], v[222:225], v[230:233], v[6:9]
	v_mfma_f32_16x16x32_bf16 v[2:5], v[222:225], v[238:241], v[2:5]
	s_setprio 0
	s_add_i32 s17, s17, 2
	s_add_u32 s14, s14, 0x100
	s_addc_u32 s15, s15, 0
	s_cmp_lt_u32 s17, 12
	s_barrier
	s_cbranch_scc1 .LBB0_37
	s_add_u32 s6, s12, 0x780
	s_addc_u32 s7, s13, 0
	v_readfirstlane_b32 s1, v162
	s_nop 0
	ds_read_b128 v[136:139], v147
	ds_read_b128 v[148:151], v147 offset:1024
	ds_read_b128 v[156:159], v147 offset:2048
	ds_read_b128 v[164:167], v147 offset:3072
	ds_read_b128 v[168:171], v145
	ds_read_b128 v[172:175], v145 offset:1024
	ds_read_b128 v[176:179], v145 offset:2048
	ds_read_b128 v[180:183], v145 offset:3072
	ds_read_b128 v[184:187], v145 offset:4096
	ds_read_b128 v[188:191], v145 offset:5120
	ds_read_b128 v[192:195], v145 offset:6144
	ds_read_b128 v[196:199], v145 offset:7168
	s_mov_b32 m0, s1
	v_lshl_add_u64 v[134:135], v[134:135], 1, s[6:7]
	v_readfirstlane_b32 s1, v163
	global_load_lds_dwordx4 v[134:135], off
	v_lshl_add_u64 v[132:133], v[132:133], 1, s[6:7]
	s_mov_b32 m0, s1
	s_nop 0
	global_load_lds_dwordx4 v[132:133], off
	s_barrier
	s_waitcnt lgkmcnt(0)
	s_setprio 1
	s_waitcnt lgkmcnt(0)
	v_mfma_f32_16x16x32_bf16 v[126:129], v[168:171], v[136:139], v[126:129]
	v_mfma_f32_16x16x32_bf16 v[122:125], v[168:171], v[156:159], v[122:125]
	v_mfma_f32_16x16x32_bf16 v[118:121], v[176:179], v[136:139], v[118:121]
	v_mfma_f32_16x16x32_bf16 v[114:117], v[176:179], v[156:159], v[114:117]
	v_mfma_f32_16x16x32_bf16 v[126:129], v[172:175], v[148:151], v[126:129]
	v_mfma_f32_16x16x32_bf16 v[122:125], v[172:175], v[164:167], v[122:125]
	v_mfma_f32_16x16x32_bf16 v[118:121], v[180:183], v[148:151], v[118:121]
	v_mfma_f32_16x16x32_bf16 v[114:117], v[180:183], v[164:167], v[114:117]
	v_mfma_f32_16x16x32_bf16 v[110:113], v[184:187], v[136:139], v[110:113]
	v_mfma_f32_16x16x32_bf16 v[106:109], v[184:187], v[156:159], v[106:109]
	v_mfma_f32_16x16x32_bf16 v[102:105], v[192:195], v[136:139], v[102:105]
	v_mfma_f32_16x16x32_bf16 v[98:101], v[192:195], v[156:159], v[98:101]
	v_mfma_f32_16x16x32_bf16 v[132:135], v[188:191], v[148:151], v[110:113]
	v_mfma_f32_16x16x32_bf16 v[160:163], v[188:191], v[164:167], v[106:109]
	v_mfma_f32_16x16x32_bf16 v[214:217], v[196:199], v[148:151], v[102:105]
	v_mfma_f32_16x16x32_bf16 v[218:221], v[196:199], v[164:167], v[98:101]
	s_setprio 0
	s_barrier
	s_nop 0
	s_nop 0
	ds_read_b128 v[98:101], v147 offset:16384
	ds_read_b128 v[102:105], v147 offset:17408
	ds_read_b128 v[106:109], v147 offset:18432
	ds_read_b128 v[110:113], v147 offset:19456
	s_barrier
	s_waitcnt lgkmcnt(0)
	s_setprio 1
	s_waitcnt lgkmcnt(3)
	v_mfma_f32_16x16x32_bf16 v[94:97], v[168:171], v[98:101], v[94:97]
	s_waitcnt lgkmcnt(1)
	v_mfma_f32_16x16x32_bf16 v[90:93], v[168:171], v[106:109], v[90:93]
	v_mfma_f32_16x16x32_bf16 v[86:89], v[176:179], v[98:101], v[86:89]
	v_mfma_f32_16x16x32_bf16 v[82:85], v[176:179], v[106:109], v[82:85]
	v_mfma_f32_16x16x32_bf16 v[94:97], v[172:175], v[102:105], v[94:97]
	s_waitcnt lgkmcnt(0)
	v_mfma_f32_16x16x32_bf16 v[90:93], v[172:175], v[110:113], v[90:93]
	v_mfma_f32_16x16x32_bf16 v[86:89], v[180:183], v[102:105], v[86:89]
	v_mfma_f32_16x16x32_bf16 v[82:85], v[180:183], v[110:113], v[82:85]
	v_mfma_f32_16x16x32_bf16 v[78:81], v[184:187], v[98:101], v[78:81]
	v_mfma_f32_16x16x32_bf16 v[74:77], v[184:187], v[106:109], v[74:77]
	v_mfma_f32_16x16x32_bf16 v[70:73], v[192:195], v[98:101], v[70:73]
	v_mfma_f32_16x16x32_bf16 v[66:69], v[192:195], v[106:109], v[66:69]
	v_mfma_f32_16x16x32_bf16 v[168:171], v[188:191], v[102:105], v[78:81]
	v_mfma_f32_16x16x32_bf16 v[172:175], v[188:191], v[110:113], v[74:77]
	v_mfma_f32_16x16x32_bf16 v[176:179], v[196:199], v[102:105], v[70:73]
	v_mfma_f32_16x16x32_bf16 v[180:183], v[196:199], v[110:113], v[66:69]
	s_setprio 0
	s_barrier
	s_nop 1
	ds_read_b128 v[66:69], v145 offset:16384
	ds_read_b128 v[70:73], v145 offset:17408
	ds_read_b128 v[74:77], v145 offset:18432
	ds_read_b128 v[78:81], v145 offset:19456
	ds_read_b128 v[184:187], v145 offset:20480
	ds_read_b128 v[188:191], v145 offset:21504
	ds_read_b128 v[192:195], v145 offset:22528
	ds_read_b128 v[196:199], v145 offset:23552
	s_waitcnt vmcnt(4)
	s_barrier
; #define LDA(dst, b, h) _Pragma("unroll") for (int m = 0; m < 4; ++m) _Pragma("unroll") for (int k = 0; k < 2; ++k) \
;     dst[m][k] = *(const __attribute__((address_space(3))) bf16x8*)(aB + (((b) * 2 + (h)) * 16384 + m * 2048 + k * 1024))
; #define LDB(dst, b, h) _Pragma("unroll") for (int n = 0; n < 2; ++n) _Pragma("unroll") for (int k = 0; k < 2; ++k) \
;     dst[n][k] = *(const __attribute__((address_space(3))) bf16x8*)(bB + (((b) * 2 + (h)) * 16384 + n * 2048 + k * 1024))
; #define MMA(ai, bj, At, Bq) do { __builtin_amdgcn_s_setprio(1); \
;     _Pragma("unroll") for (int m = 0; m < 4; ++m) _Pragma("unroll") for (int n = 0; n < 2; ++n) _Pragma("unroll") for (int k = 0; k < 2; ++k) \
;       acc[ai][bj][m][n] = __builtin_amdgcn_mfma_f32_16x16x32_bf16(At[m][k], Bq[n][k], acc[ai][bj][m][n], 0, 0, 0); \
;     __builtin_amdgcn_s_setprio(0); } while (0)
; #define WAIT_V(n) asm volatile("s_waitcnt vmcnt(" #n ")" ::: "memory")
; #define WAIT_L(n) asm volatile("s_waitcnt lgkmcnt(" #n ")" ::: "memory")
; #define BAR __builtin_amdgcn_s_barrier()
; template <int MODE>
; DI void gemm_tile(const Params& p, const bf16_t* __restrict__ A, const bf16_t* __restrict__ Bt, int K, int brow, int bcol, int mp, int nt, bool vt, char* smem) {
;     ...
;     LDA(At, 0, 1); WAIT_V(4); BAR; WAIT_L(0); MMA(1, 0, At, B0); MMA(1, 1, At, B1); BAR; }
;   { LDB(B0, 1, 0); LDA(At, 1, 0); WAIT_V(2); BAR; WAIT_L(0); MMA(0, 0, At, B0); BAR;
	s_waitcnt lgkmcnt(0)
	s_setprio 1
	s_waitcnt lgkmcnt(7)
	v_mfma_f32_16x16x32_bf16 v[62:65], v[66:69], v[136:139], v[62:65]
	v_mfma_f32_16x16x32_bf16 v[58:61], v[66:69], v[156:159], v[58:61]
	s_waitcnt lgkmcnt(5)
	v_mfma_f32_16x16x32_bf16 v[54:57], v[74:77], v[136:139], v[54:57]
	v_mfma_f32_16x16x32_bf16 v[50:53], v[74:77], v[156:159], v[50:53]
	v_mfma_f32_16x16x32_bf16 v[62:65], v[70:73], v[148:151], v[62:65]
	v_mfma_f32_16x16x32_bf16 v[58:61], v[70:73], v[164:167], v[58:61]
	s_waitcnt lgkmcnt(4)
	v_mfma_f32_16x16x32_bf16 v[54:57], v[78:81], v[148:151], v[54:57]
	v_mfma_f32_16x16x32_bf16 v[50:53], v[78:81], v[164:167], v[50:53]
	s_waitcnt lgkmcnt(3)
	v_mfma_f32_16x16x32_bf16 v[46:49], v[184:187], v[136:139], v[46:49]
	v_mfma_f32_16x16x32_bf16 v[42:45], v[184:187], v[156:159], v[42:45]
	s_waitcnt lgkmcnt(1)
	v_mfma_f32_16x16x32_bf16 v[38:41], v[192:195], v[136:139], v[38:41]
	v_mfma_f32_16x16x32_bf16 v[34:37], v[192:195], v[156:159], v[34:37]
	v_mfma_f32_16x16x32_bf16 v[222:225], v[188:191], v[148:151], v[46:49]
	v_mfma_f32_16x16x32_bf16 v[226:229], v[188:191], v[164:167], v[42:45]
	s_waitcnt lgkmcnt(0)
	v_mfma_f32_16x16x32_bf16 v[136:139], v[196:199], v[148:151], v[38:41]
	v_mfma_f32_16x16x32_bf16 v[148:151], v[196:199], v[164:167], v[34:37]
	s_setprio 0
	s_setprio 1
	v_mfma_f32_16x16x32_bf16 v[30:33], v[66:69], v[98:101], v[30:33]
	v_mfma_f32_16x16x32_bf16 v[26:29], v[66:69], v[106:109], v[26:29]
	v_mfma_f32_16x16x32_bf16 v[22:25], v[74:77], v[98:101], v[22:25]
	v_mfma_f32_16x16x32_bf16 v[18:21], v[74:77], v[106:109], v[18:21]
	v_mfma_f32_16x16x32_bf16 v[30:33], v[70:73], v[102:105], v[30:33]
	v_mfma_f32_16x16x32_bf16 v[26:29], v[70:73], v[110:113], v[26:29]
	v_mfma_f32_16x16x32_bf16 v[22:25], v[78:81], v[102:105], v[22:25]
	v_mfma_f32_16x16x32_bf16 v[18:21], v[78:81], v[110:113], v[18:21]
	v_mfma_f32_16x16x32_bf16 v[14:17], v[184:187], v[98:101], v[14:17]
	v_mfma_f32_16x16x32_bf16 v[10:13], v[184:187], v[106:109], v[10:13]
	v_mfma_f32_16x16x32_bf16 v[6:9], v[192:195], v[98:101], v[6:9]
	v_mfma_f32_16x16x32_bf16 v[2:5], v[192:195], v[106:109], v[2:5]
	v_mfma_f32_16x16x32_bf16 v[156:159], v[188:191], v[102:105], v[14:17]
	v_mfma_f32_16x16x32_bf16 v[164:167], v[188:191], v[110:113], v[10:13]
	v_mfma_f32_16x16x32_bf16 v[184:187], v[196:199], v[102:105], v[6:9]
	v_mfma_f32_16x16x32_bf16 v[188:191], v[196:199], v[110:113], v[2:5]
	s_setprio 0
	s_barrier
	s_nop 1
	ds_read_b128 v[2:5], v147 offset:32768
	ds_read_b128 v[6:9], v147 offset:33792
	ds_read_b128 v[10:13], v147 offset:34816
	ds_read_b128 v[14:17], v147 offset:35840
	ds_read_b128 v[34:37], v145 offset:32768
	ds_read_b128 v[38:41], v145 offset:33792
	ds_read_b128 v[42:45], v145 offset:34816
	ds_read_b128 v[46:49], v145 offset:35840
	ds_read_b128 v[192:195], v145 offset:36864
	ds_read_b128 v[196:199], v145 offset:37888
	ds_read_b128 v[230:233], v145 offset:38912
	ds_read_b128 v[234:237], v145 offset:39936
	s_waitcnt vmcnt(2)
	s_barrier
	s_waitcnt lgkmcnt(0)
	s_setprio 1
	s_waitcnt lgkmcnt(7)
	v_mfma_f32_16x16x32_bf16 v[66:69], v[34:37], v[2:5], v[126:129]
	s_waitcnt lgkmcnt(6)
	v_mfma_f32_16x16x32_bf16 v[98:101], v[38:41], v[6:9], v[66:69]
	v_mfma_f32_16x16x32_bf16 v[66:69], v[34:37], v[10:13], v[122:125]
	v_mfma_f32_16x16x32_bf16 v[102:105], v[38:41], v[14:17], v[66:69]
	s_waitcnt lgkmcnt(5)
	v_mfma_f32_16x16x32_bf16 v[66:69], v[42:45], v[2:5], v[118:121]
	s_waitcnt lgkmcnt(4)
	v_mfma_f32_16x16x32_bf16 v[106:109], v[46:49], v[6:9], v[66:69]
	v_mfma_f32_16x16x32_bf16 v[66:69], v[42:45], v[10:13], v[114:117]
	v_mfma_f32_16x16x32_bf16 v[110:113], v[46:49], v[14:17], v[66:69]
	s_waitcnt lgkmcnt(3)
	v_mfma_f32_16x16x32_bf16 v[66:69], v[192:195], v[2:5], v[132:135]
	s_waitcnt lgkmcnt(2)
	v_mfma_f32_16x16x32_bf16 v[114:117], v[196:199], v[6:9], v[66:69]
	v_mfma_f32_16x16x32_bf16 v[66:69], v[192:195], v[10:13], v[160:163]
	v_mfma_f32_16x16x32_bf16 v[118:121], v[196:199], v[14:17], v[66:69]
	s_waitcnt lgkmcnt(1)
	v_mfma_f32_16x16x32_bf16 v[66:69], v[230:233], v[2:5], v[214:217]
	s_waitcnt lgkmcnt(0)
	v_mfma_f32_16x16x32_bf16 v[122:125], v[234:237], v[6:9], v[66:69]
	v_mfma_f32_16x16x32_bf16 v[66:69], v[230:233], v[10:13], v[218:221]
	v_mfma_f32_16x16x32_bf16 v[126:129], v[234:237], v[14:17], v[66:69]
	s_setprio 0
	s_barrier
; #define LDA(dst, b, h) _Pragma("unroll") for (int m = 0; m < 4; ++m) _Pragma("unroll") for (int k = 0; k < 2; ++k) \
;     dst[m][k] = *(const __attribute__((address_space(3))) bf16x8*)(aB + (((b) * 2 + (h)) * 16384 + m * 2048 + k * 1024))
; #define LDB(dst, b, h) _Pragma("unroll") for (int n = 0; n < 2; ++n) _Pragma("unroll") for (int k = 0; k < 2; ++k) \
;     dst[n][k] = *(const __attribute__((address_space(3))) bf16x8*)(bB + (((b) * 2 + (h)) * 16384 + n * 2048 + k * 1024))
; #define MMA(ai, bj, At, Bq) do { __builtin_amdgcn_s_setprio(1); \
;     _Pragma("unroll") for (int m = 0; m < 4; ++m) _Pragma("unroll") for (int n = 0; n < 2; ++n) _Pragma("unroll") for (int k = 0; k < 2; ++k) \
;       acc[ai][bj][m][n] = __builtin_amdgcn_mfma_f32_16x16x32_bf16(At[m][k], Bq[n][k], acc[ai][bj][m][n], 0, 0, 0); \
;     __builtin_amdgcn_s_setprio(0); } while (0)
; #define WAIT_V(n) asm volatile("s_waitcnt vmcnt(" #n ")" ::: "memory")
; #define WAIT_L(n) asm volatile("s_waitcnt lgkmcnt(" #n ")" ::: "memory")
; #define BAR __builtin_amdgcn_s_barrier()
; template <int MODE>
; DI void gemm_tile(const Params& p, const bf16_t* __restrict__ A, const bf16_t* __restrict__ Bt, int K, int brow, int bcol, int mp, int nt, bool vt, char* smem) {
;     ...
;     LDB(B1, 1, 1); WAIT_V(0); BAR; WAIT_L(0); MMA(0, 1, At, B1); BAR;
;     LDA(At, 1, 1); BAR; WAIT_L(0); MMA(1, 0, At, B0); MMA(1, 1, At, B1); BAR; }
;   if (wr == 0) BAR;
	ds_read_b128 v[132:135], v147 offset:49152
	ds_read_b128 v[160:163], v147 offset:50176
	ds_read_b128 v[214:217], v147 offset:51200
	ds_read_b128 v[218:221], v147 offset:52224
	s_waitcnt vmcnt(0)
	s_barrier
	s_waitcnt lgkmcnt(0)
	s_setprio 1
	s_waitcnt lgkmcnt(3)
	v_mfma_f32_16x16x32_bf16 v[66:69], v[34:37], v[132:135], v[94:97]
	s_waitcnt lgkmcnt(1)
	v_mfma_f32_16x16x32_bf16 v[34:37], v[34:37], v[214:217], v[90:93]
	s_waitcnt lgkmcnt(0)
	v_mfma_f32_16x16x32_bf16 v[70:73], v[38:41], v[218:221], v[34:37]
	v_mfma_f32_16x16x32_bf16 v[34:37], v[42:45], v[132:135], v[86:89]
	v_mfma_f32_16x16x32_bf16 v[74:77], v[46:49], v[160:163], v[34:37]
	v_mfma_f32_16x16x32_bf16 v[34:37], v[42:45], v[214:217], v[82:85]
	v_mfma_f32_16x16x32_bf16 v[78:81], v[46:49], v[218:221], v[34:37]
	v_mfma_f32_16x16x32_bf16 v[34:37], v[192:195], v[132:135], v[168:171]
	v_mfma_f32_16x16x32_bf16 v[82:85], v[196:199], v[160:163], v[34:37]
	v_mfma_f32_16x16x32_bf16 v[34:37], v[192:195], v[214:217], v[172:175]
	v_mfma_f32_16x16x32_bf16 v[86:89], v[196:199], v[218:221], v[34:37]
	v_mfma_f32_16x16x32_bf16 v[34:37], v[230:233], v[132:135], v[176:179]
	v_mfma_f32_16x16x32_bf16 v[90:93], v[234:237], v[160:163], v[34:37]
	v_mfma_f32_16x16x32_bf16 v[34:37], v[230:233], v[214:217], v[180:183]
	v_mfma_f32_16x16x32_bf16 v[66:69], v[38:41], v[160:163], v[66:69]
	v_mfma_f32_16x16x32_bf16 v[94:97], v[234:237], v[218:221], v[34:37]
	s_setprio 0
	s_barrier
	ds_read_b128 v[168:171], v145 offset:49152
	ds_read_b128 v[172:175], v145 offset:50176
	ds_read_b128 v[176:179], v145 offset:51200
	ds_read_b128 v[180:183], v145 offset:52224
	ds_read_b128 v[192:195], v145 offset:53248
	ds_read_b128 v[196:199], v145 offset:54272
	ds_read_b128 v[230:233], v145 offset:55296
	ds_read_b128 v[144:147], v145 offset:56320
	s_barrier
	s_waitcnt lgkmcnt(0)
	s_setprio 1
	s_waitcnt lgkmcnt(7)
	v_mfma_f32_16x16x32_bf16 v[34:37], v[168:171], v[2:5], v[62:65]
	s_waitcnt lgkmcnt(5)
	v_mfma_f32_16x16x32_bf16 v[42:45], v[176:179], v[2:5], v[54:57]
	v_mfma_f32_16x16x32_bf16 v[46:49], v[176:179], v[10:13], v[50:53]
	s_waitcnt lgkmcnt(3)
	v_mfma_f32_16x16x32_bf16 v[50:53], v[192:195], v[2:5], v[222:225]
	s_waitcnt lgkmcnt(1)
	v_mfma_f32_16x16x32_bf16 v[2:5], v[230:233], v[2:5], v[136:139]
	v_mfma_f32_16x16x32_bf16 v[38:41], v[168:171], v[10:13], v[58:61]
	v_mfma_f32_16x16x32_bf16 v[54:57], v[192:195], v[10:13], v[226:229]
	s_waitcnt lgkmcnt(0)
	v_mfma_f32_16x16x32_bf16 v[58:61], v[144:147], v[6:9], v[2:5]
	v_mfma_f32_16x16x32_bf16 v[2:5], v[230:233], v[10:13], v[148:151]
	v_mfma_f32_16x16x32_bf16 v[34:37], v[172:175], v[6:9], v[34:37]
	v_mfma_f32_16x16x32_bf16 v[38:41], v[172:175], v[14:17], v[38:41]
	v_mfma_f32_16x16x32_bf16 v[42:45], v[180:183], v[6:9], v[42:45]
	v_mfma_f32_16x16x32_bf16 v[46:49], v[180:183], v[14:17], v[46:49]
	v_mfma_f32_16x16x32_bf16 v[50:53], v[196:199], v[6:9], v[50:53]
	v_mfma_f32_16x16x32_bf16 v[54:57], v[196:199], v[14:17], v[54:57]
	v_mfma_f32_16x16x32_bf16 v[62:65], v[144:147], v[14:17], v[2:5]
	s_setprio 0
	s_setprio 1
	v_mfma_f32_16x16x32_bf16 v[2:5], v[168:171], v[132:135], v[30:33]
	v_mfma_f32_16x16x32_bf16 v[6:9], v[168:171], v[214:217], v[26:29]
	v_mfma_f32_16x16x32_bf16 v[10:13], v[176:179], v[132:135], v[22:25]
	v_mfma_f32_16x16x32_bf16 v[14:17], v[176:179], v[214:217], v[18:21]
	v_mfma_f32_16x16x32_bf16 v[18:21], v[192:195], v[132:135], v[156:159]
	v_mfma_f32_16x16x32_bf16 v[22:25], v[192:195], v[214:217], v[164:167]
	v_mfma_f32_16x16x32_bf16 v[26:29], v[230:233], v[132:135], v[184:187]
	v_mfma_f32_16x16x32_bf16 v[30:33], v[230:233], v[214:217], v[188:191]
	v_mfma_f32_16x16x32_bf16 v[2:5], v[172:175], v[160:163], v[2:5]
	v_mfma_f32_16x16x32_bf16 v[6:9], v[172:175], v[218:221], v[6:9]
	v_mfma_f32_16x16x32_bf16 v[10:13], v[180:183], v[160:163], v[10:13]
	v_mfma_f32_16x16x32_bf16 v[14:17], v[180:183], v[218:221], v[14:17]
	v_mfma_f32_16x16x32_bf16 v[18:21], v[196:199], v[160:163], v[18:21]
	v_mfma_f32_16x16x32_bf16 v[22:25], v[196:199], v[218:221], v[22:25]
	v_mfma_f32_16x16x32_bf16 v[26:29], v[144:147], v[160:163], v[26:29]
	v_mfma_f32_16x16x32_bf16 v[30:33], v[144:147], v[218:221], v[30:33]
	s_setprio 0
	s_movk_i32 s1, 0x100
	v_cmp_gt_u32_e32 vcc, s1, v0
	s_barrier
	s_and_saveexec_b64 s[6:7], vcc
	s_cbranch_execz .LBB0_40
	s_barrier

; #define STAGE(P, BASE, br, kt) do { const bf16_t* _gb = (BASE) + (long)(br) * K + (long)(kt) * 64; asm volatile("" : "+s"(_gb)); \
;     __builtin_amdgcn_global_load_lds((const unsigned*)(_gb + go0), (lds_u32*)((char*)(P) + tid * 16), 16, 0, 0); \
;     __builtin_amdgcn_global_load_lds((const unsigned*)(_gb + go1), (lds_u32*)((char*)(P) + tid * 16 + 8192), 16, 0, 0); } while (0)
; #define LDA(dst, b, h) _Pragma("unroll") for (int m = 0; m < 4; ++m) _Pragma("unroll") for (int k = 0; k < 2; ++k) \
;     dst[m][k] = *(const __attribute__((address_space(3))) bf16x8*)(aB + (((b) * 2 + (h)) * 16384 + m * 2048 + k * 1024))
; #define LDB(dst, b, h) _Pragma("unroll") for (int n = 0; n < 2; ++n) _Pragma("unroll") for (int k = 0; k < 2; ++k) \
;     dst[n][k] = *(const __attribute__((address_space(3))) bf16x8*)(bB + (((b) * 2 + (h)) * 16384 + n * 2048 + k * 1024))
; #define WAIT_V(n) asm volatile("s_waitcnt vmcnt(" #n ")" ::: "memory")
; #define WAIT_L(n) asm volatile("s_waitcnt lgkmcnt(" #n ")" ::: "memory")
; #define BAR __builtin_amdgcn_s_barrier()
; #define SCHED __builtin_amdgcn_sched_barrier(0)
; template <int MODE>
; DI void gemm_tile(const Params& p, const bf16_t* __restrict__ A, const bf16_t* __restrict__ Bt, int K, int brow, int bcol, int mp, int nt, bool vt, char* smem) {
;     ...
;   const int wid = tid >> 6, lane = tid & 63, wr = wid >> 2, wc = wid & 3, fr = lane & 15, fq = lane >> 4;
;   const int laneoff = (fr * 64 + fq * 16) ^ ((fr >> 3) << 5);
;   const __attribute__((address_space(3))) char* aB = (const __attribute__((address_space(3))) char*)smem + wr * 8192 + laneoff;
;   const __attribute__((address_space(3))) char* bB = (const __attribute__((address_space(3))) char*)smem + 65536 + wc * 4096 + laneoff;
;     ...
;   WAIT_V(4); BAR;
;   STAGE(SB(1, 0), Bt, bcol, 1); STAGE(SA(1, 0), A, brow, 1); STAGE(SB(1, 1), Bt, bcol + 128, 1);
;   WAIT_V(6); BAR;
;   if (MODE == MODE_PROJ || MODE == MODE_UP) {
;     float t = (ssa.x + ssa.y) + (ssa.z + ssa.w);
;     t += __shfl_xor(t, 1);
;     if ((tid & 1) == 0) rsl[tid >> 1] = rsqrtf(t * (1.f / 1024.f) + 1e-6f);
;   }
;   for (int t = 0; t < ntk - 2; t += 2) {
;     LDB(B0, 0, 0); SCHED; LDA(At, 0, 0); STAGE(SA(1, 1), A, brow + 128, t + 1);
;     WAIT_L(8); BAR; WAIT_L(0); MMA(0, 0, At, B0); BAR; SCHED;
;     LDB(B1, 0, 1); STAGE(SB(0, 0), Bt, bcol, t + 2);
.LBB0_58:
	s_or_b64 exec, exec, s[16:17]
	v_and_b32_e32 v147, 15, v144
	v_lshlrev_b32_e32 v0, 2, v144
	s_add_u32 s16, s6, 0x80
	v_add_u32_e32 v156, 0x18000, v138
	v_and_b32_e32 v146, 48, v144
	v_and_b32_e32 v3, 32, v0
	v_lshlrev_b32_e32 v4, 13, v2
	v_lshlrev_b32_e32 v2, 6, v147
	s_addc_u32 s17, s7, 0
	v_readfirstlane_b32 s1, v156
	v_bitop3_b32 v6, v2, v3, v146 bitop3:0x36
	s_waitcnt vmcnt(4)
	s_barrier
	s_mov_b32 m0, s1
	v_lshl_add_u64 v[2:3], s[16:17], 0, v[134:135]
	v_add_u32_e32 v157, 0x1a000, v138
	global_load_lds_dwordx4 v[2:3], off
	v_lshl_add_u64 v[2:3], s[16:17], 0, v[136:137]
	v_readfirstlane_b32 s1, v157
	s_add_u32 s16, s8, 0x80
	v_add_u32_e32 v158, 0x8000, v138
	s_mov_b32 m0, s1
	s_addc_u32 s17, s9, 0
	v_readfirstlane_b32 s1, v158
	global_load_lds_dwordx4 v[2:3], off
	s_mov_b32 m0, s1
	v_lshl_add_u64 v[2:3], s[16:17], 0, v[134:135]
	v_add_u32_e32 v159, 0xa000, v138
	global_load_lds_dwordx4 v[2:3], off
	v_lshl_add_u64 v[2:3], s[16:17], 0, v[136:137]
	v_readfirstlane_b32 s1, v159
	s_add_u32 s16, s10, 0x80
	v_add_u32_e32 v160, 0x1c000, v138
	s_mov_b32 m0, s1
	s_addc_u32 s17, s11, 0
	v_readfirstlane_b32 s1, v160
	v_add_u32_e32 v161, 0x1e000, v138
	global_load_lds_dwordx4 v[2:3], off
	s_mov_b32 m0, s1
	v_lshl_add_u64 v[2:3], s[16:17], 0, v[134:135]
	v_readfirstlane_b32 s1, v161
	global_load_lds_dwordx4 v[2:3], off
	v_lshl_add_u64 v[2:3], s[16:17], 0, v[136:137]
	s_mov_b32 m0, s1
	s_add_u32 s1, s12, 0x100
	global_load_lds_dwordx4 v[2:3], off
	v_bfe_u32 v145, v144, 6, 2
	s_waitcnt vmcnt(6)
	s_addc_u32 s5, s13, 0
	v_lshl_or_b32 v5, v145, 12, v205
	s_add_u32 s16, s20, s14
	s_addc_u32 s17, s21, s15
	s_mov_b32 s24, -2
	s_mov_b64 s[14:15], 0
	v_add_u32_e32 v142, v5, v6
	v_add_u32_e32 v140, v4, v6
	s_nop 0
	s_barrier
	s_nop 0
	ds_read_b128 v[164:167], v142
	ds_read_b128 v[168:171], v142 offset:1024
	ds_read_b128 v[172:175], v142 offset:2048
	ds_read_b128 v[176:179], v142 offset:3072
	s_add_u32 s25, s16, s14
	s_addc_u32 s27, s17, s15
	s_add_u32 s26, s25, 0x80
	v_add_u32_e32 v162, 0xc000, v138
	s_addc_u32 s27, s27, 0
	v_readfirstlane_b32 s25, v162
	v_add_u32_e32 v163, 0xe000, v138
	ds_read_b128 v[180:183], v140
	ds_read_b128 v[184:187], v140 offset:1024
	ds_read_b128 v[188:191], v140 offset:2048
	ds_read_b128 v[192:195], v140 offset:3072
	ds_read_b128 v[196:199], v140 offset:4096
	ds_read_b128 v[214:217], v140 offset:5120
	ds_read_b128 v[218:221], v140 offset:6144
	ds_read_b128 v[222:225], v140 offset:7168
	s_mov_b32 m0, s25
	v_lshl_add_u64 v[226:227], s[26:27], 0, v[134:135]
	v_readfirstlane_b32 s25, v163
	global_load_lds_dwordx4 v[226:227], off
	v_lshl_add_u64 v[226:227], s[26:27], 0, v[136:137]
	s_mov_b32 m0, s25
	s_nop 0
	global_load_lds_dwordx4 v[226:227], off
	s_waitcnt lgkmcnt(8)
	s_barrier
	s_waitcnt lgkmcnt(0)
	s_setprio 1
	s_waitcnt lgkmcnt(0)
	v_mfma_f32_16x16x32_bf16 v[126:129], v[180:183], v[164:167], 0
	v_mfma_f32_16x16x32_bf16 v[122:125], v[180:183], v[172:175], 0
	v_mfma_f32_16x16x32_bf16 v[118:121], v[188:191], v[164:167], 0
	v_mfma_f32_16x16x32_bf16 v[114:117], v[188:191], v[172:175], 0
	v_mfma_f32_16x16x32_bf16 v[110:113], v[196:199], v[164:167], 0
	v_mfma_f32_16x16x32_bf16 v[106:109], v[196:199], v[172:175], 0
	v_mfma_f32_16x16x32_bf16 v[102:105], v[218:221], v[164:167], 0
	v_mfma_f32_16x16x32_bf16 v[98:101], v[218:221], v[172:175], 0
	v_mfma_f32_16x16x32_bf16 v[126:129], v[184:187], v[168:171], v[126:129]
	v_mfma_f32_16x16x32_bf16 v[122:125], v[184:187], v[176:179], v[122:125]
	v_mfma_f32_16x16x32_bf16 v[118:121], v[192:195], v[168:171], v[118:121]
	v_mfma_f32_16x16x32_bf16 v[114:117], v[192:195], v[176:179], v[114:117]
	v_mfma_f32_16x16x32_bf16 v[110:113], v[214:217], v[168:171], v[110:113]
	v_mfma_f32_16x16x32_bf16 v[106:109], v[214:217], v[176:179], v[106:109]
	v_mfma_f32_16x16x32_bf16 v[102:105], v[222:225], v[168:171], v[102:105]
	v_mfma_f32_16x16x32_bf16 v[98:101], v[222:225], v[176:179], v[98:101]
	s_setprio 0
	s_barrier
	s_add_u32 s25, s6, s14
	s_addc_u32 s28, s7, s15
	s_add_u32 s26, s25, 0x100
	s_addc_u32 s27, s28, 0
	v_readfirstlane_b32 s29, v141
	s_nop 0
	ds_read_b128 v[226:229], v142 offset:16384
	ds_read_b128 v[230:233], v142 offset:17408
	ds_read_b128 v[234:237], v142 offset:18432
	ds_read_b128 v[238:241], v142 offset:19456
	s_mov_b32 m0, s29
	v_lshl_add_u64 v[242:243], s[26:27], 0, v[134:135]
	global_load_lds_dwordx4 v[242:243], off
	v_lshl_add_u64 v[242:243], s[26:27], 0, v[136:137]
	v_readfirstlane_b32 s26, v143
	s_mov_b32 m0, s26
	s_nop 0
	global_load_lds_dwordx4 v[242:243], off
	s_barrier
; #define STAGE(P, BASE, br, kt) do { const bf16_t* _gb = (BASE) + (long)(br) * K + (long)(kt) * 64; asm volatile("" : "+s"(_gb)); \
;     __builtin_amdgcn_global_load_lds((const unsigned*)(_gb + go0), (lds_u32*)((char*)(P) + tid * 16), 16, 0, 0); \
;     __builtin_amdgcn_global_load_lds((const unsigned*)(_gb + go1), (lds_u32*)((char*)(P) + tid * 16 + 8192), 16, 0, 0); } while (0)
; #define LDA(dst, b, h) _Pragma("unroll") for (int m = 0; m < 4; ++m) _Pragma("unroll") for (int k = 0; k < 2; ++k) \
;     dst[m][k] = *(const __attribute__((address_space(3))) bf16x8*)(aB + (((b) * 2 + (h)) * 16384 + m * 2048 + k * 1024))
; #define MMA(ai, bj, At, Bq) do { __builtin_amdgcn_s_setprio(1); \
;     _Pragma("unroll") for (int m = 0; m < 4; ++m) _Pragma("unroll") for (int n = 0; n < 2; ++n) _Pragma("unroll") for (int k = 0; k < 2; ++k) \
;       acc[ai][bj][m][n] = __builtin_amdgcn_mfma_f32_16x16x32_bf16(At[m][k], Bq[n][k], acc[ai][bj][m][n], 0, 0, 0); \
;     __builtin_amdgcn_s_setprio(0); } while (0)
; #define WAIT_V(n) asm volatile("s_waitcnt vmcnt(" #n ")" ::: "memory")
; #define WAIT_L(n) asm volatile("s_waitcnt lgkmcnt(" #n ")" ::: "memory")
; #define BAR __builtin_amdgcn_s_barrier()
; #define SCHED __builtin_amdgcn_sched_barrier(0)
; template <int MODE>
; DI void gemm_tile(const Params& p, const bf16_t* __restrict__ A, const bf16_t* __restrict__ Bt, int K, int brow, int bcol, int mp, int nt, bool vt, char* smem) {
;     ...
;     BAR; WAIT_L(0); MMA(0, 1, At, B1); BAR;
;     LDA(At, 0, 1); STAGE(SA(0, 0), A, brow, t + 2);
;     BAR; WAIT_L(0); MMA(1, 0, At, B0); BAR; SCHED;
;     STAGE(SB(0, 1), Bt, bcol + 128, t + 2);
;     WAIT_V(6); BAR; MMA(1, 1, At, B1); BAR;
	s_waitcnt lgkmcnt(0)
	s_setprio 1
	s_waitcnt lgkmcnt(0)
	v_mfma_f32_16x16x32_bf16 v[94:97], v[180:183], v[226:229], 0
	v_mfma_f32_16x16x32_bf16 v[90:93], v[180:183], v[234:237], 0
	v_mfma_f32_16x16x32_bf16 v[86:89], v[188:191], v[226:229], 0
	v_mfma_f32_16x16x32_bf16 v[82:85], v[188:191], v[234:237], 0
	v_mfma_f32_16x16x32_bf16 v[78:81], v[196:199], v[226:229], 0
	v_mfma_f32_16x16x32_bf16 v[74:77], v[196:199], v[234:237], 0
	v_mfma_f32_16x16x32_bf16 v[70:73], v[218:221], v[226:229], 0
	v_mfma_f32_16x16x32_bf16 v[66:69], v[218:221], v[234:237], 0
	v_mfma_f32_16x16x32_bf16 v[94:97], v[184:187], v[230:233], v[94:97]
	v_mfma_f32_16x16x32_bf16 v[90:93], v[184:187], v[238:241], v[90:93]
	v_mfma_f32_16x16x32_bf16 v[86:89], v[192:195], v[230:233], v[86:89]
	v_mfma_f32_16x16x32_bf16 v[82:85], v[192:195], v[238:241], v[82:85]
	v_mfma_f32_16x16x32_bf16 v[78:81], v[214:217], v[230:233], v[78:81]
	v_mfma_f32_16x16x32_bf16 v[74:77], v[214:217], v[238:241], v[74:77]
	v_mfma_f32_16x16x32_bf16 v[70:73], v[222:225], v[230:233], v[70:73]
	v_mfma_f32_16x16x32_bf16 v[66:69], v[222:225], v[238:241], v[66:69]
	s_setprio 0
	s_add_u32 s29, s8, s14
	s_addc_u32 s30, s9, s15
	s_add_u32 s26, s29, 0x100
	s_addc_u32 s27, s30, 0
	v_readfirstlane_b32 s31, v138
	s_barrier
	s_nop 0
	ds_read_b128 v[180:183], v140 offset:16384
	ds_read_b128 v[184:187], v140 offset:17408
	ds_read_b128 v[188:191], v140 offset:18432
	ds_read_b128 v[192:195], v140 offset:19456
	ds_read_b128 v[196:199], v140 offset:20480
	ds_read_b128 v[214:217], v140 offset:21504
	ds_read_b128 v[218:221], v140 offset:22528
	ds_read_b128 v[222:225], v140 offset:23552
	s_mov_b32 m0, s31
	v_lshl_add_u64 v[242:243], s[26:27], 0, v[134:135]
	global_load_lds_dwordx4 v[242:243], off
	v_lshl_add_u64 v[242:243], s[26:27], 0, v[136:137]
	v_readfirstlane_b32 s26, v139
	s_mov_b32 m0, s26
	s_nop 0
	global_load_lds_dwordx4 v[242:243], off
	s_barrier
	s_waitcnt lgkmcnt(0)
	s_setprio 1
	s_waitcnt lgkmcnt(0)
	v_mfma_f32_16x16x32_bf16 v[62:65], v[180:183], v[164:167], 0
	v_mfma_f32_16x16x32_bf16 v[58:61], v[180:183], v[172:175], 0
	v_mfma_f32_16x16x32_bf16 v[54:57], v[188:191], v[164:167], 0
	v_mfma_f32_16x16x32_bf16 v[50:53], v[188:191], v[172:175], 0
	v_mfma_f32_16x16x32_bf16 v[46:49], v[196:199], v[164:167], 0
	v_mfma_f32_16x16x32_bf16 v[42:45], v[196:199], v[172:175], 0
	v_mfma_f32_16x16x32_bf16 v[38:41], v[218:221], v[164:167], 0
	v_mfma_f32_16x16x32_bf16 v[34:37], v[218:221], v[172:175], 0
	v_mfma_f32_16x16x32_bf16 v[62:65], v[184:187], v[168:171], v[62:65]
	v_mfma_f32_16x16x32_bf16 v[58:61], v[184:187], v[176:179], v[58:61]
	v_mfma_f32_16x16x32_bf16 v[54:57], v[192:195], v[168:171], v[54:57]
	v_mfma_f32_16x16x32_bf16 v[50:53], v[192:195], v[176:179], v[50:53]
	v_mfma_f32_16x16x32_bf16 v[46:49], v[214:217], v[168:171], v[46:49]
	v_mfma_f32_16x16x32_bf16 v[42:45], v[214:217], v[176:179], v[42:45]
	v_mfma_f32_16x16x32_bf16 v[38:41], v[222:225], v[168:171], v[38:41]
	v_mfma_f32_16x16x32_bf16 v[34:37], v[222:225], v[176:179], v[34:37]
	s_setprio 0
	s_barrier
	s_add_u32 s31, s10, s14
	s_addc_u32 s34, s11, s15
	s_add_u32 s26, s31, 0x100
	s_addc_u32 s27, s34, 0
	v_readfirstlane_b32 s35, v148
	s_mov_b32 m0, s35
	v_lshl_add_u64 v[164:165], s[26:27], 0, v[134:135]
	global_load_lds_dwordx4 v[164:165], off
	v_lshl_add_u64 v[164:165], s[26:27], 0, v[136:137]
	v_readfirstlane_b32 s26, v149
	s_mov_b32 m0, s26
	s_nop 0
	global_load_lds_dwordx4 v[164:165], off
	s_waitcnt vmcnt(6)
	s_barrier
	s_setprio 1
	v_mfma_f32_16x16x32_bf16 v[30:33], v[180:183], v[226:229], 0
	v_mfma_f32_16x16x32_bf16 v[26:29], v[180:183], v[234:237], 0
	v_mfma_f32_16x16x32_bf16 v[22:25], v[188:191], v[226:229], 0
	v_mfma_f32_16x16x32_bf16 v[18:21], v[188:191], v[234:237], 0
	v_mfma_f32_16x16x32_bf16 v[14:17], v[196:199], v[226:229], 0
	v_mfma_f32_16x16x32_bf16 v[10:13], v[196:199], v[234:237], 0
	v_mfma_f32_16x16x32_bf16 v[6:9], v[218:221], v[226:229], 0
	v_mfma_f32_16x16x32_bf16 v[2:5], v[218:221], v[234:237], 0
	v_mfma_f32_16x16x32_bf16 v[30:33], v[184:187], v[230:233], v[30:33]
	v_mfma_f32_16x16x32_bf16 v[26:29], v[184:187], v[238:241], v[26:29]
	v_mfma_f32_16x16x32_bf16 v[22:25], v[192:195], v[230:233], v[22:25]
	v_mfma_f32_16x16x32_bf16 v[18:21], v[192:195], v[238:241], v[18:21]
	v_mfma_f32_16x16x32_bf16 v[14:17], v[214:217], v[230:233], v[14:17]
	v_mfma_f32_16x16x32_bf16 v[10:13], v[214:217], v[238:241], v[10:13]
	v_mfma_f32_16x16x32_bf16 v[6:9], v[222:225], v[230:233], v[6:9]
	v_mfma_f32_16x16x32_bf16 v[2:5], v[222:225], v[238:241], v[2:5]
	s_setprio 0
	s_barrier
	s_branch .Lgemm1_p5

; #define STAGE(P, BASE, br, kt) do { const bf16_t* _gb = (BASE) + (long)(br) * K + (long)(kt) * 64; asm volatile("" : "+s"(_gb)); \
;     __builtin_amdgcn_global_load_lds((const unsigned*)(_gb + go0), (lds_u32*)((char*)(P) + tid * 16), 16, 0, 0); \
;     __builtin_amdgcn_global_load_lds((const unsigned*)(_gb + go1), (lds_u32*)((char*)(P) + tid * 16 + 8192), 16, 0, 0); } while (0)
; #define LDA(dst, b, h) _Pragma("unroll") for (int m = 0; m < 4; ++m) _Pragma("unroll") for (int k = 0; k < 2; ++k) \
;     dst[m][k] = *(const __attribute__((address_space(3))) bf16x8*)(aB + (((b) * 2 + (h)) * 16384 + m * 2048 + k * 1024))
; #define LDB(dst, b, h) _Pragma("unroll") for (int n = 0; n < 2; ++n) _Pragma("unroll") for (int k = 0; k < 2; ++k) \
;     dst[n][k] = *(const __attribute__((address_space(3))) bf16x8*)(bB + (((b) * 2 + (h)) * 16384 + n * 2048 + k * 1024))
; #define MMA(ai, bj, At, Bq) do { __builtin_amdgcn_s_setprio(1); \
;     _Pragma("unroll") for (int m = 0; m < 4; ++m) _Pragma("unroll") for (int n = 0; n < 2; ++n) _Pragma("unroll") for (int k = 0; k < 2; ++k) \
;       acc[ai][bj][m][n] = __builtin_amdgcn_mfma_f32_16x16x32_bf16(At[m][k], Bq[n][k], acc[ai][bj][m][n], 0, 0, 0); \
;     __builtin_amdgcn_s_setprio(0); } while (0)
; #define WAIT_L(n) asm volatile("s_waitcnt lgkmcnt(" #n ")" ::: "memory")
; #define BAR __builtin_amdgcn_s_barrier()
; #define SCHED __builtin_amdgcn_sched_barrier(0)
; template <int MODE>
; DI void gemm_tile(const Params& p, const bf16_t* __restrict__ A, const bf16_t* __restrict__ Bt, int K, int brow, int bcol, int mp, int nt, bool vt, char* smem) {
;     ...
;     LDB(B0, 1, 0); SCHED; LDA(At, 1, 0); STAGE(SA(0, 1), A, brow + 128, t + 2);
;     WAIT_L(8); BAR; WAIT_L(0); MMA(0, 0, At, B0); BAR; SCHED;
;     LDB(B1, 1, 1); STAGE(SB(1, 0), Bt, bcol, t + 3);
;     BAR; WAIT_L(0); MMA(0, 1, At, B1); BAR;
;     LDA(At, 1, 1); STAGE(SA(1, 0), A, brow, t + 3);
;     BAR; WAIT_L(0); MMA(1, 0, At, B0); BAR; SCHED;
.Lgemm1_p5:
	s_nop 0
	ds_read_b128 v[164:167], v142 offset:32768
	ds_read_b128 v[168:171], v142 offset:33792
	ds_read_b128 v[172:175], v142 offset:34816
	ds_read_b128 v[176:179], v142 offset:35840
	s_add_u32 s26, s1, s14
	s_addc_u32 s27, s5, s15
	v_readfirstlane_b32 s35, v150
	ds_read_b128 v[180:183], v140 offset:32768
	ds_read_b128 v[184:187], v140 offset:33792
	ds_read_b128 v[188:191], v140 offset:34816
	ds_read_b128 v[192:195], v140 offset:35840
	ds_read_b128 v[196:199], v140 offset:36864
	ds_read_b128 v[214:217], v140 offset:37888
	ds_read_b128 v[218:221], v140 offset:38912
	ds_read_b128 v[222:225], v140 offset:39936
	s_mov_b32 m0, s35
	v_lshl_add_u64 v[226:227], s[26:27], 0, v[134:135]
	global_load_lds_dwordx4 v[226:227], off
	v_lshl_add_u64 v[226:227], s[26:27], 0, v[136:137]
	v_readfirstlane_b32 s26, v151
	s_mov_b32 m0, s26
	s_nop 0
	global_load_lds_dwordx4 v[226:227], off
	s_waitcnt lgkmcnt(8)
	s_barrier
	s_waitcnt lgkmcnt(0)
	s_setprio 1
	s_waitcnt lgkmcnt(0)
	v_mfma_f32_16x16x32_bf16 v[126:129], v[180:183], v[164:167], v[126:129]
	v_mfma_f32_16x16x32_bf16 v[122:125], v[180:183], v[172:175], v[122:125]
	v_mfma_f32_16x16x32_bf16 v[118:121], v[188:191], v[164:167], v[118:121]
	v_mfma_f32_16x16x32_bf16 v[114:117], v[188:191], v[172:175], v[114:117]
	v_mfma_f32_16x16x32_bf16 v[110:113], v[196:199], v[164:167], v[110:113]
	v_mfma_f32_16x16x32_bf16 v[106:109], v[196:199], v[172:175], v[106:109]
	v_mfma_f32_16x16x32_bf16 v[102:105], v[218:221], v[164:167], v[102:105]
	v_mfma_f32_16x16x32_bf16 v[98:101], v[218:221], v[172:175], v[98:101]
	v_mfma_f32_16x16x32_bf16 v[126:129], v[184:187], v[168:171], v[126:129]
	v_mfma_f32_16x16x32_bf16 v[122:125], v[184:187], v[176:179], v[122:125]
	v_mfma_f32_16x16x32_bf16 v[118:121], v[192:195], v[168:171], v[118:121]
	v_mfma_f32_16x16x32_bf16 v[114:117], v[192:195], v[176:179], v[114:117]
	v_mfma_f32_16x16x32_bf16 v[110:113], v[214:217], v[168:171], v[110:113]
	v_mfma_f32_16x16x32_bf16 v[106:109], v[214:217], v[176:179], v[106:109]
	v_mfma_f32_16x16x32_bf16 v[102:105], v[222:225], v[168:171], v[102:105]
	v_mfma_f32_16x16x32_bf16 v[98:101], v[222:225], v[176:179], v[98:101]
	s_setprio 0
	s_barrier
	s_add_u32 s26, s25, 0x180
	s_addc_u32 s27, s28, 0
	v_readfirstlane_b32 s25, v156
	s_nop 0
	ds_read_b128 v[226:229], v142 offset:49152
	ds_read_b128 v[230:233], v142 offset:50176
	ds_read_b128 v[234:237], v142 offset:51200
	ds_read_b128 v[238:241], v142 offset:52224
	s_mov_b32 m0, s25
	v_lshl_add_u64 v[242:243], s[26:27], 0, v[134:135]
	v_readfirstlane_b32 s25, v157
	global_load_lds_dwordx4 v[242:243], off
	v_lshl_add_u64 v[242:243], s[26:27], 0, v[136:137]
	s_mov_b32 m0, s25
	s_nop 0
	global_load_lds_dwordx4 v[242:243], off
	s_barrier
	s_waitcnt lgkmcnt(0)
	s_setprio 1
	s_waitcnt lgkmcnt(0)
	v_mfma_f32_16x16x32_bf16 v[94:97], v[180:183], v[226:229], v[94:97]
	v_mfma_f32_16x16x32_bf16 v[90:93], v[180:183], v[234:237], v[90:93]
	v_mfma_f32_16x16x32_bf16 v[86:89], v[188:191], v[226:229], v[86:89]
	v_mfma_f32_16x16x32_bf16 v[82:85], v[188:191], v[234:237], v[82:85]
	v_mfma_f32_16x16x32_bf16 v[78:81], v[196:199], v[226:229], v[78:81]
	v_mfma_f32_16x16x32_bf16 v[74:77], v[196:199], v[234:237], v[74:77]
	v_mfma_f32_16x16x32_bf16 v[70:73], v[218:221], v[226:229], v[70:73]
	v_mfma_f32_16x16x32_bf16 v[66:69], v[218:221], v[234:237], v[66:69]
	v_mfma_f32_16x16x32_bf16 v[94:97], v[184:187], v[230:233], v[94:97]
	v_mfma_f32_16x16x32_bf16 v[90:93], v[184:187], v[238:241], v[90:93]
	v_mfma_f32_16x16x32_bf16 v[86:89], v[192:195], v[230:233], v[86:89]
	v_mfma_f32_16x16x32_bf16 v[82:85], v[192:195], v[238:241], v[82:85]
	v_mfma_f32_16x16x32_bf16 v[78:81], v[214:217], v[230:233], v[78:81]
	v_mfma_f32_16x16x32_bf16 v[74:77], v[214:217], v[238:241], v[74:77]
	v_mfma_f32_16x16x32_bf16 v[70:73], v[222:225], v[230:233], v[70:73]
	v_mfma_f32_16x16x32_bf16 v[66:69], v[222:225], v[238:241], v[66:69]
	s_setprio 0
	s_add_u32 s26, s29, 0x180
	s_addc_u32 s27, s30, 0
	v_readfirstlane_b32 s25, v158
	s_barrier
	s_nop 0
	ds_read_b128 v[180:183], v140 offset:49152
	ds_read_b128 v[184:187], v140 offset:50176
	ds_read_b128 v[188:191], v140 offset:51200
	ds_read_b128 v[192:195], v140 offset:52224
	ds_read_b128 v[196:199], v140 offset:53248
	ds_read_b128 v[214:217], v140 offset:54272
	ds_read_b128 v[218:221], v140 offset:55296
	ds_read_b128 v[222:225], v140 offset:56320
	s_mov_b32 m0, s25
	v_lshl_add_u64 v[242:243], s[26:27], 0, v[134:135]
	v_readfirstlane_b32 s25, v159
	global_load_lds_dwordx4 v[242:243], off
	v_lshl_add_u64 v[242:243], s[26:27], 0, v[136:137]
	s_mov_b32 m0, s25
	s_nop 0
	global_load_lds_dwordx4 v[242:243], off
	s_barrier
	s_waitcnt lgkmcnt(0)
	s_setprio 1
	s_waitcnt lgkmcnt(0)
	v_mfma_f32_16x16x32_bf16 v[62:65], v[180:183], v[164:167], v[62:65]
	v_mfma_f32_16x16x32_bf16 v[58:61], v[180:183], v[172:175], v[58:61]
	v_mfma_f32_16x16x32_bf16 v[54:57], v[188:191], v[164:167], v[54:57]
	v_mfma_f32_16x16x32_bf16 v[50:53], v[188:191], v[172:175], v[50:53]
	v_mfma_f32_16x16x32_bf16 v[46:49], v[196:199], v[164:167], v[46:49]
	v_mfma_f32_16x16x32_bf16 v[42:45], v[196:199], v[172:175], v[42:45]
	v_mfma_f32_16x16x32_bf16 v[38:41], v[218:221], v[164:167], v[38:41]
	v_mfma_f32_16x16x32_bf16 v[34:37], v[218:221], v[172:175], v[34:37]
	v_mfma_f32_16x16x32_bf16 v[62:65], v[184:187], v[168:171], v[62:65]
	v_mfma_f32_16x16x32_bf16 v[58:61], v[184:187], v[176:179], v[58:61]
	v_mfma_f32_16x16x32_bf16 v[54:57], v[192:195], v[168:171], v[54:57]
	v_mfma_f32_16x16x32_bf16 v[50:53], v[192:195], v[176:179], v[50:53]
	v_mfma_f32_16x16x32_bf16 v[46:49], v[214:217], v[168:171], v[46:49]
	v_mfma_f32_16x16x32_bf16 v[42:45], v[214:217], v[176:179], v[42:45]
	v_mfma_f32_16x16x32_bf16 v[38:41], v[222:225], v[168:171], v[38:41]
	v_mfma_f32_16x16x32_bf16 v[34:37], v[222:225], v[176:179], v[34:37]
	s_setprio 0
	s_barrier
; #define STAGE(P, BASE, br, kt) do { const bf16_t* _gb = (BASE) + (long)(br) * K + (long)(kt) * 64; asm volatile("" : "+s"(_gb)); \
;     __builtin_amdgcn_global_load_lds((const unsigned*)(_gb + go0), (lds_u32*)((char*)(P) + tid * 16), 16, 0, 0); \
;     __builtin_amdgcn_global_load_lds((const unsigned*)(_gb + go1), (lds_u32*)((char*)(P) + tid * 16 + 8192), 16, 0, 0); } while (0)
; #define LDA(dst, b, h) _Pragma("unroll") for (int m = 0; m < 4; ++m) _Pragma("unroll") for (int k = 0; k < 2; ++k) \
;     dst[m][k] = *(const __attribute__((address_space(3))) bf16x8*)(aB + (((b) * 2 + (h)) * 16384 + m * 2048 + k * 1024))
; #define LDB(dst, b, h) _Pragma("unroll") for (int n = 0; n < 2; ++n) _Pragma("unroll") for (int k = 0; k < 2; ++k) \
;     dst[n][k] = *(const __attribute__((address_space(3))) bf16x8*)(bB + (((b) * 2 + (h)) * 16384 + n * 2048 + k * 1024))
; #define MMA(ai, bj, At, Bq) do { __builtin_amdgcn_s_setprio(1); \
;     _Pragma("unroll") for (int m = 0; m < 4; ++m) _Pragma("unroll") for (int n = 0; n < 2; ++n) _Pragma("unroll") for (int k = 0; k < 2; ++k) \
;       acc[ai][bj][m][n] = __builtin_amdgcn_mfma_f32_16x16x32_bf16(At[m][k], Bq[n][k], acc[ai][bj][m][n], 0, 0, 0); \
;     __builtin_amdgcn_s_setprio(0); } while (0)
; #define WAIT_V(n) asm volatile("s_waitcnt vmcnt(" #n ")" ::: "memory")
; #define WAIT_L(n) asm volatile("s_waitcnt lgkmcnt(" #n ")" ::: "memory")
; #define BAR __builtin_amdgcn_s_barrier()
; template <int MODE>
; DI void gemm_tile(const Params& p, const bf16_t* __restrict__ A, const bf16_t* __restrict__ Bt, int K, int brow, int bcol, int mp, int nt, bool vt, char* smem) {
;     ...
;     STAGE(SB(1, 1), Bt, bcol + 128, t + 3);
;     WAIT_V(6); BAR; MMA(1, 1, At, B1); BAR;
;   }
;   { LDB(B0, 0, 0); LDA(At, 0, 0); STAGE(SA(1, 1), A, brow + 128, ntk - 1);
;     BAR; WAIT_L(0); MMA(0, 0, At, B0); BAR;
;     LDB(B1, 0, 1); BAR; WAIT_L(0); MMA(0, 1, At, B1); BAR;
;     LDA(At, 0, 1); WAIT_V(4); BAR; WAIT_L(0); MMA(1, 0, At, B0); MMA(1, 1, At, B1); BAR; }
	s_add_u32 s26, s31, 0x180
	s_addc_u32 s27, s34, 0
	v_readfirstlane_b32 s25, v160
	s_mov_b32 m0, s25
	v_lshl_add_u64 v[164:165], s[26:27], 0, v[134:135]
	v_readfirstlane_b32 s25, v161
	global_load_lds_dwordx4 v[164:165], off
	v_lshl_add_u64 v[164:165], s[26:27], 0, v[136:137]
	s_mov_b32 m0, s25
	s_nop 0
	global_load_lds_dwordx4 v[164:165], off
	s_waitcnt vmcnt(6)
	s_barrier
	s_setprio 1
	v_mfma_f32_16x16x32_bf16 v[30:33], v[180:183], v[226:229], v[30:33]
	v_mfma_f32_16x16x32_bf16 v[26:29], v[180:183], v[234:237], v[26:29]
	v_mfma_f32_16x16x32_bf16 v[22:25], v[188:191], v[226:229], v[22:25]
	v_mfma_f32_16x16x32_bf16 v[18:21], v[188:191], v[234:237], v[18:21]
	v_mfma_f32_16x16x32_bf16 v[14:17], v[196:199], v[226:229], v[14:17]
	v_mfma_f32_16x16x32_bf16 v[10:13], v[196:199], v[234:237], v[10:13]
	v_mfma_f32_16x16x32_bf16 v[6:9], v[218:221], v[226:229], v[6:9]
	v_mfma_f32_16x16x32_bf16 v[2:5], v[218:221], v[234:237], v[2:5]
	v_mfma_f32_16x16x32_bf16 v[30:33], v[184:187], v[230:233], v[30:33]
	v_mfma_f32_16x16x32_bf16 v[26:29], v[184:187], v[238:241], v[26:29]
	v_mfma_f32_16x16x32_bf16 v[22:25], v[192:195], v[230:233], v[22:25]
	v_mfma_f32_16x16x32_bf16 v[18:21], v[192:195], v[238:241], v[18:21]
	v_mfma_f32_16x16x32_bf16 v[14:17], v[214:217], v[230:233], v[14:17]
	v_mfma_f32_16x16x32_bf16 v[10:13], v[214:217], v[238:241], v[10:13]
	v_mfma_f32_16x16x32_bf16 v[6:9], v[222:225], v[230:233], v[6:9]
	v_mfma_f32_16x16x32_bf16 v[2:5], v[222:225], v[238:241], v[2:5]
	s_setprio 0
	s_add_i32 s24, s24, 2
	s_add_u32 s14, s14, 0x100
	s_addc_u32 s15, s15, 0
	s_cmp_lt_u32 s24, 12
	s_barrier
	s_cbranch_scc1 .LBB0_59
	s_add_u32 s6, s12, 0x780
	s_addc_u32 s7, s13, 0
	v_readfirstlane_b32 s1, v162
	s_nop 0
	ds_read_b128 v[134:137], v142
	ds_read_b128 v[148:151], v142 offset:1024
	ds_read_b128 v[156:159], v142 offset:2048
	ds_read_b128 v[164:167], v142 offset:3072
	ds_read_b128 v[168:171], v140
	ds_read_b128 v[172:175], v140 offset:1024
	ds_read_b128 v[176:179], v140 offset:2048
	ds_read_b128 v[180:183], v140 offset:3072
	ds_read_b128 v[184:187], v140 offset:4096
	ds_read_b128 v[188:191], v140 offset:5120
	ds_read_b128 v[192:195], v140 offset:6144
	ds_read_b128 v[196:199], v140 offset:7168
	s_mov_b32 m0, s1
	v_lshl_add_u64 v[132:133], v[132:133], 1, s[6:7]
	v_readfirstlane_b32 s1, v163
	global_load_lds_dwordx4 v[132:133], off
	v_lshl_add_u64 v[130:131], v[130:131], 1, s[6:7]
	s_mov_b32 m0, s1
	s_nop 0
	global_load_lds_dwordx4 v[130:131], off
	s_barrier
	s_waitcnt lgkmcnt(0)
	s_setprio 1
	s_waitcnt lgkmcnt(0)
	v_mfma_f32_16x16x32_bf16 v[126:129], v[168:171], v[134:137], v[126:129]
	v_mfma_f32_16x16x32_bf16 v[122:125], v[168:171], v[156:159], v[122:125]
	v_mfma_f32_16x16x32_bf16 v[118:121], v[176:179], v[134:137], v[118:121]
	v_mfma_f32_16x16x32_bf16 v[114:117], v[176:179], v[156:159], v[114:117]
	v_mfma_f32_16x16x32_bf16 v[126:129], v[172:175], v[148:151], v[126:129]
	v_mfma_f32_16x16x32_bf16 v[122:125], v[172:175], v[164:167], v[122:125]
	v_mfma_f32_16x16x32_bf16 v[118:121], v[180:183], v[148:151], v[118:121]
	v_mfma_f32_16x16x32_bf16 v[114:117], v[180:183], v[164:167], v[114:117]
	v_mfma_f32_16x16x32_bf16 v[110:113], v[184:187], v[134:137], v[110:113]
	v_mfma_f32_16x16x32_bf16 v[106:109], v[184:187], v[156:159], v[106:109]
	v_mfma_f32_16x16x32_bf16 v[102:105], v[192:195], v[134:137], v[102:105]
	v_mfma_f32_16x16x32_bf16 v[98:101], v[192:195], v[156:159], v[98:101]
	v_mfma_f32_16x16x32_bf16 v[130:133], v[188:191], v[148:151], v[110:113]
	v_mfma_f32_16x16x32_bf16 v[160:163], v[188:191], v[164:167], v[106:109]
	v_mfma_f32_16x16x32_bf16 v[214:217], v[196:199], v[148:151], v[102:105]
	v_mfma_f32_16x16x32_bf16 v[218:221], v[196:199], v[164:167], v[98:101]
	s_setprio 0
	s_barrier
	s_nop 0
	s_nop 0
	ds_read_b128 v[98:101], v142 offset:16384
	ds_read_b128 v[102:105], v142 offset:17408
	ds_read_b128 v[106:109], v142 offset:18432
	ds_read_b128 v[110:113], v142 offset:19456
	s_barrier
	s_waitcnt lgkmcnt(0)
	s_setprio 1
	s_waitcnt lgkmcnt(3)
	v_mfma_f32_16x16x32_bf16 v[94:97], v[168:171], v[98:101], v[94:97]
	s_waitcnt lgkmcnt(1)
	v_mfma_f32_16x16x32_bf16 v[90:93], v[168:171], v[106:109], v[90:93]
	v_mfma_f32_16x16x32_bf16 v[86:89], v[176:179], v[98:101], v[86:89]
	v_mfma_f32_16x16x32_bf16 v[82:85], v[176:179], v[106:109], v[82:85]
	v_mfma_f32_16x16x32_bf16 v[94:97], v[172:175], v[102:105], v[94:97]
	s_waitcnt lgkmcnt(0)
	v_mfma_f32_16x16x32_bf16 v[90:93], v[172:175], v[110:113], v[90:93]
	v_mfma_f32_16x16x32_bf16 v[86:89], v[180:183], v[102:105], v[86:89]
	v_mfma_f32_16x16x32_bf16 v[82:85], v[180:183], v[110:113], v[82:85]
	v_mfma_f32_16x16x32_bf16 v[78:81], v[184:187], v[98:101], v[78:81]
	v_mfma_f32_16x16x32_bf16 v[74:77], v[184:187], v[106:109], v[74:77]
	v_mfma_f32_16x16x32_bf16 v[70:73], v[192:195], v[98:101], v[70:73]
	v_mfma_f32_16x16x32_bf16 v[66:69], v[192:195], v[106:109], v[66:69]
	v_mfma_f32_16x16x32_bf16 v[168:171], v[188:191], v[102:105], v[78:81]
	v_mfma_f32_16x16x32_bf16 v[172:175], v[188:191], v[110:113], v[74:77]
	v_mfma_f32_16x16x32_bf16 v[176:179], v[196:199], v[102:105], v[70:73]
	v_mfma_f32_16x16x32_bf16 v[180:183], v[196:199], v[110:113], v[66:69]
	s_setprio 0
	s_barrier
	s_nop 1
	ds_read_b128 v[66:69], v140 offset:16384
	ds_read_b128 v[70:73], v140 offset:17408
	ds_read_b128 v[74:77], v140 offset:18432
	ds_read_b128 v[78:81], v140 offset:19456
	ds_read_b128 v[184:187], v140 offset:20480
	ds_read_b128 v[188:191], v140 offset:21504
	ds_read_b128 v[192:195], v140 offset:22528
	ds_read_b128 v[196:199], v140 offset:23552
	s_waitcnt vmcnt(4)
	s_barrier
; #define LDA(dst, b, h) _Pragma("unroll") for (int m = 0; m < 4; ++m) _Pragma("unroll") for (int k = 0; k < 2; ++k) \
;     dst[m][k] = *(const __attribute__((address_space(3))) bf16x8*)(aB + (((b) * 2 + (h)) * 16384 + m * 2048 + k * 1024))
; #define LDB(dst, b, h) _Pragma("unroll") for (int n = 0; n < 2; ++n) _Pragma("unroll") for (int k = 0; k < 2; ++k) \
;     dst[n][k] = *(const __attribute__((address_space(3))) bf16x8*)(bB + (((b) * 2 + (h)) * 16384 + n * 2048 + k * 1024))
; #define MMA(ai, bj, At, Bq) do { __builtin_amdgcn_s_setprio(1); \
;     _Pragma("unroll") for (int m = 0; m < 4; ++m) _Pragma("unroll") for (int n = 0; n < 2; ++n) _Pragma("unroll") for (int k = 0; k < 2; ++k) \
;       acc[ai][bj][m][n] = __builtin_amdgcn_mfma_f32_16x16x32_bf16(At[m][k], Bq[n][k], acc[ai][bj][m][n], 0, 0, 0); \
;     __builtin_amdgcn_s_setprio(0); } while (0)
; #define WAIT_V(n) asm volatile("s_waitcnt vmcnt(" #n ")" ::: "memory")
; #define WAIT_L(n) asm volatile("s_waitcnt lgkmcnt(" #n ")" ::: "memory")
; #define BAR __builtin_amdgcn_s_barrier()
; template <int MODE>
; DI void gemm_tile(const Params& p, const bf16_t* __restrict__ A, const bf16_t* __restrict__ Bt, int K, int brow, int bcol, int mp, int nt, bool vt, char* smem) {
;     ...
;     LDA(At, 0, 1); WAIT_V(4); BAR; WAIT_L(0); MMA(1, 0, At, B0); MMA(1, 1, At, B1); BAR; }
;   { LDB(B0, 1, 0); LDA(At, 1, 0); WAIT_V(2); BAR; WAIT_L(0); MMA(0, 0, At, B0); BAR;
	s_waitcnt lgkmcnt(0)
	s_setprio 1
	s_waitcnt lgkmcnt(7)
	v_mfma_f32_16x16x32_bf16 v[62:65], v[66:69], v[134:137], v[62:65]
	v_mfma_f32_16x16x32_bf16 v[58:61], v[66:69], v[156:159], v[58:61]
	s_waitcnt lgkmcnt(5)
	v_mfma_f32_16x16x32_bf16 v[54:57], v[74:77], v[134:137], v[54:57]
	v_mfma_f32_16x16x32_bf16 v[50:53], v[74:77], v[156:159], v[50:53]
	v_mfma_f32_16x16x32_bf16 v[62:65], v[70:73], v[148:151], v[62:65]
	v_mfma_f32_16x16x32_bf16 v[58:61], v[70:73], v[164:167], v[58:61]
	s_waitcnt lgkmcnt(4)
	v_mfma_f32_16x16x32_bf16 v[54:57], v[78:81], v[148:151], v[54:57]
	v_mfma_f32_16x16x32_bf16 v[50:53], v[78:81], v[164:167], v[50:53]
	s_waitcnt lgkmcnt(3)
	v_mfma_f32_16x16x32_bf16 v[46:49], v[184:187], v[134:137], v[46:49]
	v_mfma_f32_16x16x32_bf16 v[42:45], v[184:187], v[156:159], v[42:45]
	s_waitcnt lgkmcnt(1)
	v_mfma_f32_16x16x32_bf16 v[38:41], v[192:195], v[134:137], v[38:41]
	v_mfma_f32_16x16x32_bf16 v[34:37], v[192:195], v[156:159], v[34:37]
	v_mfma_f32_16x16x32_bf16 v[222:225], v[188:191], v[148:151], v[46:49]
	v_mfma_f32_16x16x32_bf16 v[226:229], v[188:191], v[164:167], v[42:45]
	s_waitcnt lgkmcnt(0)
	v_mfma_f32_16x16x32_bf16 v[134:137], v[196:199], v[148:151], v[38:41]
	v_mfma_f32_16x16x32_bf16 v[148:151], v[196:199], v[164:167], v[34:37]
	s_setprio 0
	s_setprio 1
	v_mfma_f32_16x16x32_bf16 v[30:33], v[66:69], v[98:101], v[30:33]
	v_mfma_f32_16x16x32_bf16 v[26:29], v[66:69], v[106:109], v[26:29]
	v_mfma_f32_16x16x32_bf16 v[22:25], v[74:77], v[98:101], v[22:25]
	v_mfma_f32_16x16x32_bf16 v[18:21], v[74:77], v[106:109], v[18:21]
	v_mfma_f32_16x16x32_bf16 v[30:33], v[70:73], v[102:105], v[30:33]
	v_mfma_f32_16x16x32_bf16 v[26:29], v[70:73], v[110:113], v[26:29]
	v_mfma_f32_16x16x32_bf16 v[22:25], v[78:81], v[102:105], v[22:25]
	v_mfma_f32_16x16x32_bf16 v[18:21], v[78:81], v[110:113], v[18:21]
	v_mfma_f32_16x16x32_bf16 v[14:17], v[184:187], v[98:101], v[14:17]
	v_mfma_f32_16x16x32_bf16 v[10:13], v[184:187], v[106:109], v[10:13]
	v_mfma_f32_16x16x32_bf16 v[6:9], v[192:195], v[98:101], v[6:9]
	v_mfma_f32_16x16x32_bf16 v[2:5], v[192:195], v[106:109], v[2:5]
	v_mfma_f32_16x16x32_bf16 v[156:159], v[188:191], v[102:105], v[14:17]
	v_mfma_f32_16x16x32_bf16 v[164:167], v[188:191], v[110:113], v[10:13]
	v_mfma_f32_16x16x32_bf16 v[184:187], v[196:199], v[102:105], v[6:9]
	v_mfma_f32_16x16x32_bf16 v[188:191], v[196:199], v[110:113], v[2:5]
	s_setprio 0
	s_barrier
	s_nop 1
	ds_read_b128 v[2:5], v142 offset:32768
	ds_read_b128 v[6:9], v142 offset:33792
	ds_read_b128 v[10:13], v142 offset:34816
	ds_read_b128 v[14:17], v142 offset:35840
	ds_read_b128 v[34:37], v140 offset:32768
	ds_read_b128 v[38:41], v140 offset:33792
	ds_read_b128 v[42:45], v140 offset:34816
	ds_read_b128 v[46:49], v140 offset:35840
	ds_read_b128 v[192:195], v140 offset:36864
	ds_read_b128 v[196:199], v140 offset:37888
	ds_read_b128 v[230:233], v140 offset:38912
	ds_read_b128 v[234:237], v140 offset:39936
	s_waitcnt vmcnt(2)
	s_barrier
	s_waitcnt lgkmcnt(0)
	s_setprio 1
	s_waitcnt lgkmcnt(7)
	v_mfma_f32_16x16x32_bf16 v[66:69], v[34:37], v[2:5], v[126:129]
	s_waitcnt lgkmcnt(6)
	v_mfma_f32_16x16x32_bf16 v[98:101], v[38:41], v[6:9], v[66:69]
	v_mfma_f32_16x16x32_bf16 v[66:69], v[34:37], v[10:13], v[122:125]
	v_mfma_f32_16x16x32_bf16 v[102:105], v[38:41], v[14:17], v[66:69]
	s_waitcnt lgkmcnt(5)
	v_mfma_f32_16x16x32_bf16 v[66:69], v[42:45], v[2:5], v[118:121]
	s_waitcnt lgkmcnt(4)
	v_mfma_f32_16x16x32_bf16 v[106:109], v[46:49], v[6:9], v[66:69]
	v_mfma_f32_16x16x32_bf16 v[66:69], v[42:45], v[10:13], v[114:117]
	v_mfma_f32_16x16x32_bf16 v[110:113], v[46:49], v[14:17], v[66:69]
	s_waitcnt lgkmcnt(3)
	v_mfma_f32_16x16x32_bf16 v[66:69], v[192:195], v[2:5], v[130:133]
	s_waitcnt lgkmcnt(2)
	v_mfma_f32_16x16x32_bf16 v[114:117], v[196:199], v[6:9], v[66:69]
	v_mfma_f32_16x16x32_bf16 v[66:69], v[192:195], v[10:13], v[160:163]
	v_mfma_f32_16x16x32_bf16 v[118:121], v[196:199], v[14:17], v[66:69]
	s_waitcnt lgkmcnt(1)
	v_mfma_f32_16x16x32_bf16 v[66:69], v[230:233], v[2:5], v[214:217]
	s_waitcnt lgkmcnt(0)
	v_mfma_f32_16x16x32_bf16 v[122:125], v[234:237], v[6:9], v[66:69]
	v_mfma_f32_16x16x32_bf16 v[66:69], v[230:233], v[10:13], v[218:221]
	v_mfma_f32_16x16x32_bf16 v[126:129], v[234:237], v[14:17], v[66:69]
	s_setprio 0
	s_barrier
; #define LDA(dst, b, h) _Pragma("unroll") for (int m = 0; m < 4; ++m) _Pragma("unroll") for (int k = 0; k < 2; ++k) \
;     dst[m][k] = *(const __attribute__((address_space(3))) bf16x8*)(aB + (((b) * 2 + (h)) * 16384 + m * 2048 + k * 1024))
; #define LDB(dst, b, h) _Pragma("unroll") for (int n = 0; n < 2; ++n) _Pragma("unroll") for (int k = 0; k < 2; ++k) \
;     dst[n][k] = *(const __attribute__((address_space(3))) bf16x8*)(bB + (((b) * 2 + (h)) * 16384 + n * 2048 + k * 1024))
; #define MMA(ai, bj, At, Bq) do { __builtin_amdgcn_s_setprio(1); \
;     _Pragma("unroll") for (int m = 0; m < 4; ++m) _Pragma("unroll") for (int n = 0; n < 2; ++n) _Pragma("unroll") for (int k = 0; k < 2; ++k) \
;       acc[ai][bj][m][n] = __builtin_amdgcn_mfma_f32_16x16x32_bf16(At[m][k], Bq[n][k], acc[ai][bj][m][n], 0, 0, 0); \
;     __builtin_amdgcn_s_setprio(0); } while (0)
; #define WAIT_V(n) asm volatile("s_waitcnt vmcnt(" #n ")" ::: "memory")
; #define WAIT_L(n) asm volatile("s_waitcnt lgkmcnt(" #n ")" ::: "memory")
; #define BAR __builtin_amdgcn_s_barrier()
; template <int MODE>
; DI void gemm_tile(const Params& p, const bf16_t* __restrict__ A, const bf16_t* __restrict__ Bt, int K, int brow, int bcol, int mp, int nt, bool vt, char* smem) {
;     ...
;     LDB(B1, 1, 1); WAIT_V(0); BAR; WAIT_L(0); MMA(0, 1, At, B1); BAR;
;     LDA(At, 1, 1); BAR; WAIT_L(0); MMA(1, 0, At, B0); MMA(1, 1, At, B1); BAR; }
;   if (wr == 0) BAR;
	ds_read_b128 v[130:133], v142 offset:49152
	ds_read_b128 v[160:163], v142 offset:50176
	ds_read_b128 v[214:217], v142 offset:51200
	ds_read_b128 v[218:221], v142 offset:52224
	s_waitcnt vmcnt(0)
	s_barrier
	s_waitcnt lgkmcnt(0)
	s_setprio 1
	s_waitcnt lgkmcnt(3)
	v_mfma_f32_16x16x32_bf16 v[66:69], v[34:37], v[130:133], v[94:97]
	s_waitcnt lgkmcnt(1)
	v_mfma_f32_16x16x32_bf16 v[34:37], v[34:37], v[214:217], v[90:93]
	s_waitcnt lgkmcnt(0)
	v_mfma_f32_16x16x32_bf16 v[70:73], v[38:41], v[218:221], v[34:37]
	v_mfma_f32_16x16x32_bf16 v[34:37], v[42:45], v[130:133], v[86:89]
	v_mfma_f32_16x16x32_bf16 v[74:77], v[46:49], v[160:163], v[34:37]
	v_mfma_f32_16x16x32_bf16 v[34:37], v[42:45], v[214:217], v[82:85]
	v_mfma_f32_16x16x32_bf16 v[78:81], v[46:49], v[218:221], v[34:37]
	v_mfma_f32_16x16x32_bf16 v[34:37], v[192:195], v[130:133], v[168:171]
	v_mfma_f32_16x16x32_bf16 v[82:85], v[196:199], v[160:163], v[34:37]
	v_mfma_f32_16x16x32_bf16 v[34:37], v[192:195], v[214:217], v[172:175]
	v_mfma_f32_16x16x32_bf16 v[86:89], v[196:199], v[218:221], v[34:37]
	v_mfma_f32_16x16x32_bf16 v[34:37], v[230:233], v[130:133], v[176:179]
	v_mfma_f32_16x16x32_bf16 v[90:93], v[234:237], v[160:163], v[34:37]
	v_mfma_f32_16x16x32_bf16 v[34:37], v[230:233], v[214:217], v[180:183]
	v_mfma_f32_16x16x32_bf16 v[66:69], v[38:41], v[160:163], v[66:69]
	v_mfma_f32_16x16x32_bf16 v[94:97], v[234:237], v[218:221], v[34:37]
	s_setprio 0
	s_barrier
	ds_read_b128 v[168:171], v140 offset:49152
	ds_read_b128 v[172:175], v140 offset:50176
	ds_read_b128 v[176:179], v140 offset:51200
	ds_read_b128 v[180:183], v140 offset:52224
	ds_read_b128 v[192:195], v140 offset:53248
	ds_read_b128 v[196:199], v140 offset:54272
	ds_read_b128 v[230:233], v140 offset:55296
	ds_read_b128 v[138:141], v140 offset:56320
	s_barrier
	s_waitcnt lgkmcnt(0)
	s_setprio 1
	s_waitcnt lgkmcnt(7)
	v_mfma_f32_16x16x32_bf16 v[34:37], v[168:171], v[2:5], v[62:65]
	s_waitcnt lgkmcnt(5)
	v_mfma_f32_16x16x32_bf16 v[42:45], v[176:179], v[2:5], v[54:57]
	v_mfma_f32_16x16x32_bf16 v[46:49], v[176:179], v[10:13], v[50:53]
	s_waitcnt lgkmcnt(3)
	v_mfma_f32_16x16x32_bf16 v[50:53], v[192:195], v[2:5], v[222:225]
	s_waitcnt lgkmcnt(1)
	v_mfma_f32_16x16x32_bf16 v[2:5], v[230:233], v[2:5], v[134:137]
	v_mfma_f32_16x16x32_bf16 v[38:41], v[168:171], v[10:13], v[58:61]
	v_mfma_f32_16x16x32_bf16 v[54:57], v[192:195], v[10:13], v[226:229]
	s_waitcnt lgkmcnt(0)
	v_mfma_f32_16x16x32_bf16 v[58:61], v[138:141], v[6:9], v[2:5]
	v_mfma_f32_16x16x32_bf16 v[2:5], v[230:233], v[10:13], v[148:151]
	v_mfma_f32_16x16x32_bf16 v[34:37], v[172:175], v[6:9], v[34:37]
	v_mfma_f32_16x16x32_bf16 v[38:41], v[172:175], v[14:17], v[38:41]
	v_mfma_f32_16x16x32_bf16 v[42:45], v[180:183], v[6:9], v[42:45]
	v_mfma_f32_16x16x32_bf16 v[46:49], v[180:183], v[14:17], v[46:49]
	v_mfma_f32_16x16x32_bf16 v[50:53], v[196:199], v[6:9], v[50:53]
	v_mfma_f32_16x16x32_bf16 v[54:57], v[196:199], v[14:17], v[54:57]
	v_mfma_f32_16x16x32_bf16 v[62:65], v[138:141], v[14:17], v[2:5]
	s_setprio 0
	s_setprio 1
	v_mfma_f32_16x16x32_bf16 v[2:5], v[168:171], v[130:133], v[30:33]
	v_mfma_f32_16x16x32_bf16 v[6:9], v[168:171], v[214:217], v[26:29]
	v_mfma_f32_16x16x32_bf16 v[10:13], v[176:179], v[130:133], v[22:25]
	v_mfma_f32_16x16x32_bf16 v[14:17], v[176:179], v[214:217], v[18:21]
	v_mfma_f32_16x16x32_bf16 v[18:21], v[192:195], v[130:133], v[156:159]
	v_mfma_f32_16x16x32_bf16 v[22:25], v[192:195], v[214:217], v[164:167]
	v_mfma_f32_16x16x32_bf16 v[26:29], v[230:233], v[130:133], v[184:187]
	v_mfma_f32_16x16x32_bf16 v[30:33], v[230:233], v[214:217], v[188:191]
	v_mfma_f32_16x16x32_bf16 v[2:5], v[172:175], v[160:163], v[2:5]
	v_mfma_f32_16x16x32_bf16 v[6:9], v[172:175], v[218:221], v[6:9]
	v_mfma_f32_16x16x32_bf16 v[10:13], v[180:183], v[160:163], v[10:13]
	v_mfma_f32_16x16x32_bf16 v[14:17], v[180:183], v[218:221], v[14:17]
	v_mfma_f32_16x16x32_bf16 v[18:21], v[196:199], v[160:163], v[18:21]
	v_mfma_f32_16x16x32_bf16 v[22:25], v[196:199], v[218:221], v[22:25]
	v_mfma_f32_16x16x32_bf16 v[26:29], v[138:141], v[160:163], v[26:29]
	v_mfma_f32_16x16x32_bf16 v[30:33], v[138:141], v[218:221], v[30:33]
	s_setprio 0
	s_movk_i32 s1, 0x100
	v_cmp_gt_u32_e32 vcc, s1, v144
	s_barrier
	s_and_saveexec_b64 s[6:7], vcc
	s_cbranch_execz .LBB0_62
	s_barrier

; #define STAGE(P, BASE, br, kt) do { const bf16_t* _gb = (BASE) + (long)(br) * K + (long)(kt) * 64; asm volatile("" : "+s"(_gb)); \
;     __builtin_amdgcn_global_load_lds((const unsigned*)(_gb + go0), (lds_u32*)((char*)(P) + tid * 16), 16, 0, 0); \
;     __builtin_amdgcn_global_load_lds((const unsigned*)(_gb + go1), (lds_u32*)((char*)(P) + tid * 16 + 8192), 16, 0, 0); } while (0)
; #define LDA(dst, b, h) _Pragma("unroll") for (int m = 0; m < 4; ++m) _Pragma("unroll") for (int k = 0; k < 2; ++k) \
;     dst[m][k] = *(const __attribute__((address_space(3))) bf16x8*)(aB + (((b) * 2 + (h)) * 16384 + m * 2048 + k * 1024))
; #define LDB(dst, b, h) _Pragma("unroll") for (int n = 0; n < 2; ++n) _Pragma("unroll") for (int k = 0; k < 2; ++k) \
;     dst[n][k] = *(const __attribute__((address_space(3))) bf16x8*)(bB + (((b) * 2 + (h)) * 16384 + n * 2048 + k * 1024))
; #define MMA(ai, bj, At, Bq) do { __builtin_amdgcn_s_setprio(1); \
;     _Pragma("unroll") for (int m = 0; m < 4; ++m) _Pragma("unroll") for (int n = 0; n < 2; ++n) _Pragma("unroll") for (int k = 0; k < 2; ++k) \
;       acc[ai][bj][m][n] = __builtin_amdgcn_mfma_f32_16x16x32_bf16(At[m][k], Bq[n][k], acc[ai][bj][m][n], 0, 0, 0); \
;     __builtin_amdgcn_s_setprio(0); } while (0)
; #define WAIT_L(n) asm volatile("s_waitcnt lgkmcnt(" #n ")" ::: "memory")
; #define BAR __builtin_amdgcn_s_barrier()
; #define SCHED __builtin_amdgcn_sched_barrier(0)
; template <int MODE>
; DI void gemm_tile(const Params& p, const bf16_t* __restrict__ A, const bf16_t* __restrict__ Bt, int K, int brow, int bcol, int mp, int nt, bool vt, char* smem) {
;     ...
;     LDB(B0, 1, 0); SCHED; LDA(At, 1, 0); STAGE(SA(0, 1), A, brow + 128, t + 2);
;     WAIT_L(8); BAR; WAIT_L(0); MMA(0, 0, At, B0); BAR; SCHED;
;     LDB(B1, 1, 1); STAGE(SB(1, 0), Bt, bcol, t + 3);
;     BAR; WAIT_L(0); MMA(0, 1, At, B1); BAR;
;     LDA(At, 1, 1); STAGE(SA(1, 0), A, brow, t + 3);
;     BAR; WAIT_L(0); MMA(1, 0, At, B0); BAR; SCHED;
.Lgemm2_p5:
	s_nop 0
	ds_read_b128 v[164:167], v142 offset:32768
	ds_read_b128 v[168:171], v142 offset:33792
	ds_read_b128 v[172:175], v142 offset:34816
	ds_read_b128 v[176:179], v142 offset:35840
	s_add_u32 s26, s1, s14
	s_addc_u32 s27, s5, s15
	v_readfirstlane_b32 s35, v150
	ds_read_b128 v[180:183], v140 offset:32768
	ds_read_b128 v[184:187], v140 offset:33792
	ds_read_b128 v[188:191], v140 offset:34816
	ds_read_b128 v[192:195], v140 offset:35840
	ds_read_b128 v[196:199], v140 offset:36864
	ds_read_b128 v[214:217], v140 offset:37888
	ds_read_b128 v[218:221], v140 offset:38912
	ds_read_b128 v[222:225], v140 offset:39936
	s_mov_b32 m0, s35
	v_lshl_add_u64 v[226:227], s[26:27], 0, v[134:135]
	global_load_lds_dwordx4 v[226:227], off
	v_lshl_add_u64 v[226:227], s[26:27], 0, v[136:137]
	v_readfirstlane_b32 s26, v151
	s_mov_b32 m0, s26
	s_nop 0
	global_load_lds_dwordx4 v[226:227], off
	s_waitcnt lgkmcnt(8)
	s_barrier
	s_waitcnt lgkmcnt(0)
	s_setprio 1
	s_waitcnt lgkmcnt(0)
	v_mfma_f32_16x16x32_bf16 v[126:129], v[180:183], v[164:167], v[126:129]
	v_mfma_f32_16x16x32_bf16 v[122:125], v[180:183], v[172:175], v[122:125]
	v_mfma_f32_16x16x32_bf16 v[118:121], v[188:191], v[164:167], v[118:121]
	v_mfma_f32_16x16x32_bf16 v[114:117], v[188:191], v[172:175], v[114:117]
	v_mfma_f32_16x16x32_bf16 v[110:113], v[196:199], v[164:167], v[110:113]
	v_mfma_f32_16x16x32_bf16 v[106:109], v[196:199], v[172:175], v[106:109]
	v_mfma_f32_16x16x32_bf16 v[102:105], v[218:221], v[164:167], v[102:105]
	v_mfma_f32_16x16x32_bf16 v[98:101], v[218:221], v[172:175], v[98:101]
	v_mfma_f32_16x16x32_bf16 v[126:129], v[184:187], v[168:171], v[126:129]
	v_mfma_f32_16x16x32_bf16 v[122:125], v[184:187], v[176:179], v[122:125]
	v_mfma_f32_16x16x32_bf16 v[118:121], v[192:195], v[168:171], v[118:121]
	v_mfma_f32_16x16x32_bf16 v[114:117], v[192:195], v[176:179], v[114:117]
	v_mfma_f32_16x16x32_bf16 v[110:113], v[214:217], v[168:171], v[110:113]
	v_mfma_f32_16x16x32_bf16 v[106:109], v[214:217], v[176:179], v[106:109]
	v_mfma_f32_16x16x32_bf16 v[102:105], v[222:225], v[168:171], v[102:105]
	v_mfma_f32_16x16x32_bf16 v[98:101], v[222:225], v[176:179], v[98:101]
	s_setprio 0
	s_barrier
	s_add_u32 s26, s25, 0x180
	s_addc_u32 s27, s28, 0
	v_readfirstlane_b32 s25, v156
	s_nop 0
	ds_read_b128 v[226:229], v142 offset:49152
	ds_read_b128 v[230:233], v142 offset:50176
	ds_read_b128 v[234:237], v142 offset:51200
	ds_read_b128 v[238:241], v142 offset:52224
	s_mov_b32 m0, s25
	v_lshl_add_u64 v[242:243], s[26:27], 0, v[134:135]
	v_readfirstlane_b32 s25, v157
	global_load_lds_dwordx4 v[242:243], off
	v_lshl_add_u64 v[242:243], s[26:27], 0, v[136:137]
	s_mov_b32 m0, s25
	s_nop 0
	global_load_lds_dwordx4 v[242:243], off
	s_barrier
	s_waitcnt lgkmcnt(0)
	s_setprio 1
	s_waitcnt lgkmcnt(0)
	v_mfma_f32_16x16x32_bf16 v[94:97], v[180:183], v[226:229], v[94:97]
	v_mfma_f32_16x16x32_bf16 v[90:93], v[180:183], v[234:237], v[90:93]
	v_mfma_f32_16x16x32_bf16 v[86:89], v[188:191], v[226:229], v[86:89]
	v_mfma_f32_16x16x32_bf16 v[82:85], v[188:191], v[234:237], v[82:85]
	v_mfma_f32_16x16x32_bf16 v[78:81], v[196:199], v[226:229], v[78:81]
	v_mfma_f32_16x16x32_bf16 v[74:77], v[196:199], v[234:237], v[74:77]
	v_mfma_f32_16x16x32_bf16 v[70:73], v[218:221], v[226:229], v[70:73]
	v_mfma_f32_16x16x32_bf16 v[66:69], v[218:221], v[234:237], v[66:69]
	v_mfma_f32_16x16x32_bf16 v[94:97], v[184:187], v[230:233], v[94:97]
	v_mfma_f32_16x16x32_bf16 v[90:93], v[184:187], v[238:241], v[90:93]
	v_mfma_f32_16x16x32_bf16 v[86:89], v[192:195], v[230:233], v[86:89]
	v_mfma_f32_16x16x32_bf16 v[82:85], v[192:195], v[238:241], v[82:85]
	v_mfma_f32_16x16x32_bf16 v[78:81], v[214:217], v[230:233], v[78:81]
	v_mfma_f32_16x16x32_bf16 v[74:77], v[214:217], v[238:241], v[74:77]
	v_mfma_f32_16x16x32_bf16 v[70:73], v[222:225], v[230:233], v[70:73]
	v_mfma_f32_16x16x32_bf16 v[66:69], v[222:225], v[238:241], v[66:69]
	s_setprio 0
	s_add_u32 s26, s29, 0x180
	s_addc_u32 s27, s30, 0
	v_readfirstlane_b32 s25, v158
	s_barrier
	s_nop 0
	ds_read_b128 v[180:183], v140 offset:49152
	ds_read_b128 v[184:187], v140 offset:50176
	ds_read_b128 v[188:191], v140 offset:51200
	ds_read_b128 v[192:195], v140 offset:52224
	ds_read_b128 v[196:199], v140 offset:53248
	ds_read_b128 v[214:217], v140 offset:54272
	ds_read_b128 v[218:221], v140 offset:55296
	ds_read_b128 v[222:225], v140 offset:56320
	s_mov_b32 m0, s25
	v_lshl_add_u64 v[242:243], s[26:27], 0, v[134:135]
	v_readfirstlane_b32 s25, v159
	global_load_lds_dwordx4 v[242:243], off
	v_lshl_add_u64 v[242:243], s[26:27], 0, v[136:137]
	s_mov_b32 m0, s25
	s_nop 0
	global_load_lds_dwordx4 v[242:243], off
	s_barrier
	s_waitcnt lgkmcnt(0)
	s_setprio 1
	s_waitcnt lgkmcnt(0)
	v_mfma_f32_16x16x32_bf16 v[62:65], v[180:183], v[164:167], v[62:65]
	v_mfma_f32_16x16x32_bf16 v[58:61], v[180:183], v[172:175], v[58:61]
	v_mfma_f32_16x16x32_bf16 v[54:57], v[188:191], v[164:167], v[54:57]
	v_mfma_f32_16x16x32_bf16 v[50:53], v[188:191], v[172:175], v[50:53]
	v_mfma_f32_16x16x32_bf16 v[46:49], v[196:199], v[164:167], v[46:49]
	v_mfma_f32_16x16x32_bf16 v[42:45], v[196:199], v[172:175], v[42:45]
	v_mfma_f32_16x16x32_bf16 v[38:41], v[218:221], v[164:167], v[38:41]
	v_mfma_f32_16x16x32_bf16 v[34:37], v[218:221], v[172:175], v[34:37]
	v_mfma_f32_16x16x32_bf16 v[62:65], v[184:187], v[168:171], v[62:65]
	v_mfma_f32_16x16x32_bf16 v[58:61], v[184:187], v[176:179], v[58:61]
	v_mfma_f32_16x16x32_bf16 v[54:57], v[192:195], v[168:171], v[54:57]
	v_mfma_f32_16x16x32_bf16 v[50:53], v[192:195], v[176:179], v[50:53]
	v_mfma_f32_16x16x32_bf16 v[46:49], v[214:217], v[168:171], v[46:49]
	v_mfma_f32_16x16x32_bf16 v[42:45], v[214:217], v[176:179], v[42:45]
	v_mfma_f32_16x16x32_bf16 v[38:41], v[222:225], v[168:171], v[38:41]
	v_mfma_f32_16x16x32_bf16 v[34:37], v[222:225], v[176:179], v[34:37]
	s_setprio 0
	s_barrier
; #define STAGE(P, BASE, br, kt) do { const bf16_t* _gb = (BASE) + (long)(br) * K + (long)(kt) * 64; asm volatile("" : "+s"(_gb)); \
;     __builtin_amdgcn_global_load_lds((const unsigned*)(_gb + go0), (lds_u32*)((char*)(P) + tid * 16), 16, 0, 0); \
;     __builtin_amdgcn_global_load_lds((const unsigned*)(_gb + go1), (lds_u32*)((char*)(P) + tid * 16 + 8192), 16, 0, 0); } while (0)
; #define LDA(dst, b, h) _Pragma("unroll") for (int m = 0; m < 4; ++m) _Pragma("unroll") for (int k = 0; k < 2; ++k) \
;     dst[m][k] = *(const __attribute__((address_space(3))) bf16x8*)(aB + (((b) * 2 + (h)) * 16384 + m * 2048 + k * 1024))
; #define LDB(dst, b, h) _Pragma("unroll") for (int n = 0; n < 2; ++n) _Pragma("unroll") for (int k = 0; k < 2; ++k) \
;     dst[n][k] = *(const __attribute__((address_space(3))) bf16x8*)(bB + (((b) * 2 + (h)) * 16384 + n * 2048 + k * 1024))
; #define MMA(ai, bj, At, Bq) do { __builtin_amdgcn_s_setprio(1); \
;     _Pragma("unroll") for (int m = 0; m < 4; ++m) _Pragma("unroll") for (int n = 0; n < 2; ++n) _Pragma("unroll") for (int k = 0; k < 2; ++k) \
;       acc[ai][bj][m][n] = __builtin_amdgcn_mfma_f32_16x16x32_bf16(At[m][k], Bq[n][k], acc[ai][bj][m][n], 0, 0, 0); \
;     __builtin_amdgcn_s_setprio(0); } while (0)
; #define WAIT_V(n) asm volatile("s_waitcnt vmcnt(" #n ")" ::: "memory")
; #define WAIT_L(n) asm volatile("s_waitcnt lgkmcnt(" #n ")" ::: "memory")
; #define BAR __builtin_amdgcn_s_barrier()
; template <int MODE>
; DI void gemm_tile(const Params& p, const bf16_t* __restrict__ A, const bf16_t* __restrict__ Bt, int K, int brow, int bcol, int mp, int nt, bool vt, char* smem) {
;     ...
;     STAGE(SB(1, 1), Bt, bcol + 128, t + 3);
;     WAIT_V(6); BAR; MMA(1, 1, At, B1); BAR;
;   }
;   { LDB(B0, 0, 0); LDA(At, 0, 0); STAGE(SA(1, 1), A, brow + 128, ntk - 1);
;     BAR; WAIT_L(0); MMA(0, 0, At, B0); BAR;
;     LDB(B1, 0, 1); BAR; WAIT_L(0); MMA(0, 1, At, B1); BAR;
;     LDA(At, 0, 1); WAIT_V(4); BAR; WAIT_L(0); MMA(1, 0, At, B0); MMA(1, 1, At, B1); BAR; }
	s_add_u32 s26, s31, 0x180
	s_addc_u32 s27, s34, 0
	v_readfirstlane_b32 s25, v160
	s_mov_b32 m0, s25
	v_lshl_add_u64 v[164:165], s[26:27], 0, v[134:135]
	v_readfirstlane_b32 s25, v161
	global_load_lds_dwordx4 v[164:165], off
	v_lshl_add_u64 v[164:165], s[26:27], 0, v[136:137]
	s_mov_b32 m0, s25
	s_nop 0
	global_load_lds_dwordx4 v[164:165], off
	s_waitcnt vmcnt(6)
	s_barrier
	s_setprio 1
	v_mfma_f32_16x16x32_bf16 v[30:33], v[180:183], v[226:229], v[30:33]
	v_mfma_f32_16x16x32_bf16 v[26:29], v[180:183], v[234:237], v[26:29]
	v_mfma_f32_16x16x32_bf16 v[22:25], v[188:191], v[226:229], v[22:25]
	v_mfma_f32_16x16x32_bf16 v[18:21], v[188:191], v[234:237], v[18:21]
	v_mfma_f32_16x16x32_bf16 v[14:17], v[196:199], v[226:229], v[14:17]
	v_mfma_f32_16x16x32_bf16 v[10:13], v[196:199], v[234:237], v[10:13]
	v_mfma_f32_16x16x32_bf16 v[6:9], v[218:221], v[226:229], v[6:9]
	v_mfma_f32_16x16x32_bf16 v[2:5], v[218:221], v[234:237], v[2:5]
	v_mfma_f32_16x16x32_bf16 v[30:33], v[184:187], v[230:233], v[30:33]
	v_mfma_f32_16x16x32_bf16 v[26:29], v[184:187], v[238:241], v[26:29]
	v_mfma_f32_16x16x32_bf16 v[22:25], v[192:195], v[230:233], v[22:25]
	v_mfma_f32_16x16x32_bf16 v[18:21], v[192:195], v[238:241], v[18:21]
	v_mfma_f32_16x16x32_bf16 v[14:17], v[214:217], v[230:233], v[14:17]
	v_mfma_f32_16x16x32_bf16 v[10:13], v[214:217], v[238:241], v[10:13]
	v_mfma_f32_16x16x32_bf16 v[6:9], v[222:225], v[230:233], v[6:9]
	v_mfma_f32_16x16x32_bf16 v[2:5], v[222:225], v[238:241], v[2:5]
	s_setprio 0
	s_add_i32 s24, s24, 2
	s_add_u32 s14, s14, 0x100
	s_addc_u32 s15, s15, 0
	s_cmp_lt_u32 s24, 60
	s_barrier
	s_cbranch_scc1 .LBB0_526
	s_add_u32 s6, s12, 0x1f80
	s_addc_u32 s7, s13, 0
	v_readfirstlane_b32 s1, v162
	s_nop 0
	ds_read_b128 v[134:137], v142
	ds_read_b128 v[148:151], v142 offset:1024
	ds_read_b128 v[156:159], v142 offset:2048
	ds_read_b128 v[164:167], v142 offset:3072
	ds_read_b128 v[168:171], v140
	ds_read_b128 v[172:175], v140 offset:1024
	ds_read_b128 v[176:179], v140 offset:2048
	ds_read_b128 v[180:183], v140 offset:3072
	ds_read_b128 v[184:187], v140 offset:4096
	ds_read_b128 v[188:191], v140 offset:5120
	ds_read_b128 v[192:195], v140 offset:6144
	ds_read_b128 v[196:199], v140 offset:7168
	s_mov_b32 m0, s1
	v_lshl_add_u64 v[132:133], v[132:133], 1, s[6:7]
	v_readfirstlane_b32 s1, v163
	global_load_lds_dwordx4 v[132:133], off
	v_lshl_add_u64 v[130:131], v[130:131], 1, s[6:7]
	s_mov_b32 m0, s1
	s_nop 0
	global_load_lds_dwordx4 v[130:131], off
	s_barrier
	s_waitcnt lgkmcnt(0)
	s_setprio 1
	s_waitcnt lgkmcnt(0)
	v_mfma_f32_16x16x32_bf16 v[126:129], v[168:171], v[134:137], v[126:129]
	v_mfma_f32_16x16x32_bf16 v[122:125], v[168:171], v[156:159], v[122:125]
	v_mfma_f32_16x16x32_bf16 v[118:121], v[176:179], v[134:137], v[118:121]
	v_mfma_f32_16x16x32_bf16 v[114:117], v[176:179], v[156:159], v[114:117]
	v_mfma_f32_16x16x32_bf16 v[126:129], v[172:175], v[148:151], v[126:129]
	v_mfma_f32_16x16x32_bf16 v[122:125], v[172:175], v[164:167], v[122:125]
	v_mfma_f32_16x16x32_bf16 v[118:121], v[180:183], v[148:151], v[118:121]
	v_mfma_f32_16x16x32_bf16 v[114:117], v[180:183], v[164:167], v[114:117]
	v_mfma_f32_16x16x32_bf16 v[110:113], v[184:187], v[134:137], v[110:113]
	v_mfma_f32_16x16x32_bf16 v[106:109], v[184:187], v[156:159], v[106:109]
	v_mfma_f32_16x16x32_bf16 v[102:105], v[192:195], v[134:137], v[102:105]
	v_mfma_f32_16x16x32_bf16 v[98:101], v[192:195], v[156:159], v[98:101]
	v_mfma_f32_16x16x32_bf16 v[130:133], v[188:191], v[148:151], v[110:113]
	v_mfma_f32_16x16x32_bf16 v[160:163], v[188:191], v[164:167], v[106:109]
	v_mfma_f32_16x16x32_bf16 v[214:217], v[196:199], v[148:151], v[102:105]
	v_mfma_f32_16x16x32_bf16 v[218:221], v[196:199], v[164:167], v[98:101]
	s_setprio 0
	s_barrier
	s_nop 0
	s_nop 0
	ds_read_b128 v[98:101], v142 offset:16384
	ds_read_b128 v[102:105], v142 offset:17408
	ds_read_b128 v[106:109], v142 offset:18432
	ds_read_b128 v[110:113], v142 offset:19456
	s_barrier
	s_waitcnt lgkmcnt(0)
	s_setprio 1
	s_waitcnt lgkmcnt(3)
	v_mfma_f32_16x16x32_bf16 v[94:97], v[168:171], v[98:101], v[94:97]
	s_waitcnt lgkmcnt(1)
	v_mfma_f32_16x16x32_bf16 v[90:93], v[168:171], v[106:109], v[90:93]
	v_mfma_f32_16x16x32_bf16 v[86:89], v[176:179], v[98:101], v[86:89]
	v_mfma_f32_16x16x32_bf16 v[82:85], v[176:179], v[106:109], v[82:85]
	v_mfma_f32_16x16x32_bf16 v[94:97], v[172:175], v[102:105], v[94:97]
	s_waitcnt lgkmcnt(0)
	v_mfma_f32_16x16x32_bf16 v[90:93], v[172:175], v[110:113], v[90:93]
	v_mfma_f32_16x16x32_bf16 v[86:89], v[180:183], v[102:105], v[86:89]
	v_mfma_f32_16x16x32_bf16 v[82:85], v[180:183], v[110:113], v[82:85]
	v_mfma_f32_16x16x32_bf16 v[78:81], v[184:187], v[98:101], v[78:81]
	v_mfma_f32_16x16x32_bf16 v[74:77], v[184:187], v[106:109], v[74:77]
	v_mfma_f32_16x16x32_bf16 v[70:73], v[192:195], v[98:101], v[70:73]
	v_mfma_f32_16x16x32_bf16 v[66:69], v[192:195], v[106:109], v[66:69]
	v_mfma_f32_16x16x32_bf16 v[168:171], v[188:191], v[102:105], v[78:81]
	v_mfma_f32_16x16x32_bf16 v[172:175], v[188:191], v[110:113], v[74:77]
	v_mfma_f32_16x16x32_bf16 v[176:179], v[196:199], v[102:105], v[70:73]
	v_mfma_f32_16x16x32_bf16 v[180:183], v[196:199], v[110:113], v[66:69]
	s_setprio 0
	s_barrier
	s_nop 1
	ds_read_b128 v[66:69], v140 offset:16384
	ds_read_b128 v[70:73], v140 offset:17408
	ds_read_b128 v[74:77], v140 offset:18432
	ds_read_b128 v[78:81], v140 offset:19456
	ds_read_b128 v[184:187], v140 offset:20480
	ds_read_b128 v[188:191], v140 offset:21504
	ds_read_b128 v[192:195], v140 offset:22528
	ds_read_b128 v[196:199], v140 offset:23552
	s_waitcnt vmcnt(4)
	s_barrier
; #define LDA(dst, b, h) _Pragma("unroll") for (int m = 0; m < 4; ++m) _Pragma("unroll") for (int k = 0; k < 2; ++k) \
;     dst[m][k] = *(const __attribute__((address_space(3))) bf16x8*)(aB + (((b) * 2 + (h)) * 16384 + m * 2048 + k * 1024))
; #define LDB(dst, b, h) _Pragma("unroll") for (int n = 0; n < 2; ++n) _Pragma("unroll") for (int k = 0; k < 2; ++k) \
;     dst[n][k] = *(const __attribute__((address_space(3))) bf16x8*)(bB + (((b) * 2 + (h)) * 16384 + n * 2048 + k * 1024))
; #define MMA(ai, bj, At, Bq) do { __builtin_amdgcn_s_setprio(1); \
;     _Pragma("unroll") for (int m = 0; m < 4; ++m) _Pragma("unroll") for (int n = 0; n < 2; ++n) _Pragma("unroll") for (int k = 0; k < 2; ++k) \
;       acc[ai][bj][m][n] = __builtin_amdgcn_mfma_f32_16x16x32_bf16(At[m][k], Bq[n][k], acc[ai][bj][m][n], 0, 0, 0); \
;     __builtin_amdgcn_s_setprio(0); } while (0)
; #define WAIT_V(n) asm volatile("s_waitcnt vmcnt(" #n ")" ::: "memory")
; #define WAIT_L(n) asm volatile("s_waitcnt lgkmcnt(" #n ")" ::: "memory")
; #define BAR __builtin_amdgcn_s_barrier()
; template <int MODE>
; DI void gemm_tile(const Params& p, const bf16_t* __restrict__ A, const bf16_t* __restrict__ Bt, int K, int brow, int bcol, int mp, int nt, bool vt, char* smem) {
;     ...
;     LDA(At, 0, 1); WAIT_V(4); BAR; WAIT_L(0); MMA(1, 0, At, B0); MMA(1, 1, At, B1); BAR; }
;   { LDB(B0, 1, 0); LDA(At, 1, 0); WAIT_V(2); BAR; WAIT_L(0); MMA(0, 0, At, B0); BAR;
	s_waitcnt lgkmcnt(0)
	s_setprio 1
	s_waitcnt lgkmcnt(7)
	v_mfma_f32_16x16x32_bf16 v[62:65], v[66:69], v[134:137], v[62:65]
	v_mfma_f32_16x16x32_bf16 v[58:61], v[66:69], v[156:159], v[58:61]
	s_waitcnt lgkmcnt(5)
	v_mfma_f32_16x16x32_bf16 v[54:57], v[74:77], v[134:137], v[54:57]
	v_mfma_f32_16x16x32_bf16 v[50:53], v[74:77], v[156:159], v[50:53]
	v_mfma_f32_16x16x32_bf16 v[62:65], v[70:73], v[148:151], v[62:65]
	v_mfma_f32_16x16x32_bf16 v[58:61], v[70:73], v[164:167], v[58:61]
	s_waitcnt lgkmcnt(4)
	v_mfma_f32_16x16x32_bf16 v[54:57], v[78:81], v[148:151], v[54:57]
	v_mfma_f32_16x16x32_bf16 v[50:53], v[78:81], v[164:167], v[50:53]
	s_waitcnt lgkmcnt(3)
	v_mfma_f32_16x16x32_bf16 v[46:49], v[184:187], v[134:137], v[46:49]
	v_mfma_f32_16x16x32_bf16 v[42:45], v[184:187], v[156:159], v[42:45]
	s_waitcnt lgkmcnt(1)
	v_mfma_f32_16x16x32_bf16 v[38:41], v[192:195], v[134:137], v[38:41]
	v_mfma_f32_16x16x32_bf16 v[34:37], v[192:195], v[156:159], v[34:37]
	v_mfma_f32_16x16x32_bf16 v[222:225], v[188:191], v[148:151], v[46:49]
	v_mfma_f32_16x16x32_bf16 v[226:229], v[188:191], v[164:167], v[42:45]
	s_waitcnt lgkmcnt(0)
	v_mfma_f32_16x16x32_bf16 v[134:137], v[196:199], v[148:151], v[38:41]
	v_mfma_f32_16x16x32_bf16 v[148:151], v[196:199], v[164:167], v[34:37]
	s_setprio 0
	s_setprio 1
	v_mfma_f32_16x16x32_bf16 v[30:33], v[66:69], v[98:101], v[30:33]
	v_mfma_f32_16x16x32_bf16 v[26:29], v[66:69], v[106:109], v[26:29]
	v_mfma_f32_16x16x32_bf16 v[22:25], v[74:77], v[98:101], v[22:25]
	v_mfma_f32_16x16x32_bf16 v[18:21], v[74:77], v[106:109], v[18:21]
	v_mfma_f32_16x16x32_bf16 v[30:33], v[70:73], v[102:105], v[30:33]
	v_mfma_f32_16x16x32_bf16 v[26:29], v[70:73], v[110:113], v[26:29]
	v_mfma_f32_16x16x32_bf16 v[22:25], v[78:81], v[102:105], v[22:25]
	v_mfma_f32_16x16x32_bf16 v[18:21], v[78:81], v[110:113], v[18:21]
	v_mfma_f32_16x16x32_bf16 v[14:17], v[184:187], v[98:101], v[14:17]
	v_mfma_f32_16x16x32_bf16 v[10:13], v[184:187], v[106:109], v[10:13]
	v_mfma_f32_16x16x32_bf16 v[6:9], v[192:195], v[98:101], v[6:9]
	v_mfma_f32_16x16x32_bf16 v[2:5], v[192:195], v[106:109], v[2:5]
	v_mfma_f32_16x16x32_bf16 v[156:159], v[188:191], v[102:105], v[14:17]
	v_mfma_f32_16x16x32_bf16 v[164:167], v[188:191], v[110:113], v[10:13]
	v_mfma_f32_16x16x32_bf16 v[184:187], v[196:199], v[102:105], v[6:9]
	v_mfma_f32_16x16x32_bf16 v[188:191], v[196:199], v[110:113], v[2:5]
	s_setprio 0
	s_barrier
	s_nop 1
	ds_read_b128 v[2:5], v142 offset:32768
	ds_read_b128 v[6:9], v142 offset:33792
	ds_read_b128 v[10:13], v142 offset:34816
	ds_read_b128 v[14:17], v142 offset:35840
	ds_read_b128 v[34:37], v140 offset:32768
	ds_read_b128 v[38:41], v140 offset:33792
	ds_read_b128 v[42:45], v140 offset:34816
	ds_read_b128 v[46:49], v140 offset:35840
	ds_read_b128 v[192:195], v140 offset:36864
	ds_read_b128 v[196:199], v140 offset:37888
	ds_read_b128 v[230:233], v140 offset:38912
	ds_read_b128 v[234:237], v140 offset:39936
	s_waitcnt vmcnt(2)
	s_barrier
	s_waitcnt lgkmcnt(0)
	s_setprio 1
	s_waitcnt lgkmcnt(7)
	v_mfma_f32_16x16x32_bf16 v[66:69], v[34:37], v[2:5], v[126:129]
	s_waitcnt lgkmcnt(6)
	v_mfma_f32_16x16x32_bf16 v[98:101], v[38:41], v[6:9], v[66:69]
	v_mfma_f32_16x16x32_bf16 v[66:69], v[34:37], v[10:13], v[122:125]
	v_mfma_f32_16x16x32_bf16 v[102:105], v[38:41], v[14:17], v[66:69]
	s_waitcnt lgkmcnt(5)
	v_mfma_f32_16x16x32_bf16 v[66:69], v[42:45], v[2:5], v[118:121]
	s_waitcnt lgkmcnt(4)
	v_mfma_f32_16x16x32_bf16 v[106:109], v[46:49], v[6:9], v[66:69]
	v_mfma_f32_16x16x32_bf16 v[66:69], v[42:45], v[10:13], v[114:117]
	v_mfma_f32_16x16x32_bf16 v[110:113], v[46:49], v[14:17], v[66:69]
	s_waitcnt lgkmcnt(3)
	v_mfma_f32_16x16x32_bf16 v[66:69], v[192:195], v[2:5], v[130:133]
	s_waitcnt lgkmcnt(2)
	v_mfma_f32_16x16x32_bf16 v[114:117], v[196:199], v[6:9], v[66:69]
	v_mfma_f32_16x16x32_bf16 v[66:69], v[192:195], v[10:13], v[160:163]
	v_mfma_f32_16x16x32_bf16 v[118:121], v[196:199], v[14:17], v[66:69]
	s_waitcnt lgkmcnt(1)
	v_mfma_f32_16x16x32_bf16 v[66:69], v[230:233], v[2:5], v[214:217]
	s_waitcnt lgkmcnt(0)
	v_mfma_f32_16x16x32_bf16 v[122:125], v[234:237], v[6:9], v[66:69]
	v_mfma_f32_16x16x32_bf16 v[66:69], v[230:233], v[10:13], v[218:221]
	v_mfma_f32_16x16x32_bf16 v[126:129], v[234:237], v[14:17], v[66:69]
	s_setprio 0
	s_barrier
; #define LDA(dst, b, h) _Pragma("unroll") for (int m = 0; m < 4; ++m) _Pragma("unroll") for (int k = 0; k < 2; ++k) \
;     dst[m][k] = *(const __attribute__((address_space(3))) bf16x8*)(aB + (((b) * 2 + (h)) * 16384 + m * 2048 + k * 1024))
; #define LDB(dst, b, h) _Pragma("unroll") for (int n = 0; n < 2; ++n) _Pragma("unroll") for (int k = 0; k < 2; ++k) \
;     dst[n][k] = *(const __attribute__((address_space(3))) bf16x8*)(bB + (((b) * 2 + (h)) * 16384 + n * 2048 + k * 1024))
; #define MMA(ai, bj, At, Bq) do { __builtin_amdgcn_s_setprio(1); \
;     _Pragma("unroll") for (int m = 0; m < 4; ++m) _Pragma("unroll") for (int n = 0; n < 2; ++n) _Pragma("unroll") for (int k = 0; k < 2; ++k) \
;       acc[ai][bj][m][n] = __builtin_amdgcn_mfma_f32_16x16x32_bf16(At[m][k], Bq[n][k], acc[ai][bj][m][n], 0, 0, 0); \
;     __builtin_amdgcn_s_setprio(0); } while (0)
; #define WAIT_V(n) asm volatile("s_waitcnt vmcnt(" #n ")" ::: "memory")
; #define WAIT_L(n) asm volatile("s_waitcnt lgkmcnt(" #n ")" ::: "memory")
; #define BAR __builtin_amdgcn_s_barrier()
; template <int MODE>
; DI void gemm_tile(const Params& p, const bf16_t* __restrict__ A, const bf16_t* __restrict__ Bt, int K, int brow, int bcol, int mp, int nt, bool vt, char* smem) {
;     ...
;     LDB(B1, 1, 1); WAIT_V(0); BAR; WAIT_L(0); MMA(0, 1, At, B1); BAR;
;     LDA(At, 1, 1); BAR; WAIT_L(0); MMA(1, 0, At, B0); MMA(1, 1, At, B1); BAR; }
;   if (wr == 0) BAR;
	ds_read_b128 v[130:133], v142 offset:49152
	ds_read_b128 v[160:163], v142 offset:50176
	ds_read_b128 v[214:217], v142 offset:51200
	ds_read_b128 v[218:221], v142 offset:52224
	s_waitcnt vmcnt(0)
	s_barrier
	s_waitcnt lgkmcnt(0)
	s_setprio 1
	s_waitcnt lgkmcnt(3)
	v_mfma_f32_16x16x32_bf16 v[66:69], v[34:37], v[130:133], v[94:97]
	s_waitcnt lgkmcnt(1)
	v_mfma_f32_16x16x32_bf16 v[34:37], v[34:37], v[214:217], v[90:93]
	s_waitcnt lgkmcnt(0)
	v_mfma_f32_16x16x32_bf16 v[70:73], v[38:41], v[218:221], v[34:37]
	v_mfma_f32_16x16x32_bf16 v[34:37], v[42:45], v[130:133], v[86:89]
	v_mfma_f32_16x16x32_bf16 v[74:77], v[46:49], v[160:163], v[34:37]
	v_mfma_f32_16x16x32_bf16 v[34:37], v[42:45], v[214:217], v[82:85]
	v_mfma_f32_16x16x32_bf16 v[78:81], v[46:49], v[218:221], v[34:37]
	v_mfma_f32_16x16x32_bf16 v[34:37], v[192:195], v[130:133], v[168:171]
	v_mfma_f32_16x16x32_bf16 v[82:85], v[196:199], v[160:163], v[34:37]
	v_mfma_f32_16x16x32_bf16 v[34:37], v[192:195], v[214:217], v[172:175]
	v_mfma_f32_16x16x32_bf16 v[86:89], v[196:199], v[218:221], v[34:37]
	v_mfma_f32_16x16x32_bf16 v[34:37], v[230:233], v[130:133], v[176:179]
	v_mfma_f32_16x16x32_bf16 v[90:93], v[234:237], v[160:163], v[34:37]
	v_mfma_f32_16x16x32_bf16 v[34:37], v[230:233], v[214:217], v[180:183]
	v_mfma_f32_16x16x32_bf16 v[66:69], v[38:41], v[160:163], v[66:69]
	v_mfma_f32_16x16x32_bf16 v[94:97], v[234:237], v[218:221], v[34:37]
	s_setprio 0
	s_barrier
	ds_read_b128 v[168:171], v140 offset:49152
	ds_read_b128 v[172:175], v140 offset:50176
	ds_read_b128 v[176:179], v140 offset:51200
	ds_read_b128 v[180:183], v140 offset:52224
	ds_read_b128 v[192:195], v140 offset:53248
	ds_read_b128 v[196:199], v140 offset:54272
	ds_read_b128 v[230:233], v140 offset:55296
	ds_read_b128 v[138:141], v140 offset:56320
	s_barrier
	s_waitcnt lgkmcnt(0)
	s_setprio 1
	s_waitcnt lgkmcnt(7)
	v_mfma_f32_16x16x32_bf16 v[34:37], v[168:171], v[2:5], v[62:65]
	s_waitcnt lgkmcnt(5)
	v_mfma_f32_16x16x32_bf16 v[42:45], v[176:179], v[2:5], v[54:57]
	v_mfma_f32_16x16x32_bf16 v[46:49], v[176:179], v[10:13], v[50:53]
	s_waitcnt lgkmcnt(3)
	v_mfma_f32_16x16x32_bf16 v[50:53], v[192:195], v[2:5], v[222:225]
	s_waitcnt lgkmcnt(1)
	v_mfma_f32_16x16x32_bf16 v[2:5], v[230:233], v[2:5], v[134:137]
	v_mfma_f32_16x16x32_bf16 v[38:41], v[168:171], v[10:13], v[58:61]
	v_mfma_f32_16x16x32_bf16 v[54:57], v[192:195], v[10:13], v[226:229]
	s_waitcnt lgkmcnt(0)
	v_mfma_f32_16x16x32_bf16 v[58:61], v[138:141], v[6:9], v[2:5]
	v_mfma_f32_16x16x32_bf16 v[2:5], v[230:233], v[10:13], v[148:151]
	v_mfma_f32_16x16x32_bf16 v[34:37], v[172:175], v[6:9], v[34:37]
	v_mfma_f32_16x16x32_bf16 v[38:41], v[172:175], v[14:17], v[38:41]
	v_mfma_f32_16x16x32_bf16 v[42:45], v[180:183], v[6:9], v[42:45]
	v_mfma_f32_16x16x32_bf16 v[46:49], v[180:183], v[14:17], v[46:49]
	v_mfma_f32_16x16x32_bf16 v[50:53], v[196:199], v[6:9], v[50:53]
	v_mfma_f32_16x16x32_bf16 v[54:57], v[196:199], v[14:17], v[54:57]
	v_mfma_f32_16x16x32_bf16 v[62:65], v[138:141], v[14:17], v[2:5]
	s_setprio 0
	s_setprio 1
	v_mfma_f32_16x16x32_bf16 v[2:5], v[168:171], v[130:133], v[30:33]
	v_mfma_f32_16x16x32_bf16 v[6:9], v[168:171], v[214:217], v[26:29]
	v_mfma_f32_16x16x32_bf16 v[10:13], v[176:179], v[130:133], v[22:25]
	v_mfma_f32_16x16x32_bf16 v[14:17], v[176:179], v[214:217], v[18:21]
	v_mfma_f32_16x16x32_bf16 v[18:21], v[192:195], v[130:133], v[156:159]
	v_mfma_f32_16x16x32_bf16 v[22:25], v[192:195], v[214:217], v[164:167]
	v_mfma_f32_16x16x32_bf16 v[26:29], v[230:233], v[130:133], v[184:187]
	v_mfma_f32_16x16x32_bf16 v[30:33], v[230:233], v[214:217], v[188:191]
	v_mfma_f32_16x16x32_bf16 v[2:5], v[172:175], v[160:163], v[2:5]
	v_mfma_f32_16x16x32_bf16 v[6:9], v[172:175], v[218:221], v[6:9]
	v_mfma_f32_16x16x32_bf16 v[10:13], v[180:183], v[160:163], v[10:13]
	v_mfma_f32_16x16x32_bf16 v[14:17], v[180:183], v[218:221], v[14:17]
	v_mfma_f32_16x16x32_bf16 v[18:21], v[196:199], v[160:163], v[18:21]
	v_mfma_f32_16x16x32_bf16 v[22:25], v[196:199], v[218:221], v[22:25]
	v_mfma_f32_16x16x32_bf16 v[26:29], v[138:141], v[160:163], v[26:29]
	v_mfma_f32_16x16x32_bf16 v[30:33], v[138:141], v[218:221], v[30:33]
	s_setprio 0
	s_movk_i32 s1, 0x100
	v_cmp_gt_u32_e32 vcc, s1, v144
	s_barrier
	s_and_saveexec_b64 s[6:7], vcc
	s_cbranch_execz .LBB0_529
	s_barrier

; #define STAGE(P, BASE, br, kt) do { const bf16_t* _gb = (BASE) + (long)(br) * K + (long)(kt) * 64; asm volatile("" : "+s"(_gb)); \
;     __builtin_amdgcn_global_load_lds((const unsigned*)(_gb + go0), (lds_u32*)((char*)(P) + tid * 16), 16, 0, 0); \
;     __builtin_amdgcn_global_load_lds((const unsigned*)(_gb + go1), (lds_u32*)((char*)(P) + tid * 16 + 8192), 16, 0, 0); } while (0)
; #define LDA(dst, b, h) _Pragma("unroll") for (int m = 0; m < 4; ++m) _Pragma("unroll") for (int k = 0; k < 2; ++k) \
;     dst[m][k] = *(const __attribute__((address_space(3))) bf16x8*)(aB + (((b) * 2 + (h)) * 16384 + m * 2048 + k * 1024))
; #define LDB(dst, b, h) _Pragma("unroll") for (int n = 0; n < 2; ++n) _Pragma("unroll") for (int k = 0; k < 2; ++k) \
;     dst[n][k] = *(const __attribute__((address_space(3))) bf16x8*)(bB + (((b) * 2 + (h)) * 16384 + n * 2048 + k * 1024))
; #define MMA(ai, bj, At, Bq) do { __builtin_amdgcn_s_setprio(1); \
;     _Pragma("unroll") for (int m = 0; m < 4; ++m) _Pragma("unroll") for (int n = 0; n < 2; ++n) _Pragma("unroll") for (int k = 0; k < 2; ++k) \
;       acc[ai][bj][m][n] = __builtin_amdgcn_mfma_f32_16x16x32_bf16(At[m][k], Bq[n][k], acc[ai][bj][m][n], 0, 0, 0); \
;     __builtin_amdgcn_s_setprio(0); } while (0)
; #define WAIT_L(n) asm volatile("s_waitcnt lgkmcnt(" #n ")" ::: "memory")
; #define BAR __builtin_amdgcn_s_barrier()
; #define SCHED __builtin_amdgcn_sched_barrier(0)
; template <int MODE>
; DI void gemm_tile(const Params& p, const bf16_t* __restrict__ A, const bf16_t* __restrict__ Bt, int K, int brow, int bcol, int mp, int nt, bool vt, char* smem) {
;     ...
;   const int wid = tid >> 6, lane = tid & 63, wr = wid >> 2, wc = wid & 3, fr = lane & 15, fq = lane >> 4;
;   const int laneoff = (fr * 64 + fq * 16) ^ ((fr >> 3) << 5);
;   const __attribute__((address_space(3))) char* aB = (const __attribute__((address_space(3))) char*)smem + wr * 8192 + laneoff;
;   const __attribute__((address_space(3))) char* bB = (const __attribute__((address_space(3))) char*)smem + 65536 + wc * 4096 + laneoff;
;     ...
;     LDB(B0, 0, 0); SCHED; LDA(At, 0, 0); STAGE(SA(1, 1), A, brow + 128, t + 1);
;     WAIT_L(8); BAR; WAIT_L(0); MMA(0, 0, At, B0); BAR; SCHED;
;     LDB(B1, 0, 1); STAGE(SB(0, 0), Bt, bcol, t + 2);
.LBB0_586:
	s_or_b64 exec, exec, s[14:15]
	s_add_u32 s1, s10, 0x100
	s_addc_u32 s14, s11, 0
	v_and_b32_e32 v142, 15, v0
	s_add_u32 s12, s22, s12
	v_bfe_u32 v131, v0, 6, 2
	v_and_b32_e32 v141, 48, v0
	v_and_b32_e32 v2, 32, v130
	v_lshlrev_b32_e32 v5, 6, v142
	s_addc_u32 s13, s21, s13
	s_waitcnt lgkmcnt(0)
	v_lshlrev_b32_e32 v3, 13, v6
	v_lshl_or_b32 v4, v131, 12, v205
	v_bitop3_b32 v5, v5, v2, v141 bitop3:0x36
	s_add_u32 s15, s12, 0x40000
	s_addc_u32 s21, s13, 0
	s_mov_b32 s22, -2
	s_mov_b64 s[12:13], 0
	v_add_u32_e32 v147, v4, v5
	v_add_u32_e32 v145, v3, v5
	s_nop 0
	ds_read_b128 v[164:167], v147
	ds_read_b128 v[168:171], v147 offset:1024
	ds_read_b128 v[172:175], v147 offset:2048
	ds_read_b128 v[176:179], v147 offset:3072
	s_add_u32 s23, s15, s12
	s_addc_u32 s25, s21, s13
	s_add_u32 s24, s23, 0x80
	v_add_u32_e32 v162, 0xc000, v140
	s_addc_u32 s25, s25, 0
	v_readfirstlane_b32 s23, v162
	v_add_u32_e32 v163, 0xe000, v140
	ds_read_b128 v[180:183], v145
	ds_read_b128 v[184:187], v145 offset:1024
	ds_read_b128 v[188:191], v145 offset:2048
	ds_read_b128 v[192:195], v145 offset:3072
	ds_read_b128 v[196:199], v145 offset:4096
	ds_read_b128 v[214:217], v145 offset:5120
	ds_read_b128 v[218:221], v145 offset:6144
	ds_read_b128 v[222:225], v145 offset:7168
	s_mov_b32 m0, s23
	v_lshl_add_u64 v[226:227], s[24:25], 0, v[136:137]
	v_readfirstlane_b32 s23, v163
	global_load_lds_dwordx4 v[226:227], off
	v_lshl_add_u64 v[226:227], s[24:25], 0, v[138:139]
	s_mov_b32 m0, s23
	s_nop 0
	global_load_lds_dwordx4 v[226:227], off
	s_waitcnt lgkmcnt(8)
	s_barrier
	s_waitcnt lgkmcnt(0)
	s_setprio 1
	s_waitcnt lgkmcnt(0)
	v_mfma_f32_16x16x32_bf16 v[126:129], v[180:183], v[164:167], 0
	v_mfma_f32_16x16x32_bf16 v[122:125], v[180:183], v[172:175], 0
	v_mfma_f32_16x16x32_bf16 v[118:121], v[188:191], v[164:167], 0
	v_mfma_f32_16x16x32_bf16 v[114:117], v[188:191], v[172:175], 0
	v_mfma_f32_16x16x32_bf16 v[110:113], v[196:199], v[164:167], 0
	v_mfma_f32_16x16x32_bf16 v[106:109], v[196:199], v[172:175], 0
	v_mfma_f32_16x16x32_bf16 v[102:105], v[218:221], v[164:167], 0
	v_mfma_f32_16x16x32_bf16 v[98:101], v[218:221], v[172:175], 0
	v_mfma_f32_16x16x32_bf16 v[126:129], v[184:187], v[168:171], v[126:129]
	v_mfma_f32_16x16x32_bf16 v[122:125], v[184:187], v[176:179], v[122:125]
	v_mfma_f32_16x16x32_bf16 v[118:121], v[192:195], v[168:171], v[118:121]
	v_mfma_f32_16x16x32_bf16 v[114:117], v[192:195], v[176:179], v[114:117]
	v_mfma_f32_16x16x32_bf16 v[110:113], v[214:217], v[168:171], v[110:113]
	v_mfma_f32_16x16x32_bf16 v[106:109], v[214:217], v[176:179], v[106:109]
	v_mfma_f32_16x16x32_bf16 v[102:105], v[222:225], v[168:171], v[102:105]
	v_mfma_f32_16x16x32_bf16 v[98:101], v[222:225], v[176:179], v[98:101]
	s_setprio 0
	s_barrier
	s_add_u32 s23, s2, s12
	s_addc_u32 s26, s3, s13
	s_add_u32 s24, s23, 0x100
	s_addc_u32 s25, s26, 0
	v_readfirstlane_b32 s27, v144
	s_nop 0
	ds_read_b128 v[226:229], v147 offset:16384
	ds_read_b128 v[230:233], v147 offset:17408
	ds_read_b128 v[234:237], v147 offset:18432
	ds_read_b128 v[238:241], v147 offset:19456
	s_mov_b32 m0, s27
	v_lshl_add_u64 v[242:243], s[24:25], 0, v[136:137]
	global_load_lds_dwordx4 v[242:243], off
	v_lshl_add_u64 v[242:243], s[24:25], 0, v[138:139]
	v_readfirstlane_b32 s24, v146
	s_mov_b32 m0, s24
	s_nop 0
	global_load_lds_dwordx4 v[242:243], off
	s_barrier
; #define STAGE(P, BASE, br, kt) do { const bf16_t* _gb = (BASE) + (long)(br) * K + (long)(kt) * 64; asm volatile("" : "+s"(_gb)); \
;     __builtin_amdgcn_global_load_lds((const unsigned*)(_gb + go0), (lds_u32*)((char*)(P) + tid * 16), 16, 0, 0); \
;     __builtin_amdgcn_global_load_lds((const unsigned*)(_gb + go1), (lds_u32*)((char*)(P) + tid * 16 + 8192), 16, 0, 0); } while (0)
; #define LDA(dst, b, h) _Pragma("unroll") for (int m = 0; m < 4; ++m) _Pragma("unroll") for (int k = 0; k < 2; ++k) \
;     dst[m][k] = *(const __attribute__((address_space(3))) bf16x8*)(aB + (((b) * 2 + (h)) * 16384 + m * 2048 + k * 1024))
; #define MMA(ai, bj, At, Bq) do { __builtin_amdgcn_s_setprio(1); \
;     _Pragma("unroll") for (int m = 0; m < 4; ++m) _Pragma("unroll") for (int n = 0; n < 2; ++n) _Pragma("unroll") for (int k = 0; k < 2; ++k) \
;       acc[ai][bj][m][n] = __builtin_amdgcn_mfma_f32_16x16x32_bf16(At[m][k], Bq[n][k], acc[ai][bj][m][n], 0, 0, 0); \
;     __builtin_amdgcn_s_setprio(0); } while (0)
; #define WAIT_V(n) asm volatile("s_waitcnt vmcnt(" #n ")" ::: "memory")
; #define WAIT_L(n) asm volatile("s_waitcnt lgkmcnt(" #n ")" ::: "memory")
; #define BAR __builtin_amdgcn_s_barrier()
; #define SCHED __builtin_amdgcn_sched_barrier(0)
; template <int MODE>
; DI void gemm_tile(const Params& p, const bf16_t* __restrict__ A, const bf16_t* __restrict__ Bt, int K, int brow, int bcol, int mp, int nt, bool vt, char* smem) {
;     ...
;     BAR; WAIT_L(0); MMA(0, 1, At, B1); BAR;
;     LDA(At, 0, 1); STAGE(SA(0, 0), A, brow, t + 2);
;     BAR; WAIT_L(0); MMA(1, 0, At, B0); BAR; SCHED;
;     STAGE(SB(0, 1), Bt, bcol + 128, t + 2);
;     WAIT_V(6); BAR; MMA(1, 1, At, B1); BAR;
	s_waitcnt lgkmcnt(0)
	s_setprio 1
	s_waitcnt lgkmcnt(0)
	v_mfma_f32_16x16x32_bf16 v[94:97], v[180:183], v[226:229], 0
	v_mfma_f32_16x16x32_bf16 v[90:93], v[180:183], v[234:237], 0
	v_mfma_f32_16x16x32_bf16 v[86:89], v[188:191], v[226:229], 0
	v_mfma_f32_16x16x32_bf16 v[82:85], v[188:191], v[234:237], 0
	v_mfma_f32_16x16x32_bf16 v[78:81], v[196:199], v[226:229], 0
	v_mfma_f32_16x16x32_bf16 v[74:77], v[196:199], v[234:237], 0
	v_mfma_f32_16x16x32_bf16 v[70:73], v[218:221], v[226:229], 0
	v_mfma_f32_16x16x32_bf16 v[66:69], v[218:221], v[234:237], 0
	v_mfma_f32_16x16x32_bf16 v[94:97], v[184:187], v[230:233], v[94:97]
	v_mfma_f32_16x16x32_bf16 v[90:93], v[184:187], v[238:241], v[90:93]
	v_mfma_f32_16x16x32_bf16 v[86:89], v[192:195], v[230:233], v[86:89]
	v_mfma_f32_16x16x32_bf16 v[82:85], v[192:195], v[238:241], v[82:85]
	v_mfma_f32_16x16x32_bf16 v[78:81], v[214:217], v[230:233], v[78:81]
	v_mfma_f32_16x16x32_bf16 v[74:77], v[214:217], v[238:241], v[74:77]
	v_mfma_f32_16x16x32_bf16 v[70:73], v[222:225], v[230:233], v[70:73]
	v_mfma_f32_16x16x32_bf16 v[66:69], v[222:225], v[238:241], v[66:69]
	s_setprio 0
	s_add_u32 s27, s4, s12
	s_addc_u32 s28, s5, s13
	s_add_u32 s24, s27, 0x100
	s_addc_u32 s25, s28, 0
	v_readfirstlane_b32 s29, v140
	s_barrier
	s_nop 0
	ds_read_b128 v[180:183], v145 offset:16384
	ds_read_b128 v[184:187], v145 offset:17408
	ds_read_b128 v[188:191], v145 offset:18432
	ds_read_b128 v[192:195], v145 offset:19456
	ds_read_b128 v[196:199], v145 offset:20480
	ds_read_b128 v[214:217], v145 offset:21504
	ds_read_b128 v[218:221], v145 offset:22528
	ds_read_b128 v[222:225], v145 offset:23552
	s_mov_b32 m0, s29
	v_lshl_add_u64 v[242:243], s[24:25], 0, v[136:137]
	global_load_lds_dwordx4 v[242:243], off
	v_lshl_add_u64 v[242:243], s[24:25], 0, v[138:139]
	v_readfirstlane_b32 s24, v143
	s_mov_b32 m0, s24
	s_nop 0
	global_load_lds_dwordx4 v[242:243], off
	s_barrier
	s_waitcnt lgkmcnt(0)
	s_setprio 1
	s_waitcnt lgkmcnt(0)
	v_mfma_f32_16x16x32_bf16 v[62:65], v[180:183], v[164:167], 0
	v_mfma_f32_16x16x32_bf16 v[58:61], v[180:183], v[172:175], 0
	v_mfma_f32_16x16x32_bf16 v[54:57], v[188:191], v[164:167], 0
	v_mfma_f32_16x16x32_bf16 v[50:53], v[188:191], v[172:175], 0
	v_mfma_f32_16x16x32_bf16 v[46:49], v[196:199], v[164:167], 0
	v_mfma_f32_16x16x32_bf16 v[42:45], v[196:199], v[172:175], 0
	v_mfma_f32_16x16x32_bf16 v[38:41], v[218:221], v[164:167], 0
	v_mfma_f32_16x16x32_bf16 v[34:37], v[218:221], v[172:175], 0
	v_mfma_f32_16x16x32_bf16 v[62:65], v[184:187], v[168:171], v[62:65]
	v_mfma_f32_16x16x32_bf16 v[58:61], v[184:187], v[176:179], v[58:61]
	v_mfma_f32_16x16x32_bf16 v[54:57], v[192:195], v[168:171], v[54:57]
	v_mfma_f32_16x16x32_bf16 v[50:53], v[192:195], v[176:179], v[50:53]
	v_mfma_f32_16x16x32_bf16 v[46:49], v[214:217], v[168:171], v[46:49]
	v_mfma_f32_16x16x32_bf16 v[42:45], v[214:217], v[176:179], v[42:45]
	v_mfma_f32_16x16x32_bf16 v[38:41], v[222:225], v[168:171], v[38:41]
	v_mfma_f32_16x16x32_bf16 v[34:37], v[222:225], v[176:179], v[34:37]
	s_setprio 0
	s_barrier
	s_add_u32 s29, s6, s12
	s_addc_u32 s30, s7, s13
	s_add_u32 s24, s29, 0x100
	s_addc_u32 s25, s30, 0
	v_readfirstlane_b32 s31, v148
	s_mov_b32 m0, s31
	v_lshl_add_u64 v[164:165], s[24:25], 0, v[136:137]
	global_load_lds_dwordx4 v[164:165], off
	v_lshl_add_u64 v[164:165], s[24:25], 0, v[138:139]
	v_readfirstlane_b32 s24, v149
	s_mov_b32 m0, s24
	s_nop 0
	global_load_lds_dwordx4 v[164:165], off
	s_waitcnt vmcnt(6)
	s_barrier
	s_setprio 1
	v_mfma_f32_16x16x32_bf16 v[30:33], v[180:183], v[226:229], 0
	v_mfma_f32_16x16x32_bf16 v[26:29], v[180:183], v[234:237], 0
	v_mfma_f32_16x16x32_bf16 v[22:25], v[188:191], v[226:229], 0
	v_mfma_f32_16x16x32_bf16 v[18:21], v[188:191], v[234:237], 0
	v_mfma_f32_16x16x32_bf16 v[14:17], v[196:199], v[226:229], 0
	v_mfma_f32_16x16x32_bf16 v[10:13], v[196:199], v[234:237], 0
	v_mfma_f32_16x16x32_bf16 v[6:9], v[218:221], v[226:229], 0
	v_mfma_f32_16x16x32_bf16 v[2:5], v[218:221], v[234:237], 0
	v_mfma_f32_16x16x32_bf16 v[30:33], v[184:187], v[230:233], v[30:33]
	v_mfma_f32_16x16x32_bf16 v[26:29], v[184:187], v[238:241], v[26:29]
	v_mfma_f32_16x16x32_bf16 v[22:25], v[192:195], v[230:233], v[22:25]
	v_mfma_f32_16x16x32_bf16 v[18:21], v[192:195], v[238:241], v[18:21]
	v_mfma_f32_16x16x32_bf16 v[14:17], v[214:217], v[230:233], v[14:17]
	v_mfma_f32_16x16x32_bf16 v[10:13], v[214:217], v[238:241], v[10:13]
	v_mfma_f32_16x16x32_bf16 v[6:9], v[222:225], v[230:233], v[6:9]
	v_mfma_f32_16x16x32_bf16 v[2:5], v[222:225], v[238:241], v[2:5]
	s_setprio 0
	s_barrier
	s_branch .Lgemm3_p5

; #define STAGE(P, BASE, br, kt) do { const bf16_t* _gb = (BASE) + (long)(br) * K + (long)(kt) * 64; asm volatile("" : "+s"(_gb)); \
;     __builtin_amdgcn_global_load_lds((const unsigned*)(_gb + go0), (lds_u32*)((char*)(P) + tid * 16), 16, 0, 0); \
;     __builtin_amdgcn_global_load_lds((const unsigned*)(_gb + go1), (lds_u32*)((char*)(P) + tid * 16 + 8192), 16, 0, 0); } while (0)
; #define LDA(dst, b, h) _Pragma("unroll") for (int m = 0; m < 4; ++m) _Pragma("unroll") for (int k = 0; k < 2; ++k) \
;     dst[m][k] = *(const __attribute__((address_space(3))) bf16x8*)(aB + (((b) * 2 + (h)) * 16384 + m * 2048 + k * 1024))
; #define LDB(dst, b, h) _Pragma("unroll") for (int n = 0; n < 2; ++n) _Pragma("unroll") for (int k = 0; k < 2; ++k) \
;     dst[n][k] = *(const __attribute__((address_space(3))) bf16x8*)(bB + (((b) * 2 + (h)) * 16384 + n * 2048 + k * 1024))
; #define MMA(ai, bj, At, Bq) do { __builtin_amdgcn_s_setprio(1); \
;     _Pragma("unroll") for (int m = 0; m < 4; ++m) _Pragma("unroll") for (int n = 0; n < 2; ++n) _Pragma("unroll") for (int k = 0; k < 2; ++k) \
;       acc[ai][bj][m][n] = __builtin_amdgcn_mfma_f32_16x16x32_bf16(At[m][k], Bq[n][k], acc[ai][bj][m][n], 0, 0, 0); \
;     __builtin_amdgcn_s_setprio(0); } while (0)
; #define WAIT_L(n) asm volatile("s_waitcnt lgkmcnt(" #n ")" ::: "memory")
; #define BAR __builtin_amdgcn_s_barrier()
; #define SCHED __builtin_amdgcn_sched_barrier(0)
; template <int MODE>
; DI void gemm_tile(const Params& p, const bf16_t* __restrict__ A, const bf16_t* __restrict__ Bt, int K, int brow, int bcol, int mp, int nt, bool vt, char* smem) {
;     ...
;     LDB(B0, 1, 0); SCHED; LDA(At, 1, 0); STAGE(SA(0, 1), A, brow + 128, t + 2);
;     WAIT_L(8); BAR; WAIT_L(0); MMA(0, 0, At, B0); BAR; SCHED;
;     LDB(B1, 1, 1); STAGE(SB(1, 0), Bt, bcol, t + 3);
;     BAR; WAIT_L(0); MMA(0, 1, At, B1); BAR;
;     LDA(At, 1, 1); STAGE(SA(1, 0), A, brow, t + 3);
;     BAR; WAIT_L(0); MMA(1, 0, At, B0); BAR; SCHED;
.Lgemm3_p5:
	s_nop 0
	ds_read_b128 v[164:167], v147 offset:32768
	ds_read_b128 v[168:171], v147 offset:33792
	ds_read_b128 v[172:175], v147 offset:34816
	ds_read_b128 v[176:179], v147 offset:35840
	s_add_u32 s24, s1, s12
	s_addc_u32 s25, s14, s13
	v_readfirstlane_b32 s31, v150
	ds_read_b128 v[180:183], v145 offset:32768
	ds_read_b128 v[184:187], v145 offset:33792
	ds_read_b128 v[188:191], v145 offset:34816
	ds_read_b128 v[192:195], v145 offset:35840
	ds_read_b128 v[196:199], v145 offset:36864
	ds_read_b128 v[214:217], v145 offset:37888
	ds_read_b128 v[218:221], v145 offset:38912
	ds_read_b128 v[222:225], v145 offset:39936
	s_mov_b32 m0, s31
	v_lshl_add_u64 v[226:227], s[24:25], 0, v[136:137]
	global_load_lds_dwordx4 v[226:227], off
	v_lshl_add_u64 v[226:227], s[24:25], 0, v[138:139]
	v_readfirstlane_b32 s24, v151
	s_mov_b32 m0, s24
	s_nop 0
	global_load_lds_dwordx4 v[226:227], off
	s_waitcnt lgkmcnt(8)
	s_barrier
	s_waitcnt lgkmcnt(0)
	s_setprio 1
	s_waitcnt lgkmcnt(0)
	v_mfma_f32_16x16x32_bf16 v[126:129], v[180:183], v[164:167], v[126:129]
	v_mfma_f32_16x16x32_bf16 v[122:125], v[180:183], v[172:175], v[122:125]
	v_mfma_f32_16x16x32_bf16 v[118:121], v[188:191], v[164:167], v[118:121]
	v_mfma_f32_16x16x32_bf16 v[114:117], v[188:191], v[172:175], v[114:117]
	v_mfma_f32_16x16x32_bf16 v[110:113], v[196:199], v[164:167], v[110:113]
	v_mfma_f32_16x16x32_bf16 v[106:109], v[196:199], v[172:175], v[106:109]
	v_mfma_f32_16x16x32_bf16 v[102:105], v[218:221], v[164:167], v[102:105]
	v_mfma_f32_16x16x32_bf16 v[98:101], v[218:221], v[172:175], v[98:101]
	v_mfma_f32_16x16x32_bf16 v[126:129], v[184:187], v[168:171], v[126:129]
	v_mfma_f32_16x16x32_bf16 v[122:125], v[184:187], v[176:179], v[122:125]
	v_mfma_f32_16x16x32_bf16 v[118:121], v[192:195], v[168:171], v[118:121]
	v_mfma_f32_16x16x32_bf16 v[114:117], v[192:195], v[176:179], v[114:117]
	v_mfma_f32_16x16x32_bf16 v[110:113], v[214:217], v[168:171], v[110:113]
	v_mfma_f32_16x16x32_bf16 v[106:109], v[214:217], v[176:179], v[106:109]
	v_mfma_f32_16x16x32_bf16 v[102:105], v[222:225], v[168:171], v[102:105]
	v_mfma_f32_16x16x32_bf16 v[98:101], v[222:225], v[176:179], v[98:101]
	s_setprio 0
	s_barrier
	s_add_u32 s24, s23, 0x180
	s_addc_u32 s25, s26, 0
	v_readfirstlane_b32 s23, v156
	s_nop 0
	ds_read_b128 v[226:229], v147 offset:49152
	ds_read_b128 v[230:233], v147 offset:50176
	ds_read_b128 v[234:237], v147 offset:51200
	ds_read_b128 v[238:241], v147 offset:52224
	s_mov_b32 m0, s23
	v_lshl_add_u64 v[242:243], s[24:25], 0, v[136:137]
	v_readfirstlane_b32 s23, v157
	global_load_lds_dwordx4 v[242:243], off
	v_lshl_add_u64 v[242:243], s[24:25], 0, v[138:139]
	s_mov_b32 m0, s23
	s_nop 0
	global_load_lds_dwordx4 v[242:243], off
	s_barrier
	s_waitcnt lgkmcnt(0)
	s_setprio 1
	s_waitcnt lgkmcnt(0)
	v_mfma_f32_16x16x32_bf16 v[94:97], v[180:183], v[226:229], v[94:97]
	v_mfma_f32_16x16x32_bf16 v[90:93], v[180:183], v[234:237], v[90:93]
	v_mfma_f32_16x16x32_bf16 v[86:89], v[188:191], v[226:229], v[86:89]
	v_mfma_f32_16x16x32_bf16 v[82:85], v[188:191], v[234:237], v[82:85]
	v_mfma_f32_16x16x32_bf16 v[78:81], v[196:199], v[226:229], v[78:81]
	v_mfma_f32_16x16x32_bf16 v[74:77], v[196:199], v[234:237], v[74:77]
	v_mfma_f32_16x16x32_bf16 v[70:73], v[218:221], v[226:229], v[70:73]
	v_mfma_f32_16x16x32_bf16 v[66:69], v[218:221], v[234:237], v[66:69]
	v_mfma_f32_16x16x32_bf16 v[94:97], v[184:187], v[230:233], v[94:97]
	v_mfma_f32_16x16x32_bf16 v[90:93], v[184:187], v[238:241], v[90:93]
	v_mfma_f32_16x16x32_bf16 v[86:89], v[192:195], v[230:233], v[86:89]
	v_mfma_f32_16x16x32_bf16 v[82:85], v[192:195], v[238:241], v[82:85]
	v_mfma_f32_16x16x32_bf16 v[78:81], v[214:217], v[230:233], v[78:81]
	v_mfma_f32_16x16x32_bf16 v[74:77], v[214:217], v[238:241], v[74:77]
	v_mfma_f32_16x16x32_bf16 v[70:73], v[222:225], v[230:233], v[70:73]
	v_mfma_f32_16x16x32_bf16 v[66:69], v[222:225], v[238:241], v[66:69]
	s_setprio 0
	s_add_u32 s24, s27, 0x180
	s_addc_u32 s25, s28, 0
	v_readfirstlane_b32 s23, v158
	s_barrier
	s_nop 0
	ds_read_b128 v[180:183], v145 offset:49152
	ds_read_b128 v[184:187], v145 offset:50176
	ds_read_b128 v[188:191], v145 offset:51200
	ds_read_b128 v[192:195], v145 offset:52224
	ds_read_b128 v[196:199], v145 offset:53248
	ds_read_b128 v[214:217], v145 offset:54272
	ds_read_b128 v[218:221], v145 offset:55296
	ds_read_b128 v[222:225], v145 offset:56320
	s_mov_b32 m0, s23
	v_lshl_add_u64 v[242:243], s[24:25], 0, v[136:137]
	v_readfirstlane_b32 s23, v159
	global_load_lds_dwordx4 v[242:243], off
	v_lshl_add_u64 v[242:243], s[24:25], 0, v[138:139]
	s_mov_b32 m0, s23
	s_nop 0
	global_load_lds_dwordx4 v[242:243], off
	s_barrier
	s_waitcnt lgkmcnt(0)
	s_setprio 1
	s_waitcnt lgkmcnt(0)
	v_mfma_f32_16x16x32_bf16 v[62:65], v[180:183], v[164:167], v[62:65]
	v_mfma_f32_16x16x32_bf16 v[58:61], v[180:183], v[172:175], v[58:61]
	v_mfma_f32_16x16x32_bf16 v[54:57], v[188:191], v[164:167], v[54:57]
	v_mfma_f32_16x16x32_bf16 v[50:53], v[188:191], v[172:175], v[50:53]
	v_mfma_f32_16x16x32_bf16 v[46:49], v[196:199], v[164:167], v[46:49]
	v_mfma_f32_16x16x32_bf16 v[42:45], v[196:199], v[172:175], v[42:45]
	v_mfma_f32_16x16x32_bf16 v[38:41], v[218:221], v[164:167], v[38:41]
	v_mfma_f32_16x16x32_bf16 v[34:37], v[218:221], v[172:175], v[34:37]
	v_mfma_f32_16x16x32_bf16 v[62:65], v[184:187], v[168:171], v[62:65]
	v_mfma_f32_16x16x32_bf16 v[58:61], v[184:187], v[176:179], v[58:61]
	v_mfma_f32_16x16x32_bf16 v[54:57], v[192:195], v[168:171], v[54:57]
	v_mfma_f32_16x16x32_bf16 v[50:53], v[192:195], v[176:179], v[50:53]
	v_mfma_f32_16x16x32_bf16 v[46:49], v[214:217], v[168:171], v[46:49]
	v_mfma_f32_16x16x32_bf16 v[42:45], v[214:217], v[176:179], v[42:45]
	v_mfma_f32_16x16x32_bf16 v[38:41], v[222:225], v[168:171], v[38:41]
	v_mfma_f32_16x16x32_bf16 v[34:37], v[222:225], v[176:179], v[34:37]
	s_setprio 0
	s_barrier
; #define STAGE(P, BASE, br, kt) do { const bf16_t* _gb = (BASE) + (long)(br) * K + (long)(kt) * 64; asm volatile("" : "+s"(_gb)); \
;     __builtin_amdgcn_global_load_lds((const unsigned*)(_gb + go0), (lds_u32*)((char*)(P) + tid * 16), 16, 0, 0); \
;     __builtin_amdgcn_global_load_lds((const unsigned*)(_gb + go1), (lds_u32*)((char*)(P) + tid * 16 + 8192), 16, 0, 0); } while (0)
; #define LDA(dst, b, h) _Pragma("unroll") for (int m = 0; m < 4; ++m) _Pragma("unroll") for (int k = 0; k < 2; ++k) \
;     dst[m][k] = *(const __attribute__((address_space(3))) bf16x8*)(aB + (((b) * 2 + (h)) * 16384 + m * 2048 + k * 1024))
; #define LDB(dst, b, h) _Pragma("unroll") for (int n = 0; n < 2; ++n) _Pragma("unroll") for (int k = 0; k < 2; ++k) \
;     dst[n][k] = *(const __attribute__((address_space(3))) bf16x8*)(bB + (((b) * 2 + (h)) * 16384 + n * 2048 + k * 1024))
; #define MMA(ai, bj, At, Bq) do { __builtin_amdgcn_s_setprio(1); \
;     _Pragma("unroll") for (int m = 0; m < 4; ++m) _Pragma("unroll") for (int n = 0; n < 2; ++n) _Pragma("unroll") for (int k = 0; k < 2; ++k) \
;       acc[ai][bj][m][n] = __builtin_amdgcn_mfma_f32_16x16x32_bf16(At[m][k], Bq[n][k], acc[ai][bj][m][n], 0, 0, 0); \
;     __builtin_amdgcn_s_setprio(0); } while (0)
; #define WAIT_V(n) asm volatile("s_waitcnt vmcnt(" #n ")" ::: "memory")
; #define WAIT_L(n) asm volatile("s_waitcnt lgkmcnt(" #n ")" ::: "memory")
; #define BAR __builtin_amdgcn_s_barrier()
; template <int MODE>
; DI void gemm_tile(const Params& p, const bf16_t* __restrict__ A, const bf16_t* __restrict__ Bt, int K, int brow, int bcol, int mp, int nt, bool vt, char* smem) {
;     ...
;     STAGE(SB(1, 1), Bt, bcol + 128, t + 3);
;     WAIT_V(6); BAR; MMA(1, 1, At, B1); BAR;
;   }
;   { LDB(B0, 0, 0); LDA(At, 0, 0); STAGE(SA(1, 1), A, brow + 128, ntk - 1);
;     BAR; WAIT_L(0); MMA(0, 0, At, B0); BAR;
;     LDB(B1, 0, 1); BAR; WAIT_L(0); MMA(0, 1, At, B1); BAR;
;     LDA(At, 0, 1); WAIT_V(4); BAR; WAIT_L(0); MMA(1, 0, At, B0); MMA(1, 1, At, B1); BAR; }
	s_add_u32 s24, s29, 0x180
	s_addc_u32 s25, s30, 0
	v_readfirstlane_b32 s23, v160
	s_mov_b32 m0, s23
	v_lshl_add_u64 v[164:165], s[24:25], 0, v[136:137]
	v_readfirstlane_b32 s23, v161
	global_load_lds_dwordx4 v[164:165], off
	v_lshl_add_u64 v[164:165], s[24:25], 0, v[138:139]
	s_mov_b32 m0, s23
	s_nop 0
	global_load_lds_dwordx4 v[164:165], off
	s_waitcnt vmcnt(6)
	s_barrier
	s_setprio 1
	v_mfma_f32_16x16x32_bf16 v[30:33], v[180:183], v[226:229], v[30:33]
	v_mfma_f32_16x16x32_bf16 v[26:29], v[180:183], v[234:237], v[26:29]
	v_mfma_f32_16x16x32_bf16 v[22:25], v[188:191], v[226:229], v[22:25]
	v_mfma_f32_16x16x32_bf16 v[18:21], v[188:191], v[234:237], v[18:21]
	v_mfma_f32_16x16x32_bf16 v[14:17], v[196:199], v[226:229], v[14:17]
	v_mfma_f32_16x16x32_bf16 v[10:13], v[196:199], v[234:237], v[10:13]
	v_mfma_f32_16x16x32_bf16 v[6:9], v[218:221], v[226:229], v[6:9]
	v_mfma_f32_16x16x32_bf16 v[2:5], v[218:221], v[234:237], v[2:5]
	v_mfma_f32_16x16x32_bf16 v[30:33], v[184:187], v[230:233], v[30:33]
	v_mfma_f32_16x16x32_bf16 v[26:29], v[184:187], v[238:241], v[26:29]
	v_mfma_f32_16x16x32_bf16 v[22:25], v[192:195], v[230:233], v[22:25]
	v_mfma_f32_16x16x32_bf16 v[18:21], v[192:195], v[238:241], v[18:21]
	v_mfma_f32_16x16x32_bf16 v[14:17], v[214:217], v[230:233], v[14:17]
	v_mfma_f32_16x16x32_bf16 v[10:13], v[214:217], v[238:241], v[10:13]
	v_mfma_f32_16x16x32_bf16 v[6:9], v[222:225], v[230:233], v[6:9]
	v_mfma_f32_16x16x32_bf16 v[2:5], v[222:225], v[238:241], v[2:5]
	s_setprio 0
	s_add_i32 s22, s22, 2
	s_add_u32 s12, s12, 0x100
	s_addc_u32 s13, s13, 0
	s_cmp_lt_u32 s22, 12
	s_barrier
	s_cbranch_scc1 .LBB0_587
	s_add_u32 s2, s10, 0x780
	s_addc_u32 s3, s11, 0
	v_readfirstlane_b32 s1, v162
	s_nop 0
	ds_read_b128 v[136:139], v147
	ds_read_b128 v[148:151], v147 offset:1024
	ds_read_b128 v[156:159], v147 offset:2048
	ds_read_b128 v[164:167], v147 offset:3072
	ds_read_b128 v[168:171], v145
	ds_read_b128 v[172:175], v145 offset:1024
	ds_read_b128 v[176:179], v145 offset:2048
	ds_read_b128 v[180:183], v145 offset:3072
	ds_read_b128 v[184:187], v145 offset:4096
	ds_read_b128 v[188:191], v145 offset:5120
	ds_read_b128 v[192:195], v145 offset:6144
	ds_read_b128 v[196:199], v145 offset:7168
	s_mov_b32 m0, s1
	v_lshl_add_u64 v[134:135], v[134:135], 1, s[2:3]
	v_readfirstlane_b32 s1, v163
	global_load_lds_dwordx4 v[134:135], off
	v_lshl_add_u64 v[132:133], v[132:133], 1, s[2:3]
	s_mov_b32 m0, s1
	s_nop 0
	global_load_lds_dwordx4 v[132:133], off
	s_barrier
	s_waitcnt lgkmcnt(0)
	s_setprio 1
	s_waitcnt lgkmcnt(0)
	v_mfma_f32_16x16x32_bf16 v[126:129], v[168:171], v[136:139], v[126:129]
	v_mfma_f32_16x16x32_bf16 v[122:125], v[168:171], v[156:159], v[122:125]
	v_mfma_f32_16x16x32_bf16 v[118:121], v[176:179], v[136:139], v[118:121]
	v_mfma_f32_16x16x32_bf16 v[114:117], v[176:179], v[156:159], v[114:117]
	v_mfma_f32_16x16x32_bf16 v[126:129], v[172:175], v[148:151], v[126:129]
	v_mfma_f32_16x16x32_bf16 v[122:125], v[172:175], v[164:167], v[122:125]
	v_mfma_f32_16x16x32_bf16 v[118:121], v[180:183], v[148:151], v[118:121]
	v_mfma_f32_16x16x32_bf16 v[114:117], v[180:183], v[164:167], v[114:117]
	v_mfma_f32_16x16x32_bf16 v[110:113], v[184:187], v[136:139], v[110:113]
	v_mfma_f32_16x16x32_bf16 v[106:109], v[184:187], v[156:159], v[106:109]
	v_mfma_f32_16x16x32_bf16 v[102:105], v[192:195], v[136:139], v[102:105]
	v_mfma_f32_16x16x32_bf16 v[98:101], v[192:195], v[156:159], v[98:101]
	v_mfma_f32_16x16x32_bf16 v[132:135], v[188:191], v[148:151], v[110:113]
	v_mfma_f32_16x16x32_bf16 v[160:163], v[188:191], v[164:167], v[106:109]
	v_mfma_f32_16x16x32_bf16 v[214:217], v[196:199], v[148:151], v[102:105]
	v_mfma_f32_16x16x32_bf16 v[218:221], v[196:199], v[164:167], v[98:101]
	s_setprio 0
	s_barrier
	s_nop 0
	s_nop 0
	ds_read_b128 v[98:101], v147 offset:16384
	ds_read_b128 v[102:105], v147 offset:17408
	ds_read_b128 v[106:109], v147 offset:18432
	ds_read_b128 v[110:113], v147 offset:19456
	s_barrier
	s_waitcnt lgkmcnt(0)
	s_setprio 1
	s_waitcnt lgkmcnt(3)
	v_mfma_f32_16x16x32_bf16 v[94:97], v[168:171], v[98:101], v[94:97]
	s_waitcnt lgkmcnt(1)
	v_mfma_f32_16x16x32_bf16 v[90:93], v[168:171], v[106:109], v[90:93]
	v_mfma_f32_16x16x32_bf16 v[86:89], v[176:179], v[98:101], v[86:89]
	v_mfma_f32_16x16x32_bf16 v[82:85], v[176:179], v[106:109], v[82:85]
	v_mfma_f32_16x16x32_bf16 v[94:97], v[172:175], v[102:105], v[94:97]
	s_waitcnt lgkmcnt(0)
	v_mfma_f32_16x16x32_bf16 v[90:93], v[172:175], v[110:113], v[90:93]
	v_mfma_f32_16x16x32_bf16 v[86:89], v[180:183], v[102:105], v[86:89]
	v_mfma_f32_16x16x32_bf16 v[82:85], v[180:183], v[110:113], v[82:85]
	v_mfma_f32_16x16x32_bf16 v[78:81], v[184:187], v[98:101], v[78:81]
	v_mfma_f32_16x16x32_bf16 v[74:77], v[184:187], v[106:109], v[74:77]
	v_mfma_f32_16x16x32_bf16 v[70:73], v[192:195], v[98:101], v[70:73]
	v_mfma_f32_16x16x32_bf16 v[66:69], v[192:195], v[106:109], v[66:69]
	v_mfma_f32_16x16x32_bf16 v[168:171], v[188:191], v[102:105], v[78:81]
	v_mfma_f32_16x16x32_bf16 v[172:175], v[188:191], v[110:113], v[74:77]
	v_mfma_f32_16x16x32_bf16 v[176:179], v[196:199], v[102:105], v[70:73]
	v_mfma_f32_16x16x32_bf16 v[180:183], v[196:199], v[110:113], v[66:69]
	s_setprio 0
	s_barrier
	s_nop 1
	ds_read_b128 v[66:69], v145 offset:16384
	ds_read_b128 v[70:73], v145 offset:17408
	ds_read_b128 v[74:77], v145 offset:18432
	ds_read_b128 v[78:81], v145 offset:19456
	ds_read_b128 v[184:187], v145 offset:20480
	ds_read_b128 v[188:191], v145 offset:21504
	ds_read_b128 v[192:195], v145 offset:22528
	ds_read_b128 v[196:199], v145 offset:23552
	s_waitcnt vmcnt(4)
	s_barrier
; #define LDA(dst, b, h) _Pragma("unroll") for (int m = 0; m < 4; ++m) _Pragma("unroll") for (int k = 0; k < 2; ++k) \
;     dst[m][k] = *(const __attribute__((address_space(3))) bf16x8*)(aB + (((b) * 2 + (h)) * 16384 + m * 2048 + k * 1024))
; #define LDB(dst, b, h) _Pragma("unroll") for (int n = 0; n < 2; ++n) _Pragma("unroll") for (int k = 0; k < 2; ++k) \
;     dst[n][k] = *(const __attribute__((address_space(3))) bf16x8*)(bB + (((b) * 2 + (h)) * 16384 + n * 2048 + k * 1024))
; #define MMA(ai, bj, At, Bq) do { __builtin_amdgcn_s_setprio(1); \
;     _Pragma("unroll") for (int m = 0; m < 4; ++m) _Pragma("unroll") for (int n = 0; n < 2; ++n) _Pragma("unroll") for (int k = 0; k < 2; ++k) \
;       acc[ai][bj][m][n] = __builtin_amdgcn_mfma_f32_16x16x32_bf16(At[m][k], Bq[n][k], acc[ai][bj][m][n], 0, 0, 0); \
;     __builtin_amdgcn_s_setprio(0); } while (0)
; #define WAIT_V(n) asm volatile("s_waitcnt vmcnt(" #n ")" ::: "memory")
; #define WAIT_L(n) asm volatile("s_waitcnt lgkmcnt(" #n ")" ::: "memory")
; #define BAR __builtin_amdgcn_s_barrier()
; template <int MODE>
; DI void gemm_tile(const Params& p, const bf16_t* __restrict__ A, const bf16_t* __restrict__ Bt, int K, int brow, int bcol, int mp, int nt, bool vt, char* smem) {
;     ...
;     LDA(At, 0, 1); WAIT_V(4); BAR; WAIT_L(0); MMA(1, 0, At, B0); MMA(1, 1, At, B1); BAR; }
;   { LDB(B0, 1, 0); LDA(At, 1, 0); WAIT_V(2); BAR; WAIT_L(0); MMA(0, 0, At, B0); BAR;
	s_waitcnt lgkmcnt(0)
	s_setprio 1
	s_waitcnt lgkmcnt(7)
	v_mfma_f32_16x16x32_bf16 v[62:65], v[66:69], v[136:139], v[62:65]
	v_mfma_f32_16x16x32_bf16 v[58:61], v[66:69], v[156:159], v[58:61]
	s_waitcnt lgkmcnt(5)
	v_mfma_f32_16x16x32_bf16 v[54:57], v[74:77], v[136:139], v[54:57]
	v_mfma_f32_16x16x32_bf16 v[50:53], v[74:77], v[156:159], v[50:53]
	v_mfma_f32_16x16x32_bf16 v[62:65], v[70:73], v[148:151], v[62:65]
	v_mfma_f32_16x16x32_bf16 v[58:61], v[70:73], v[164:167], v[58:61]
	s_waitcnt lgkmcnt(4)
	v_mfma_f32_16x16x32_bf16 v[54:57], v[78:81], v[148:151], v[54:57]
	v_mfma_f32_16x16x32_bf16 v[50:53], v[78:81], v[164:167], v[50:53]
	s_waitcnt lgkmcnt(3)
	v_mfma_f32_16x16x32_bf16 v[46:49], v[184:187], v[136:139], v[46:49]
	v_mfma_f32_16x16x32_bf16 v[42:45], v[184:187], v[156:159], v[42:45]
	s_waitcnt lgkmcnt(1)
	v_mfma_f32_16x16x32_bf16 v[38:41], v[192:195], v[136:139], v[38:41]
	v_mfma_f32_16x16x32_bf16 v[34:37], v[192:195], v[156:159], v[34:37]
	v_mfma_f32_16x16x32_bf16 v[222:225], v[188:191], v[148:151], v[46:49]
	v_mfma_f32_16x16x32_bf16 v[226:229], v[188:191], v[164:167], v[42:45]
	s_waitcnt lgkmcnt(0)
	v_mfma_f32_16x16x32_bf16 v[136:139], v[196:199], v[148:151], v[38:41]
	v_mfma_f32_16x16x32_bf16 v[148:151], v[196:199], v[164:167], v[34:37]
	s_setprio 0
	s_setprio 1
	v_mfma_f32_16x16x32_bf16 v[30:33], v[66:69], v[98:101], v[30:33]
	v_mfma_f32_16x16x32_bf16 v[26:29], v[66:69], v[106:109], v[26:29]
	v_mfma_f32_16x16x32_bf16 v[22:25], v[74:77], v[98:101], v[22:25]
	v_mfma_f32_16x16x32_bf16 v[18:21], v[74:77], v[106:109], v[18:21]
	v_mfma_f32_16x16x32_bf16 v[30:33], v[70:73], v[102:105], v[30:33]
	v_mfma_f32_16x16x32_bf16 v[26:29], v[70:73], v[110:113], v[26:29]
	v_mfma_f32_16x16x32_bf16 v[22:25], v[78:81], v[102:105], v[22:25]
	v_mfma_f32_16x16x32_bf16 v[18:21], v[78:81], v[110:113], v[18:21]
	v_mfma_f32_16x16x32_bf16 v[14:17], v[184:187], v[98:101], v[14:17]
	v_mfma_f32_16x16x32_bf16 v[10:13], v[184:187], v[106:109], v[10:13]
	v_mfma_f32_16x16x32_bf16 v[6:9], v[192:195], v[98:101], v[6:9]
	v_mfma_f32_16x16x32_bf16 v[2:5], v[192:195], v[106:109], v[2:5]
	v_mfma_f32_16x16x32_bf16 v[156:159], v[188:191], v[102:105], v[14:17]
	v_mfma_f32_16x16x32_bf16 v[164:167], v[188:191], v[110:113], v[10:13]
	v_mfma_f32_16x16x32_bf16 v[184:187], v[196:199], v[102:105], v[6:9]
	v_mfma_f32_16x16x32_bf16 v[188:191], v[196:199], v[110:113], v[2:5]
	s_setprio 0
	s_barrier
	s_nop 1
	ds_read_b128 v[2:5], v147 offset:32768
	ds_read_b128 v[6:9], v147 offset:33792
	ds_read_b128 v[10:13], v147 offset:34816
	ds_read_b128 v[14:17], v147 offset:35840
	ds_read_b128 v[34:37], v145 offset:32768
	ds_read_b128 v[38:41], v145 offset:33792
	ds_read_b128 v[42:45], v145 offset:34816
	ds_read_b128 v[46:49], v145 offset:35840
	ds_read_b128 v[192:195], v145 offset:36864
	ds_read_b128 v[196:199], v145 offset:37888
	ds_read_b128 v[230:233], v145 offset:38912
	ds_read_b128 v[234:237], v145 offset:39936
	s_waitcnt vmcnt(2)
	s_barrier
	s_waitcnt lgkmcnt(0)
	s_setprio 1
	s_waitcnt lgkmcnt(7)
	v_mfma_f32_16x16x32_bf16 v[66:69], v[34:37], v[2:5], v[126:129]
	s_waitcnt lgkmcnt(6)
	v_mfma_f32_16x16x32_bf16 v[98:101], v[38:41], v[6:9], v[66:69]
	v_mfma_f32_16x16x32_bf16 v[66:69], v[34:37], v[10:13], v[122:125]
	v_mfma_f32_16x16x32_bf16 v[102:105], v[38:41], v[14:17], v[66:69]
	s_waitcnt lgkmcnt(5)
	v_mfma_f32_16x16x32_bf16 v[66:69], v[42:45], v[2:5], v[118:121]
	s_waitcnt lgkmcnt(4)
	v_mfma_f32_16x16x32_bf16 v[106:109], v[46:49], v[6:9], v[66:69]
	v_mfma_f32_16x16x32_bf16 v[66:69], v[42:45], v[10:13], v[114:117]
	v_mfma_f32_16x16x32_bf16 v[110:113], v[46:49], v[14:17], v[66:69]
	s_waitcnt lgkmcnt(3)
	v_mfma_f32_16x16x32_bf16 v[66:69], v[192:195], v[2:5], v[132:135]
	s_waitcnt lgkmcnt(2)
	v_mfma_f32_16x16x32_bf16 v[114:117], v[196:199], v[6:9], v[66:69]
	v_mfma_f32_16x16x32_bf16 v[66:69], v[192:195], v[10:13], v[160:163]
	v_mfma_f32_16x16x32_bf16 v[118:121], v[196:199], v[14:17], v[66:69]
	s_waitcnt lgkmcnt(1)
	v_mfma_f32_16x16x32_bf16 v[66:69], v[230:233], v[2:5], v[214:217]
	s_waitcnt lgkmcnt(0)
	v_mfma_f32_16x16x32_bf16 v[122:125], v[234:237], v[6:9], v[66:69]
	v_mfma_f32_16x16x32_bf16 v[66:69], v[230:233], v[10:13], v[218:221]
	v_mfma_f32_16x16x32_bf16 v[126:129], v[234:237], v[14:17], v[66:69]
	s_setprio 0
	s_barrier
; #define LDA(dst, b, h) _Pragma("unroll") for (int m = 0; m < 4; ++m) _Pragma("unroll") for (int k = 0; k < 2; ++k) \
;     dst[m][k] = *(const __attribute__((address_space(3))) bf16x8*)(aB + (((b) * 2 + (h)) * 16384 + m * 2048 + k * 1024))
; #define LDB(dst, b, h) _Pragma("unroll") for (int n = 0; n < 2; ++n) _Pragma("unroll") for (int k = 0; k < 2; ++k) \
;     dst[n][k] = *(const __attribute__((address_space(3))) bf16x8*)(bB + (((b) * 2 + (h)) * 16384 + n * 2048 + k * 1024))
; #define MMA(ai, bj, At, Bq) do { __builtin_amdgcn_s_setprio(1); \
;     _Pragma("unroll") for (int m = 0; m < 4; ++m) _Pragma("unroll") for (int n = 0; n < 2; ++n) _Pragma("unroll") for (int k = 0; k < 2; ++k) \
;       acc[ai][bj][m][n] = __builtin_amdgcn_mfma_f32_16x16x32_bf16(At[m][k], Bq[n][k], acc[ai][bj][m][n], 0, 0, 0); \
;     __builtin_amdgcn_s_setprio(0); } while (0)
; #define WAIT_V(n) asm volatile("s_waitcnt vmcnt(" #n ")" ::: "memory")
; #define WAIT_L(n) asm volatile("s_waitcnt lgkmcnt(" #n ")" ::: "memory")
; #define BAR __builtin_amdgcn_s_barrier()
; template <int MODE>
; DI void gemm_tile(const Params& p, const bf16_t* __restrict__ A, const bf16_t* __restrict__ Bt, int K, int brow, int bcol, int mp, int nt, bool vt, char* smem) {
;     ...
;     LDB(B1, 1, 1); WAIT_V(0); BAR; WAIT_L(0); MMA(0, 1, At, B1); BAR;
;     LDA(At, 1, 1); BAR; WAIT_L(0); MMA(1, 0, At, B0); MMA(1, 1, At, B1); BAR; }
;   if (wr == 0) BAR;
	ds_read_b128 v[132:135], v147 offset:49152
	ds_read_b128 v[160:163], v147 offset:50176
	ds_read_b128 v[214:217], v147 offset:51200
	ds_read_b128 v[218:221], v147 offset:52224
	s_waitcnt vmcnt(0)
	s_barrier
	s_waitcnt lgkmcnt(0)
	s_setprio 1
	s_waitcnt lgkmcnt(3)
	v_mfma_f32_16x16x32_bf16 v[66:69], v[34:37], v[132:135], v[94:97]
	s_waitcnt lgkmcnt(1)
	v_mfma_f32_16x16x32_bf16 v[34:37], v[34:37], v[214:217], v[90:93]
	s_waitcnt lgkmcnt(0)
	v_mfma_f32_16x16x32_bf16 v[70:73], v[38:41], v[218:221], v[34:37]
	v_mfma_f32_16x16x32_bf16 v[34:37], v[42:45], v[132:135], v[86:89]
	v_mfma_f32_16x16x32_bf16 v[74:77], v[46:49], v[160:163], v[34:37]
	v_mfma_f32_16x16x32_bf16 v[34:37], v[42:45], v[214:217], v[82:85]
	v_mfma_f32_16x16x32_bf16 v[78:81], v[46:49], v[218:221], v[34:37]
	v_mfma_f32_16x16x32_bf16 v[34:37], v[192:195], v[132:135], v[168:171]
	v_mfma_f32_16x16x32_bf16 v[82:85], v[196:199], v[160:163], v[34:37]
	v_mfma_f32_16x16x32_bf16 v[34:37], v[192:195], v[214:217], v[172:175]
	v_mfma_f32_16x16x32_bf16 v[86:89], v[196:199], v[218:221], v[34:37]
	v_mfma_f32_16x16x32_bf16 v[34:37], v[230:233], v[132:135], v[176:179]
	v_mfma_f32_16x16x32_bf16 v[90:93], v[234:237], v[160:163], v[34:37]
	v_mfma_f32_16x16x32_bf16 v[34:37], v[230:233], v[214:217], v[180:183]
	v_mfma_f32_16x16x32_bf16 v[66:69], v[38:41], v[160:163], v[66:69]
	v_mfma_f32_16x16x32_bf16 v[94:97], v[234:237], v[218:221], v[34:37]
	s_setprio 0
	s_barrier
	ds_read_b128 v[168:171], v145 offset:49152
	ds_read_b128 v[172:175], v145 offset:50176
	ds_read_b128 v[176:179], v145 offset:51200
	ds_read_b128 v[180:183], v145 offset:52224
	ds_read_b128 v[192:195], v145 offset:53248
	ds_read_b128 v[196:199], v145 offset:54272
	ds_read_b128 v[230:233], v145 offset:55296
	ds_read_b128 v[144:147], v145 offset:56320
	s_barrier
	s_waitcnt lgkmcnt(0)
	s_setprio 1
	s_waitcnt lgkmcnt(7)
	v_mfma_f32_16x16x32_bf16 v[34:37], v[168:171], v[2:5], v[62:65]
	s_waitcnt lgkmcnt(5)
	v_mfma_f32_16x16x32_bf16 v[42:45], v[176:179], v[2:5], v[54:57]
	v_mfma_f32_16x16x32_bf16 v[46:49], v[176:179], v[10:13], v[50:53]
	s_waitcnt lgkmcnt(3)
	v_mfma_f32_16x16x32_bf16 v[50:53], v[192:195], v[2:5], v[222:225]
	s_waitcnt lgkmcnt(1)
	v_mfma_f32_16x16x32_bf16 v[2:5], v[230:233], v[2:5], v[136:139]
	v_mfma_f32_16x16x32_bf16 v[38:41], v[168:171], v[10:13], v[58:61]
	v_mfma_f32_16x16x32_bf16 v[54:57], v[192:195], v[10:13], v[226:229]
	s_waitcnt lgkmcnt(0)
	v_mfma_f32_16x16x32_bf16 v[58:61], v[144:147], v[6:9], v[2:5]
	v_mfma_f32_16x16x32_bf16 v[2:5], v[230:233], v[10:13], v[148:151]
	v_mfma_f32_16x16x32_bf16 v[34:37], v[172:175], v[6:9], v[34:37]
	v_mfma_f32_16x16x32_bf16 v[38:41], v[172:175], v[14:17], v[38:41]
	v_mfma_f32_16x16x32_bf16 v[42:45], v[180:183], v[6:9], v[42:45]
	v_mfma_f32_16x16x32_bf16 v[46:49], v[180:183], v[14:17], v[46:49]
	v_mfma_f32_16x16x32_bf16 v[50:53], v[196:199], v[6:9], v[50:53]
	v_mfma_f32_16x16x32_bf16 v[54:57], v[196:199], v[14:17], v[54:57]
	v_mfma_f32_16x16x32_bf16 v[62:65], v[144:147], v[14:17], v[2:5]
	s_setprio 0
	s_setprio 1
	v_mfma_f32_16x16x32_bf16 v[2:5], v[168:171], v[132:135], v[30:33]
	v_mfma_f32_16x16x32_bf16 v[6:9], v[168:171], v[214:217], v[26:29]
	v_mfma_f32_16x16x32_bf16 v[10:13], v[176:179], v[132:135], v[22:25]
	v_mfma_f32_16x16x32_bf16 v[14:17], v[176:179], v[214:217], v[18:21]
	v_mfma_f32_16x16x32_bf16 v[18:21], v[192:195], v[132:135], v[156:159]
	v_mfma_f32_16x16x32_bf16 v[22:25], v[192:195], v[214:217], v[164:167]
	v_mfma_f32_16x16x32_bf16 v[26:29], v[230:233], v[132:135], v[184:187]
	v_mfma_f32_16x16x32_bf16 v[30:33], v[230:233], v[214:217], v[188:191]
	v_mfma_f32_16x16x32_bf16 v[2:5], v[172:175], v[160:163], v[2:5]
	v_mfma_f32_16x16x32_bf16 v[6:9], v[172:175], v[218:221], v[6:9]
	v_mfma_f32_16x16x32_bf16 v[10:13], v[180:183], v[160:163], v[10:13]
	v_mfma_f32_16x16x32_bf16 v[14:17], v[180:183], v[218:221], v[14:17]
	v_mfma_f32_16x16x32_bf16 v[18:21], v[196:199], v[160:163], v[18:21]
	v_mfma_f32_16x16x32_bf16 v[22:25], v[196:199], v[218:221], v[22:25]
	v_mfma_f32_16x16x32_bf16 v[26:29], v[144:147], v[160:163], v[26:29]
	v_mfma_f32_16x16x32_bf16 v[30:33], v[144:147], v[218:221], v[30:33]
	s_setprio 0
	s_movk_i32 s1, 0x100
	v_cmp_gt_u32_e32 vcc, s1, v0
	s_barrier
	s_and_saveexec_b64 s[2:3], vcc
	s_cbranch_execz .LBB0_590
	s_barrier
